# adds: attention phase runs waves 4-7 at a static raised priority, per-cluster priority flips removed
# speedup vs baseline: 1.0034x; 1.0034x over previous
.LBB0_759:
	s_or_b64 exec, exec, s[0:1]
	v_readlane_b32 s0, v253, 33
	v_readlane_b32 s1, v253, 34
	v_mov_b32_e32 v229, v228
	v_mov_b32_e32 v246, v207
	s_andn2_b64 vcc, exec, s[0:1]
	s_mov_b32 s8, s24
	s_waitcnt lgkmcnt(0)
	s_barrier
	v_readfirstlane_b32 s98, v207
	s_cmp_ge_u32 s98, 0x100
	s_cbranch_scc0 .Lattn_prio
	s_setprio 1
.Lattn_prio:
	s_cbranch_vccz .LBB0_773
.LBB0_760:
	s_setprio 0
	s_getreg_b32 s2, hwreg(HW_REG_XCC_ID, 0, 4)
	s_waitcnt vmcnt(0)
	s_barrier
	s_mov_b64 s[0:1], exec
	v_readlane_b32 s4, v252, 0
	v_readlane_b32 s5, v252, 1
	s_and_b64 s[4:5], s[0:1], s[4:5]
	v_mov_b32_e32 v208, 0x1000
	v_mov_b32_e32 v228, v229
	v_mov_b32_e32 v229, 0x2000
	v_xor_b32_e32 v234, 2, v233
	v_xor_b32_e32 v240, 4, v233
	v_xor_b32_e32 v245, 8, v233
	v_xor_b32_e32 v246, 16, v233
	s_mov_b64 exec, s[4:5]
	s_cbranch_execz .LBB0_998
	v_readlane_b32 s3, v254, 31
	s_waitcnt vmcnt(0) expcnt(0) lgkmcnt(0)
	s_and_b32 s8, s2, 15
	v_mov_b32_e32 v1, s3
	ds_read_b32 v3, v1
	v_readlane_b32 s3, v254, 32
	s_waitcnt lgkmcnt(0)
	v_cmp_ne_u32_e32 vcc, 0, v3
	v_mov_b32_e32 v1, s3
	ds_read_b32 v2, v1
	s_cbranch_vccnz .LBB0_962
	s_mov_b32 s9, 1
	s_branch .LBB0_764

.LBB0_778:
	v_mul_u32_u24_e32 v52, 0x90, v50
	s_waitcnt vmcnt(0)
	v_lshrrev_b32_e32 v148, 16, v130
	v_lshrrev_b32_e32 v149, 16, v131
	v_lshrrev_b32_e32 v150, 16, v132
	v_lshrrev_b32_e32 v151, 16, v133
	s_barrier
	ds_write_b128 v145, v[134:137] offset:27648
	ds_write_b16 v144, v130 offset:62976
	ds_write_b16 v144, v148 offset:63112
	ds_write_b16 v144, v131 offset:63248
	ds_write_b16 v144, v149 offset:63384
	ds_write_b16 v144, v132 offset:63520
	ds_write_b16 v144, v150 offset:63656
	ds_write_b16 v144, v133 offset:63792
	ds_write_b16 v144, v151 offset:63928
	v_add_u32_e32 v146, v51, v52
	ds_read_b128 v[82:85], v146 offset:9216
	ds_read_b128 v[86:89], v146 offset:9248
	v_mul_u32_u24_e32 v50, 0x88, v50
	v_lshlrev_b32_e32 v53, 3, v1
	v_mov_b32_e32 v19, v18
	v_mov_b32_e32 v20, v18
	v_mov_b32_e32 v21, v18
	v_mov_b32_e32 v22, v18
	v_mov_b32_e32 v23, v18
	v_mov_b32_e32 v24, v18
	v_mov_b32_e32 v25, v18
	v_mov_b32_e32 v26, v18
	v_mov_b32_e32 v27, v18
	v_mov_b32_e32 v28, v18
	v_mov_b32_e32 v29, v18
	v_mov_b32_e32 v30, v18
	v_mov_b32_e32 v31, v18
	v_mov_b32_e32 v32, v18
	v_mov_b32_e32 v33, v18
	v_mov_b32_e32 v3, v2
	v_mov_b32_e32 v4, v2
	v_mov_b32_e32 v5, v2
	v_mov_b32_e32 v6, v2
	v_mov_b32_e32 v7, v2
	v_mov_b32_e32 v8, v2
	v_mov_b32_e32 v9, v2
	v_mov_b32_e32 v10, v2
	v_mov_b32_e32 v11, v2
	v_mov_b32_e32 v12, v2
	v_mov_b32_e32 v13, v2
	v_mov_b32_e32 v14, v2
	v_mov_b32_e32 v15, v2
	v_mov_b32_e32 v16, v2
	v_mov_b32_e32 v17, v2
	v_add3_u32 v142, 0, v50, v53
	s_waitcnt lgkmcnt(1)
	v_mfma_f32_32x32x16_bf16 v[50:65], v[82:85], v[126:129], v[18:33]
	v_exp_f32_e32 v66, v66
	v_exp_f32_e32 v67, v67
	ds_read_b128 v[90:93], v146 offset:9280
	v_exp_f32_e32 v68, v68
	v_exp_f32_e32 v69, v69
	v_pk_add_f32 v[82:83], v[66:67], 0 op_sel_hi:[1,0]
	v_cvt_pk_bf16_f32 v66, v66, v67
	v_pk_add_f32 v[94:95], v[68:69], v[82:83]
	v_cvt_pk_bf16_f32 v67, v68, v69
	s_waitcnt lgkmcnt(1)
	v_mfma_f32_32x32x16_bf16 v[50:65], v[86:89], v[122:125], v[50:65]
	ds_read_b128 v[82:85], v146 offset:9312
	v_exp_f32_e32 v68, v70
	v_exp_f32_e32 v69, v71
	v_exp_f32_e32 v72, v72
	v_exp_f32_e32 v73, v73
	v_pk_add_f32 v[70:71], v[68:69], v[94:95]
	v_cvt_pk_bf16_f32 v68, v68, v69
	v_pk_add_f32 v[70:71], v[72:73], v[70:71]
	v_cvt_pk_bf16_f32 v69, v72, v73
	s_waitcnt lgkmcnt(1)
	v_mfma_f32_32x32x16_bf16 v[50:65], v[90:93], v[118:121], v[50:65]
	v_exp_f32_e32 v72, v74
	v_exp_f32_e32 v73, v75
	ds_read_b128 v[100:103], v146 offset:13824
	v_pk_add_f32 v[74:75], v[72:73], v[70:71]
	v_cvt_pk_bf16_f32 v70, v72, v73
	v_exp_f32_e32 v72, v76
	v_exp_f32_e32 v73, v77
	s_nop 0
	v_pk_add_f32 v[74:75], v[72:73], v[74:75]
	v_cvt_pk_bf16_f32 v71, v72, v73
	s_waitcnt lgkmcnt(1)
	v_mfma_f32_32x32x16_bf16 v[50:65], v[82:85], v[114:117], v[50:65]
	v_exp_f32_e32 v72, v78
	v_exp_f32_e32 v73, v79
	ds_read_b128 v[104:107], v146 offset:13856
	v_exp_f32_e32 v76, v80
	v_exp_f32_e32 v77, v81
	v_pk_add_f32 v[74:75], v[72:73], v[74:75]
	v_cvt_pk_bf16_f32 v72, v72, v73
	v_pk_add_f32 v[74:75], v[76:77], v[74:75]
	v_cvt_pk_bf16_f32 v73, v76, v77
	s_waitcnt lgkmcnt(1)
	v_mfma_f32_32x32x16_bf16 v[82:97], v[100:103], v[126:129], v[18:33]
	v_exp_f32_e32 v34, v34
	v_exp_f32_e32 v35, v35
	ds_read_b128 v[78:81], v146 offset:13888
	v_exp_f32_e32 v36, v36
	v_exp_f32_e32 v37, v37
	v_pk_add_f32 v[76:77], v[34:35], v[74:75]
	v_cvt_pk_bf16_f32 v74, v34, v35
	v_pk_add_f32 v[76:77], v[36:37], v[76:77]
	v_cvt_pk_bf16_f32 v75, v36, v37
	v_exp_f32_e32 v38, v38
	v_exp_f32_e32 v39, v39
	s_waitcnt lgkmcnt(1)
	v_mfma_f32_32x32x16_bf16 v[82:97], v[104:107], v[122:125], v[82:97]
	ds_read_b128 v[34:37], v146 offset:13920
	v_add_f32_e64 v100, v38, v76
	v_add_f32_e64 v101, v39, v77
	v_cvt_pk_bf16_f32 v76, v38, v39
	v_exp_f32_e32 v38, v40
	v_exp_f32_e32 v39, v41
	s_nop 0
	v_pk_add_f32 v[40:41], v[38:39], v[100:101]
	v_cvt_pk_bf16_f32 v77, v38, v39
	s_waitcnt lgkmcnt(1)
	v_mfma_f32_32x32x16_bf16 v[82:97], v[78:81], v[118:121], v[82:97]
	v_exp_f32_e32 v38, v42
	v_exp_f32_e32 v39, v43
	v_add_u32_e32 v147, 0x9000, v142
	ds_read2_b64 v[100:103], v147 offset1:2
	v_pk_add_f32 v[40:41], v[38:39], v[40:41]
	v_cvt_pk_bf16_f32 v78, v38, v39
	v_exp_f32_e32 v38, v44
	v_exp_f32_e32 v39, v45
	s_nop 0
	v_pk_add_f32 v[112:113], v[38:39], v[40:41]
	v_cvt_pk_bf16_f32 v79, v38, v39
	s_waitcnt lgkmcnt(1)
	v_mfma_f32_32x32x16_bf16 v[82:97], v[34:37], v[114:117], v[82:97]
	v_add_u32_e32 v99, 0xa000, v142
	ds_read2_b64 v[104:107], v99 offset0:32 offset1:34
	v_exp_f32_e32 v152, v46
	v_exp_f32_e32 v153, v47
	v_exp_f32_e32 v154, v48
	v_exp_f32_e32 v155, v49
	v_cvt_pk_bf16_f32 v80, v152, v153
	v_cvt_pk_bf16_f32 v81, v154, v155
	s_waitcnt lgkmcnt(1)
	v_mfma_f32_32x32x16_bf16 v[34:49], v[100:103], v[66:69], v[2:17]
	ds_read2_b64 v[108:111], v147 offset0:4 offset1:6
	v_max3_f32 v100, v231, v50, v51
	s_nop 0
	v_max3_f32 v156, v100, v52, v53
	s_waitcnt lgkmcnt(1)
	v_mfma_f32_32x32x16_bf16 v[2:17], v[104:107], v[66:69], v[2:17]
	ds_read2_b64 v[100:103], v99 offset0:36 offset1:38
	v_max3_f32 v66, v156, v54, v55
	s_nop 0
	v_max3_f32 v104, v66, v56, v57
	s_waitcnt lgkmcnt(1)
	v_mfma_f32_32x32x16_bf16 v[34:49], v[108:111], v[70:73], v[34:49]
	ds_read2_b64 v[66:69], v147 offset0:8 offset1:10
	v_max3_f32 v104, v104, v58, v59
	s_nop 0
	v_max3_f32 v108, v104, v60, v61
	s_waitcnt lgkmcnt(1)
	v_mfma_f32_32x32x16_bf16 v[2:17], v[100:103], v[70:73], v[2:17]
	ds_read2_b64 v[104:107], v99 offset0:40 offset1:42
	v_max3_f32 v70, v108, v62, v63
	s_nop 0
	v_max3_f32 v100, v70, v64, v65
	s_waitcnt lgkmcnt(1)
	v_mfma_f32_32x32x16_bf16 v[34:49], v[66:69], v[74:77], v[34:49]
	ds_read2_b64 v[70:73], v147 offset0:12 offset1:14
	v_max3_f32 v66, v100, v82, v83
	s_nop 0
	v_max3_f32 v100, v66, v84, v85
	s_waitcnt lgkmcnt(1)
	v_mfma_f32_32x32x16_bf16 v[2:17], v[104:107], v[74:77], v[2:17]
	ds_read2_b64 v[66:69], v99 offset0:44 offset1:46
	v_max3_f32 v99, v100, v86, v87
	s_nop 0
	v_max3_f32 v99, v99, v88, v89
	s_waitcnt lgkmcnt(1)
	v_mfma_f32_32x32x16_bf16 v[34:49], v[70:73], v[78:81], v[34:49]
	v_max3_f32 v70, v99, v90, v91
	s_nop 0
	v_max3_f32 v70, v70, v92, v93
	s_waitcnt lgkmcnt(0)
	v_mfma_f32_32x32x16_bf16 v[2:17], v[66:69], v[78:81], v[2:17]
	v_max3_f32 v66, v70, v94, v95
	s_nop 0
	v_max3_f32 v66, v66, v96, v97
	v_add_f32_e64 v68, v152, v112
	v_add_f32_e64 v69, v153, v113
	v_add_f32_e64 v68, v154, v68
	v_add_f32_e64 v69, v155, v69
	v_add_f32_e32 v67, v68, v69
	v_add_f32_e32 v152, v98, v67
	v_add_f32_e32 v67, v140, v66
	v_readlane_b32 s62, v254, 63
	v_cmp_gt_f32_e32 vcc, v67, v143
	s_movk_i32 s64, 0x2100
	s_mov_b32 s92, 0x80000
	s_mov_b32 s93, 0x90000
	s_mov_b32 s88, 0xa0000
	s_mov_b32 s89, 0xb0000
	v_readlane_b32 s63, v255, 0
	s_mov_b64 s[66:67], 0x800
	s_cbranch_vccz .LBB0_780
	v_mbcnt_hi_u32_b32 v18, -1, v232
	v_and_b32_e32 v20, 64, v18
	v_xor_b32_e32 v19, 32, v18
	v_add_u32_e32 v20, 64, v20
	v_cmp_lt_i32_e32 vcc, v19, v20
	v_max_f32_e32 v20, v141, v141
	s_nop 0
	v_cndmask_b32_e32 v18, v18, v19, vcc
	v_lshlrev_b32_e32 v18, 2, v18
	ds_bpermute_b32 v18, v18, v66
	v_max_f32_e32 v19, v66, v66
	s_waitcnt lgkmcnt(0)
	v_max_f32_e32 v18, v18, v18
	v_max_f32_e32 v18, v19, v18
	v_add_f32_e32 v18, v140, v18
	v_max_f32_e32 v66, v20, v18
	v_sub_f32_e32 v18, v141, v66
	v_exp_f32_e32 v20, v18
	v_sub_f32_e32 v18, v140, v66
	v_pk_add_f32 v[50:51], v[50:51], v[18:19] op_sel_hi:[1,0]
	v_pk_add_f32 v[52:53], v[52:53], v[18:19] op_sel_hi:[1,0]
	v_pk_add_f32 v[54:55], v[54:55], v[18:19] op_sel_hi:[1,0]
	v_pk_add_f32 v[56:57], v[56:57], v[18:19] op_sel_hi:[1,0]
	v_pk_add_f32 v[58:59], v[58:59], v[18:19] op_sel_hi:[1,0]
	v_pk_add_f32 v[60:61], v[60:61], v[18:19] op_sel_hi:[1,0]
	v_pk_add_f32 v[62:63], v[62:63], v[18:19] op_sel_hi:[1,0]
	v_pk_add_f32 v[64:65], v[64:65], v[18:19] op_sel_hi:[1,0]
	v_pk_add_f32 v[82:83], v[82:83], v[18:19] op_sel_hi:[1,0]
	v_pk_add_f32 v[84:85], v[84:85], v[18:19] op_sel_hi:[1,0]
	v_pk_add_f32 v[86:87], v[86:87], v[18:19] op_sel_hi:[1,0]
	v_pk_add_f32 v[88:89], v[88:89], v[18:19] op_sel_hi:[1,0]
	v_pk_add_f32 v[90:91], v[90:91], v[18:19] op_sel_hi:[1,0]
	v_pk_add_f32 v[92:93], v[92:93], v[18:19] op_sel_hi:[1,0]
	v_pk_add_f32 v[94:95], v[94:95], v[18:19] op_sel_hi:[1,0]
	v_pk_add_f32 v[96:97], v[96:97], v[18:19] op_sel_hi:[1,0]
	v_xor_b32_e32 v18, 0x80000000, v66
	v_pk_mul_f32 v[48:49], v[48:49], v[20:21] op_sel_hi:[1,0]
	v_pk_mul_f32 v[46:47], v[46:47], v[20:21] op_sel_hi:[1,0]
	v_pk_mul_f32 v[44:45], v[44:45], v[20:21] op_sel_hi:[1,0]
	v_pk_mul_f32 v[42:43], v[42:43], v[20:21] op_sel_hi:[1,0]
	v_pk_mul_f32 v[40:41], v[40:41], v[20:21] op_sel_hi:[1,0]
	v_pk_mul_f32 v[38:39], v[38:39], v[20:21] op_sel_hi:[1,0]
	v_pk_mul_f32 v[36:37], v[36:37], v[20:21] op_sel_hi:[1,0]
	v_pk_mul_f32 v[34:35], v[34:35], v[20:21] op_sel_hi:[1,0]
	v_pk_mul_f32 v[16:17], v[16:17], v[20:21] op_sel_hi:[1,0]
	v_pk_mul_f32 v[14:15], v[14:15], v[20:21] op_sel_hi:[1,0]
	v_pk_mul_f32 v[12:13], v[12:13], v[20:21] op_sel_hi:[1,0]
	v_pk_mul_f32 v[10:11], v[10:11], v[20:21] op_sel_hi:[1,0]
	v_pk_mul_f32 v[8:9], v[8:9], v[20:21] op_sel_hi:[1,0]
	v_pk_mul_f32 v[6:7], v[6:7], v[20:21] op_sel_hi:[1,0]
	v_pk_mul_f32 v[4:5], v[4:5], v[20:21] op_sel_hi:[1,0]
	v_pk_mul_f32 v[2:3], v[2:3], v[20:21] op_sel_hi:[1,0]
	v_mul_f32_e32 v152, v152, v20
	v_add_f32_e32 v143, 0x41000000, v66
	v_mov_b32_e32 v19, v18
	v_mov_b32_e32 v20, v18
	v_mov_b32_e32 v21, v18
	v_mov_b32_e32 v22, v18
	v_mov_b32_e32 v23, v18
	v_mov_b32_e32 v24, v18
	v_mov_b32_e32 v25, v18
	v_mov_b32_e32 v26, v18
	v_mov_b32_e32 v27, v18
	v_mov_b32_e32 v28, v18
	v_mov_b32_e32 v29, v18
	v_mov_b32_e32 v30, v18
	v_mov_b32_e32 v31, v18
	v_mov_b32_e32 v32, v18
	v_mov_b32_e32 v33, v18
	v_mov_b32_e32 v140, v66
	v_mov_b32_e32 v141, v66
.LBB0_780:
	v_add_u32_e32 v66, 0x9000, v144
	ds_write_b128 v145, v[134:137]
	ds_write_b16 v66, v130 offset:34816
	ds_write_b16 v66, v148 offset:34952
	ds_write_b16 v66, v131 offset:35088
	ds_write_b16 v66, v149 offset:35224
	ds_write_b16 v66, v132 offset:35360
	ds_write_b16 v66, v150 offset:35496
	ds_write_b16 v66, v133 offset:35632
	ds_write_b16 v66, v151 offset:35768
	ds_read_b128 v[98:101], v146 offset:18432
	ds_read_b128 v[102:105], v146 offset:18464
	s_waitcnt lgkmcnt(1)
	v_mfma_f32_32x32x16_bf16 v[66:81], v[98:101], v[126:129], v[18:33]
	v_exp_f32_e32 v50, v50
	v_exp_f32_e32 v51, v51
	ds_read_b128 v[106:109], v146 offset:18496
	v_exp_f32_e32 v52, v52
	v_exp_f32_e32 v53, v53
	v_pk_add_f32 v[98:99], v[50:51], 0 op_sel_hi:[1,0]
	v_cvt_pk_bf16_f32 v50, v50, v51
	v_pk_add_f32 v[110:111], v[52:53], v[98:99]
	v_cvt_pk_bf16_f32 v51, v52, v53
	s_waitcnt lgkmcnt(1)
	v_mfma_f32_32x32x16_bf16 v[66:81], v[102:105], v[122:125], v[66:81]
	ds_read_b128 v[98:101], v146 offset:18528
	v_exp_f32_e32 v52, v54
	v_exp_f32_e32 v53, v55
	v_exp_f32_e32 v56, v56
	v_exp_f32_e32 v57, v57
	v_pk_add_f32 v[54:55], v[52:53], v[110:111]
	v_cvt_pk_bf16_f32 v52, v52, v53
	v_pk_add_f32 v[54:55], v[56:57], v[54:55]
	v_cvt_pk_bf16_f32 v53, v56, v57
	s_waitcnt lgkmcnt(1)
	v_mfma_f32_32x32x16_bf16 v[66:81], v[106:109], v[118:121], v[66:81]
	v_exp_f32_e32 v56, v58
	v_exp_f32_e32 v57, v59
	ds_read_b128 v[154:157], v146 offset:23040
	v_pk_add_f32 v[58:59], v[56:57], v[54:55]
	v_cvt_pk_bf16_f32 v54, v56, v57
	v_exp_f32_e32 v56, v60
	v_exp_f32_e32 v57, v61
	s_nop 0
	v_pk_add_f32 v[58:59], v[56:57], v[58:59]
	v_cvt_pk_bf16_f32 v55, v56, v57
	s_waitcnt lgkmcnt(1)
	v_mfma_f32_32x32x16_bf16 v[66:81], v[98:101], v[114:117], v[66:81]
	v_exp_f32_e32 v56, v62
	v_exp_f32_e32 v57, v63
	ds_read_b128 v[158:161], v146 offset:23072
	v_exp_f32_e32 v60, v64
	v_exp_f32_e32 v61, v65
	v_pk_add_f32 v[58:59], v[56:57], v[58:59]
	v_cvt_pk_bf16_f32 v56, v56, v57
	v_pk_add_f32 v[58:59], v[60:61], v[58:59]
	v_cvt_pk_bf16_f32 v57, v60, v61
	s_waitcnt lgkmcnt(1)
	v_mfma_f32_32x32x16_bf16 v[98:113], v[154:157], v[126:129], v[18:33]
	v_exp_f32_e32 v60, v82
	v_exp_f32_e32 v61, v83
	ds_read_b128 v[62:65], v146 offset:23104
	v_exp_f32_e32 v82, v84
	v_exp_f32_e32 v83, v85
	v_pk_add_f32 v[162:163], v[60:61], v[58:59]
	v_cvt_pk_bf16_f32 v58, v60, v61
	v_pk_add_f32 v[60:61], v[82:83], v[162:163]
	v_cvt_pk_bf16_f32 v59, v82, v83
	s_waitcnt lgkmcnt(1)
	v_mfma_f32_32x32x16_bf16 v[98:113], v[158:161], v[122:125], v[98:113]
	v_exp_f32_e32 v86, v86
	v_exp_f32_e32 v87, v87
	ds_read_b128 v[82:85], v146 offset:23136
	v_pk_add_f32 v[154:155], v[86:87], v[60:61]
	v_cvt_pk_bf16_f32 v60, v86, v87
	v_exp_f32_e32 v86, v88
	v_exp_f32_e32 v87, v89
	s_nop 0
	v_pk_add_f32 v[154:155], v[86:87], v[154:155]
	v_cvt_pk_bf16_f32 v61, v86, v87
	s_waitcnt lgkmcnt(1)
	v_mfma_f32_32x32x16_bf16 v[98:113], v[62:65], v[118:121], v[98:113]
	v_add_u32_e32 v153, 0xb000, v142
	v_exp_f32_e32 v62, v90
	v_exp_f32_e32 v63, v91
	ds_read2_b64 v[86:89], v153 offset0:64 offset1:66
	v_exp_f32_e32 v90, v92
	v_exp_f32_e32 v91, v93
	v_pk_add_f32 v[64:65], v[62:63], v[154:155]
	v_cvt_pk_bf16_f32 v62, v62, v63
	v_pk_add_f32 v[154:155], v[90:91], v[64:65]
	v_cvt_pk_bf16_f32 v63, v90, v91
	s_waitcnt lgkmcnt(1)
	v_mfma_f32_32x32x16_bf16 v[98:113], v[82:85], v[114:117], v[98:113]
	v_add_u32_e32 v156, 0xc000, v142
	ds_read2_b64 v[90:93], v156 offset0:96 offset1:98
	v_exp_f32_e32 v94, v94
	v_exp_f32_e32 v95, v95
	v_exp_f32_e32 v96, v96
	v_exp_f32_e32 v97, v97
	v_cvt_pk_bf16_f32 v64, v94, v95
	v_cvt_pk_bf16_f32 v65, v96, v97
	s_waitcnt lgkmcnt(1)
	v_mfma_f32_32x32x16_bf16 v[34:49], v[86:89], v[50:53], v[34:49]
	ds_read2_b64 v[82:85], v153 offset0:68 offset1:70
	v_max3_f32 v86, v231, v66, v67
	s_nop 0
	v_max3_f32 v157, v86, v68, v69
	s_waitcnt lgkmcnt(1)
	v_mfma_f32_32x32x16_bf16 v[2:17], v[90:93], v[50:53], v[2:17]
	ds_read2_b64 v[86:89], v156 offset0:100 offset1:102
	v_max3_f32 v50, v157, v70, v71
	s_nop 0
	v_max3_f32 v90, v50, v72, v73
	s_waitcnt lgkmcnt(1)
	v_mfma_f32_32x32x16_bf16 v[34:49], v[82:85], v[54:57], v[34:49]
	ds_read2_b64 v[50:53], v153 offset0:72 offset1:74
	v_max3_f32 v82, v90, v74, v75
	s_nop 0
	v_max3_f32 v90, v82, v76, v77
	s_waitcnt lgkmcnt(1)
	v_mfma_f32_32x32x16_bf16 v[2:17], v[86:89], v[54:57], v[2:17]
	ds_read2_b64 v[82:85], v156 offset0:104 offset1:106
	v_max3_f32 v54, v90, v78, v79
	s_nop 0
	v_max3_f32 v86, v54, v80, v81
	s_waitcnt lgkmcnt(1)
	v_mfma_f32_32x32x16_bf16 v[34:49], v[50:53], v[58:61], v[34:49]
	ds_read2_b64 v[54:57], v153 offset0:76 offset1:78
	v_max3_f32 v86, v86, v98, v99
	s_nop 0
	v_max3_f32 v86, v86, v100, v101
	s_waitcnt lgkmcnt(1)
	v_mfma_f32_32x32x16_bf16 v[2:17], v[82:85], v[58:61], v[2:17]
	ds_read2_b64 v[50:53], v156 offset0:108 offset1:110
	v_max3_f32 v86, v86, v102, v103
	s_nop 0
	v_max3_f32 v86, v86, v104, v105
	s_waitcnt lgkmcnt(1)
	v_mfma_f32_32x32x16_bf16 v[34:49], v[54:57], v[62:65], v[34:49]
	v_max3_f32 v54, v86, v106, v107
	s_nop 0
	v_max3_f32 v54, v54, v108, v109
	s_waitcnt lgkmcnt(0)
	v_mfma_f32_32x32x16_bf16 v[2:17], v[50:53], v[62:65], v[2:17]
	v_max3_f32 v50, v54, v110, v111
	s_nop 0
	v_max3_f32 v50, v50, v112, v113
	v_add_f32_e64 v52, v94, v154
	v_add_f32_e64 v53, v95, v155
	v_add_f32_e64 v52, v96, v52
	v_add_f32_e64 v53, v97, v53
	v_add_f32_e32 v51, v52, v53
	v_add_f32_e32 v94, v152, v51
	v_add_f32_e32 v51, v140, v50
	v_cmp_gt_f32_e32 vcc, v51, v143
	s_cbranch_vccz .LBB0_782
	v_mbcnt_hi_u32_b32 v18, -1, v232
	v_and_b32_e32 v20, 64, v18
	v_xor_b32_e32 v19, 32, v18
	v_add_u32_e32 v20, 64, v20
	v_cmp_lt_i32_e32 vcc, v19, v20
	v_max_f32_e32 v20, v141, v141
	s_nop 0
	v_cndmask_b32_e32 v18, v18, v19, vcc
	v_lshlrev_b32_e32 v18, 2, v18
	ds_bpermute_b32 v18, v18, v50
	v_max_f32_e32 v19, v50, v50
	s_waitcnt lgkmcnt(0)
	v_max_f32_e32 v18, v18, v18
	v_max_f32_e32 v18, v19, v18
	v_add_f32_e32 v18, v140, v18
	v_max_f32_e32 v50, v20, v18
	v_sub_f32_e32 v18, v141, v50
	v_exp_f32_e32 v20, v18
	v_sub_f32_e32 v18, v140, v50
	v_pk_add_f32 v[66:67], v[66:67], v[18:19] op_sel_hi:[1,0]
	v_pk_add_f32 v[68:69], v[68:69], v[18:19] op_sel_hi:[1,0]
	v_pk_add_f32 v[70:71], v[70:71], v[18:19] op_sel_hi:[1,0]
	v_pk_add_f32 v[72:73], v[72:73], v[18:19] op_sel_hi:[1,0]
	v_pk_add_f32 v[74:75], v[74:75], v[18:19] op_sel_hi:[1,0]
	v_pk_add_f32 v[76:77], v[76:77], v[18:19] op_sel_hi:[1,0]
	v_pk_add_f32 v[78:79], v[78:79], v[18:19] op_sel_hi:[1,0]
	v_pk_add_f32 v[80:81], v[80:81], v[18:19] op_sel_hi:[1,0]
	v_pk_add_f32 v[98:99], v[98:99], v[18:19] op_sel_hi:[1,0]
	v_pk_add_f32 v[100:101], v[100:101], v[18:19] op_sel_hi:[1,0]
	v_pk_add_f32 v[102:103], v[102:103], v[18:19] op_sel_hi:[1,0]
	v_pk_add_f32 v[104:105], v[104:105], v[18:19] op_sel_hi:[1,0]
	v_pk_add_f32 v[106:107], v[106:107], v[18:19] op_sel_hi:[1,0]
	v_pk_add_f32 v[108:109], v[108:109], v[18:19] op_sel_hi:[1,0]
	v_pk_add_f32 v[110:111], v[110:111], v[18:19] op_sel_hi:[1,0]
	v_pk_add_f32 v[112:113], v[112:113], v[18:19] op_sel_hi:[1,0]
	v_xor_b32_e32 v18, 0x80000000, v50
	v_pk_mul_f32 v[48:49], v[48:49], v[20:21] op_sel_hi:[1,0]
	v_pk_mul_f32 v[46:47], v[46:47], v[20:21] op_sel_hi:[1,0]
	v_pk_mul_f32 v[44:45], v[44:45], v[20:21] op_sel_hi:[1,0]
	v_pk_mul_f32 v[42:43], v[42:43], v[20:21] op_sel_hi:[1,0]
	v_pk_mul_f32 v[40:41], v[40:41], v[20:21] op_sel_hi:[1,0]
	v_pk_mul_f32 v[38:39], v[38:39], v[20:21] op_sel_hi:[1,0]
	v_pk_mul_f32 v[36:37], v[36:37], v[20:21] op_sel_hi:[1,0]
	v_pk_mul_f32 v[34:35], v[34:35], v[20:21] op_sel_hi:[1,0]
	v_pk_mul_f32 v[16:17], v[16:17], v[20:21] op_sel_hi:[1,0]
	v_pk_mul_f32 v[14:15], v[14:15], v[20:21] op_sel_hi:[1,0]
	v_pk_mul_f32 v[12:13], v[12:13], v[20:21] op_sel_hi:[1,0]
	v_pk_mul_f32 v[10:11], v[10:11], v[20:21] op_sel_hi:[1,0]
	v_pk_mul_f32 v[8:9], v[8:9], v[20:21] op_sel_hi:[1,0]
	v_pk_mul_f32 v[6:7], v[6:7], v[20:21] op_sel_hi:[1,0]
	v_pk_mul_f32 v[4:5], v[4:5], v[20:21] op_sel_hi:[1,0]
	v_pk_mul_f32 v[2:3], v[2:3], v[20:21] op_sel_hi:[1,0]
	v_mul_f32_e32 v94, v94, v20
	v_add_f32_e32 v143, 0x41000000, v50
	v_mov_b32_e32 v19, v18
	v_mov_b32_e32 v20, v18
	v_mov_b32_e32 v21, v18
	v_mov_b32_e32 v22, v18
	v_mov_b32_e32 v23, v18
	v_mov_b32_e32 v24, v18
	v_mov_b32_e32 v25, v18
	v_mov_b32_e32 v26, v18
	v_mov_b32_e32 v27, v18
	v_mov_b32_e32 v28, v18
	v_mov_b32_e32 v29, v18
	v_mov_b32_e32 v30, v18
	v_mov_b32_e32 v31, v18
	v_mov_b32_e32 v32, v18
	v_mov_b32_e32 v33, v18
	v_mov_b32_e32 v140, v50
	v_mov_b32_e32 v141, v50
.LBB0_782:
	s_barrier
	ds_write_b128 v145, v[134:137] offset:9216
	ds_write_b16 v144, v130 offset:36864
	ds_write_b16 v144, v148 offset:37000
	ds_write_b16 v144, v131 offset:37136
	ds_write_b16 v144, v149 offset:37272
	ds_write_b16 v144, v132 offset:37408
	ds_write_b16 v144, v150 offset:37544
	ds_write_b16 v144, v133 offset:37680
	ds_write_b16 v144, v151 offset:37816
	ds_read_b128 v[82:85], v146 offset:27648
	ds_read_b128 v[86:89], v146 offset:27680
	s_waitcnt lgkmcnt(1)
	v_mfma_f32_32x32x16_bf16 v[50:65], v[82:85], v[126:129], v[18:33]
	v_exp_f32_e32 v66, v66
	v_exp_f32_e32 v67, v67
	ds_read_b128 v[90:93], v146 offset:27712
	v_pk_add_f32 v[84:85], v[66:67], 0 op_sel_hi:[1,0]
	v_cvt_pk_bf16_f32 v82, v66, v67
	v_exp_f32_e32 v66, v68
	v_exp_f32_e32 v67, v69
	s_nop 0
	v_pk_add_f32 v[84:85], v[66:67], v[84:85]
	v_cvt_pk_bf16_f32 v83, v66, v67
	v_exp_f32_e32 v70, v70
	v_exp_f32_e32 v71, v71
	s_waitcnt lgkmcnt(1)
	v_mfma_f32_32x32x16_bf16 v[50:65], v[86:89], v[122:125], v[50:65]
	ds_read_b128 v[66:69], v146 offset:27744
	v_add_f32_e64 v86, v70, v84
	v_add_f32_e64 v87, v71, v85
	v_cvt_pk_bf16_f32 v84, v70, v71
	v_exp_f32_e32 v70, v72
	v_exp_f32_e32 v71, v73
	s_nop 0
	v_pk_add_f32 v[72:73], v[70:71], v[86:87]
	v_cvt_pk_bf16_f32 v85, v70, v71
	v_exp_f32_e32 v70, v74
	v_exp_f32_e32 v71, v75
	s_waitcnt lgkmcnt(1)
	v_mfma_f32_32x32x16_bf16 v[50:65], v[90:93], v[118:121], v[50:65]
	ds_read_b128 v[152:155], v146 offset:32256
	v_add_f32_e64 v72, v70, v72
	v_add_f32_e64 v73, v71, v73
	v_cvt_pk_bf16_f32 v86, v70, v71
	v_exp_f32_e32 v70, v76
	v_exp_f32_e32 v71, v77
	s_nop 0
	v_pk_add_f32 v[72:73], v[70:71], v[72:73]
	v_cvt_pk_bf16_f32 v87, v70, v71
	s_waitcnt lgkmcnt(1)
	v_mfma_f32_32x32x16_bf16 v[50:65], v[66:69], v[114:117], v[50:65]
	v_exp_f32_e32 v66, v78
	v_exp_f32_e32 v67, v79
	ds_read_b128 v[156:159], v146 offset:32288
	v_pk_add_f32 v[68:69], v[66:67], v[72:73]
	v_cvt_pk_bf16_f32 v88, v66, v67
	v_exp_f32_e32 v66, v80
	v_exp_f32_e32 v67, v81
	s_nop 0
	v_pk_add_f32 v[68:69], v[66:67], v[68:69]
	v_cvt_pk_bf16_f32 v89, v66, v67
	v_exp_f32_e32 v90, v98
	v_exp_f32_e32 v91, v99
	ds_read_b128 v[96:99], v146 offset:32320
	v_exp_f32_e32 v92, v100
	v_exp_f32_e32 v93, v101
	v_pk_add_f32 v[160:161], v[90:91], v[68:69]
	s_waitcnt lgkmcnt(2)
	v_mfma_f32_32x32x16_bf16 v[66:81], v[152:155], v[126:129], v[18:33]
	v_cvt_pk_bf16_f32 v90, v90, v91
	v_add_f32_e64 v100, v92, v160
	v_add_f32_e64 v101, v93, v161
	v_cvt_pk_bf16_f32 v91, v92, v93
	s_waitcnt lgkmcnt(1)
	v_mfma_f32_32x32x16_bf16 v[66:81], v[156:159], v[122:125], v[66:81]
	v_exp_f32_e32 v92, v102
	v_exp_f32_e32 v93, v103
	ds_read_b128 v[152:155], v146 offset:32352
	v_exp_f32_e32 v102, v104
	v_exp_f32_e32 v103, v105
	v_pk_add_f32 v[100:101], v[92:93], v[100:101]
	v_cvt_pk_bf16_f32 v92, v92, v93
	v_pk_add_f32 v[104:105], v[102:103], v[100:101]
	v_cvt_pk_bf16_f32 v93, v102, v103
	s_waitcnt lgkmcnt(1)
	v_mfma_f32_32x32x16_bf16 v[66:81], v[96:99], v[118:121], v[66:81]
	v_exp_f32_e32 v96, v106
	v_exp_f32_e32 v97, v107
	v_add_u32_e32 v95, 0xd000, v142
	ds_read2_b64 v[100:103], v95 offset0:128 offset1:130
	v_pk_add_f32 v[98:99], v[96:97], v[104:105]
	v_exp_f32_e32 v104, v108
	v_exp_f32_e32 v105, v109
	v_cvt_pk_bf16_f32 v96, v96, v97
	v_pk_add_f32 v[156:157], v[104:105], v[98:99]
	v_cvt_pk_bf16_f32 v97, v104, v105
	s_waitcnt lgkmcnt(1)
	v_mfma_f32_32x32x16_bf16 v[66:81], v[152:155], v[114:117], v[66:81]
	v_add_u32_e32 v158, 0xe000, v142
	v_exp_f32_e32 v152, v110
	v_exp_f32_e32 v153, v111
	ds_read2_b64 v[104:107], v158 offset0:160 offset1:162
	v_exp_f32_e32 v112, v112
	v_exp_f32_e32 v113, v113
	v_cvt_pk_bf16_f32 v98, v152, v153
	v_cvt_pk_bf16_f32 v99, v112, v113
	s_waitcnt lgkmcnt(1)
	v_mfma_f32_32x32x16_bf16 v[34:49], v[100:103], v[82:85], v[34:49]
	ds_read2_b64 v[108:111], v95 offset0:132 offset1:134
	v_max3_f32 v100, v231, v50, v51
	s_nop 0
	v_max3_f32 v154, v100, v52, v53
	s_waitcnt lgkmcnt(1)
	v_mfma_f32_32x32x16_bf16 v[2:17], v[104:107], v[82:85], v[2:17]
	ds_read2_b64 v[100:103], v158 offset0:164 offset1:166
	v_max3_f32 v82, v154, v54, v55
	s_nop 0
	v_max3_f32 v104, v82, v56, v57
	s_waitcnt lgkmcnt(1)
	v_mfma_f32_32x32x16_bf16 v[34:49], v[108:111], v[86:89], v[34:49]
	ds_read2_b64 v[82:85], v95 offset0:136 offset1:138
	v_max3_f32 v104, v104, v58, v59
	s_nop 0
	v_max3_f32 v108, v104, v60, v61
	s_waitcnt lgkmcnt(1)
	v_mfma_f32_32x32x16_bf16 v[2:17], v[100:103], v[86:89], v[2:17]
	ds_read2_b64 v[104:107], v158 offset0:168 offset1:170
	v_max3_f32 v86, v108, v62, v63
	s_nop 0
	v_max3_f32 v100, v86, v64, v65
	s_waitcnt lgkmcnt(1)
	v_mfma_f32_32x32x16_bf16 v[34:49], v[82:85], v[90:93], v[34:49]
	ds_read2_b64 v[86:89], v95 offset0:140 offset1:142
	v_max3_f32 v95, v100, v66, v67
	s_nop 0
	v_max3_f32 v95, v95, v68, v69
	s_waitcnt lgkmcnt(1)
	v_mfma_f32_32x32x16_bf16 v[2:17], v[104:107], v[90:93], v[2:17]
	ds_read2_b64 v[82:85], v158 offset0:172 offset1:174
	v_max3_f32 v95, v95, v70, v71
	s_nop 0
	v_max3_f32 v95, v95, v72, v73
	s_waitcnt lgkmcnt(1)
	v_mfma_f32_32x32x16_bf16 v[34:49], v[86:89], v[96:99], v[34:49]
	v_max3_f32 v86, v95, v74, v75
	s_nop 0
	v_max3_f32 v86, v86, v76, v77
	s_waitcnt lgkmcnt(0)
	v_mfma_f32_32x32x16_bf16 v[2:17], v[82:85], v[96:99], v[2:17]
	v_max3_f32 v82, v86, v78, v79
	s_nop 0
	v_max3_f32 v82, v82, v80, v81
	v_add_f32_e64 v84, v152, v156
	v_add_f32_e64 v85, v153, v157
	v_add_f32_e64 v84, v112, v84
	v_add_f32_e64 v85, v113, v85
	v_add_f32_e32 v83, v84, v85
	v_add_f32_e32 v98, v94, v83
	v_add_f32_e32 v83, v140, v82
	v_cmp_gt_f32_e32 vcc, v83, v143
	s_cbranch_vccz .LBB0_784
	v_mbcnt_hi_u32_b32 v18, -1, v232
	v_and_b32_e32 v20, 64, v18
	v_xor_b32_e32 v19, 32, v18
	v_add_u32_e32 v20, 64, v20
	v_cmp_lt_i32_e32 vcc, v19, v20
	v_max_f32_e32 v20, v141, v141
	s_nop 0
	v_cndmask_b32_e32 v18, v18, v19, vcc
	v_lshlrev_b32_e32 v18, 2, v18
	ds_bpermute_b32 v18, v18, v82
	v_max_f32_e32 v19, v82, v82
	s_waitcnt lgkmcnt(0)
	v_max_f32_e32 v18, v18, v18
	v_max_f32_e32 v18, v19, v18
	v_add_f32_e32 v18, v140, v18
	v_max_f32_e32 v82, v20, v18
	v_sub_f32_e32 v18, v141, v82
	v_exp_f32_e32 v20, v18
	v_sub_f32_e32 v18, v140, v82
	v_pk_add_f32 v[50:51], v[50:51], v[18:19] op_sel_hi:[1,0]
	v_pk_add_f32 v[52:53], v[52:53], v[18:19] op_sel_hi:[1,0]
	v_pk_add_f32 v[54:55], v[54:55], v[18:19] op_sel_hi:[1,0]
	v_pk_add_f32 v[56:57], v[56:57], v[18:19] op_sel_hi:[1,0]
	v_pk_add_f32 v[58:59], v[58:59], v[18:19] op_sel_hi:[1,0]
	v_pk_add_f32 v[60:61], v[60:61], v[18:19] op_sel_hi:[1,0]
	v_pk_add_f32 v[62:63], v[62:63], v[18:19] op_sel_hi:[1,0]
	v_pk_add_f32 v[64:65], v[64:65], v[18:19] op_sel_hi:[1,0]
	v_pk_add_f32 v[66:67], v[66:67], v[18:19] op_sel_hi:[1,0]
	v_pk_add_f32 v[68:69], v[68:69], v[18:19] op_sel_hi:[1,0]
	v_pk_add_f32 v[70:71], v[70:71], v[18:19] op_sel_hi:[1,0]
	v_pk_add_f32 v[72:73], v[72:73], v[18:19] op_sel_hi:[1,0]
	v_pk_add_f32 v[74:75], v[74:75], v[18:19] op_sel_hi:[1,0]
	v_pk_add_f32 v[76:77], v[76:77], v[18:19] op_sel_hi:[1,0]
	v_pk_add_f32 v[78:79], v[78:79], v[18:19] op_sel_hi:[1,0]
	v_pk_add_f32 v[80:81], v[80:81], v[18:19] op_sel_hi:[1,0]
	v_xor_b32_e32 v18, 0x80000000, v82
	v_pk_mul_f32 v[48:49], v[48:49], v[20:21] op_sel_hi:[1,0]
	v_pk_mul_f32 v[46:47], v[46:47], v[20:21] op_sel_hi:[1,0]
	v_pk_mul_f32 v[44:45], v[44:45], v[20:21] op_sel_hi:[1,0]
	v_pk_mul_f32 v[42:43], v[42:43], v[20:21] op_sel_hi:[1,0]
	v_pk_mul_f32 v[40:41], v[40:41], v[20:21] op_sel_hi:[1,0]
	v_pk_mul_f32 v[38:39], v[38:39], v[20:21] op_sel_hi:[1,0]
	v_pk_mul_f32 v[36:37], v[36:37], v[20:21] op_sel_hi:[1,0]
	v_pk_mul_f32 v[34:35], v[34:35], v[20:21] op_sel_hi:[1,0]
	v_pk_mul_f32 v[16:17], v[16:17], v[20:21] op_sel_hi:[1,0]
	v_pk_mul_f32 v[14:15], v[14:15], v[20:21] op_sel_hi:[1,0]
	v_pk_mul_f32 v[12:13], v[12:13], v[20:21] op_sel_hi:[1,0]
	v_pk_mul_f32 v[10:11], v[10:11], v[20:21] op_sel_hi:[1,0]
	v_pk_mul_f32 v[8:9], v[8:9], v[20:21] op_sel_hi:[1,0]
	v_pk_mul_f32 v[6:7], v[6:7], v[20:21] op_sel_hi:[1,0]
	v_pk_mul_f32 v[4:5], v[4:5], v[20:21] op_sel_hi:[1,0]
	v_pk_mul_f32 v[2:3], v[2:3], v[20:21] op_sel_hi:[1,0]
	v_mul_f32_e32 v98, v98, v20
	v_add_f32_e32 v143, 0x41000000, v82
	v_mov_b32_e32 v19, v18
	v_mov_b32_e32 v20, v18
	v_mov_b32_e32 v21, v18
	v_mov_b32_e32 v22, v18
	v_mov_b32_e32 v23, v18
	v_mov_b32_e32 v24, v18
	v_mov_b32_e32 v25, v18
	v_mov_b32_e32 v26, v18
	v_mov_b32_e32 v27, v18
	v_mov_b32_e32 v28, v18
	v_mov_b32_e32 v29, v18
	v_mov_b32_e32 v30, v18
	v_mov_b32_e32 v31, v18
	v_mov_b32_e32 v32, v18
	v_mov_b32_e32 v33, v18
	v_mov_b32_e32 v140, v82
	v_mov_b32_e32 v141, v82
.LBB0_784:
	ds_write_b128 v145, v[134:137] offset:18432
	ds_write_b16 v144, v130 offset:45568
	ds_write_b16 v144, v148 offset:45704
	ds_write_b16 v144, v131 offset:45840
	ds_write_b16 v144, v149 offset:45976
	ds_write_b16 v144, v132 offset:46112
	ds_write_b16 v144, v150 offset:46248
	ds_write_b16 v144, v133 offset:46384
	ds_write_b16 v144, v151 offset:46520
	ds_read_b128 v[100:103], v146
	ds_read_b128 v[104:107], v146 offset:32
	v_lshlrev_b32_e32 v1, 2, v1
	v_exp_f32_e32 v50, v50
	v_exp_f32_e32 v51, v51
	ds_read_b128 v[108:111], v146 offset:64
	v_exp_f32_e32 v52, v52
	v_exp_f32_e32 v53, v53
	s_waitcnt lgkmcnt(2)
	v_mfma_f32_32x32x16_bf16 v[82:97], v[100:103], v[126:129], v[18:33]
	v_add_f32_e64 v100, v50, 0
	v_add_f32_e64 v101, v51, 0
	v_cvt_pk_bf16_f32 v50, v50, v51
	v_add_f32_e64 v112, v52, v100
	v_add_f32_e64 v113, v53, v101
	v_cvt_pk_bf16_f32 v51, v52, v53
	v_exp_f32_e32 v52, v54
	v_exp_f32_e32 v53, v55
	ds_read_b128 v[100:103], v146 offset:96
	v_exp_f32_e32 v56, v56
	v_exp_f32_e32 v57, v57
	v_pk_add_f32 v[54:55], v[52:53], v[112:113]
	s_waitcnt lgkmcnt(2)
	v_mfma_f32_32x32x16_bf16 v[82:97], v[104:107], v[122:125], v[82:97]
	v_cvt_pk_bf16_f32 v52, v52, v53
	v_add_f32_e64 v54, v56, v54
	v_add_f32_e64 v55, v57, v55
	v_cvt_pk_bf16_f32 v53, v56, v57
	v_exp_f32_e32 v56, v58
	v_exp_f32_e32 v57, v59
	ds_read_b128 v[104:107], v146 offset:4608
	s_waitcnt lgkmcnt(2)
	v_mfma_f32_32x32x16_bf16 v[82:97], v[108:111], v[118:121], v[82:97]
	v_add_f32_e64 v58, v56, v54
	v_add_f32_e64 v59, v57, v55
	v_cvt_pk_bf16_f32 v54, v56, v57
	v_exp_f32_e32 v56, v60
	v_exp_f32_e32 v57, v61
	s_nop 0
	v_pk_add_f32 v[58:59], v[56:57], v[58:59]
	v_cvt_pk_bf16_f32 v55, v56, v57
	v_exp_f32_e32 v56, v62
	v_exp_f32_e32 v57, v63
	ds_read_b128 v[108:111], v146 offset:4640
	v_exp_f32_e32 v60, v64
	v_exp_f32_e32 v61, v65
	v_pk_add_f32 v[58:59], v[56:57], v[58:59]
	s_waitcnt lgkmcnt(2)
	v_mfma_f32_32x32x16_bf16 v[82:97], v[100:103], v[114:117], v[82:97]
	v_cvt_pk_bf16_f32 v56, v56, v57
	v_add_f32_e64 v58, v60, v58
	v_add_f32_e64 v59, v61, v59
	v_cvt_pk_bf16_f32 v57, v60, v61
	s_waitcnt lgkmcnt(1)
	v_mfma_f32_32x32x16_bf16 v[18:33], v[104:107], v[126:129], v[18:33]
	v_exp_f32_e32 v60, v66
	v_exp_f32_e32 v61, v67
	ds_read_b128 v[62:65], v146 offset:4672
	v_pk_add_f32 v[66:67], v[60:61], v[58:59]
	v_cvt_pk_bf16_f32 v58, v60, v61
	v_exp_f32_e32 v60, v68
	v_exp_f32_e32 v61, v69
	s_nop 0
	v_pk_add_f32 v[66:67], v[60:61], v[66:67]
	v_cvt_pk_bf16_f32 v59, v60, v61
	s_waitcnt lgkmcnt(1)
	v_mfma_f32_32x32x16_bf16 v[18:33], v[108:111], v[122:125], v[18:33]
	v_exp_f32_e32 v60, v70
	v_exp_f32_e32 v61, v71
	ds_read_b128 v[100:103], v146 offset:4704
	v_exp_f32_e32 v68, v72
	v_exp_f32_e32 v69, v73
	v_pk_add_f32 v[66:67], v[60:61], v[66:67]
	v_cvt_pk_bf16_f32 v60, v60, v61
	v_pk_add_f32 v[66:67], v[68:69], v[66:67]
	v_cvt_pk_bf16_f32 v61, v68, v69
	s_waitcnt lgkmcnt(1)
	v_mfma_f32_32x32x16_bf16 v[18:33], v[62:65], v[118:121], v[18:33]
	v_add_u32_e32 v99, 0xf000, v142
	v_exp_f32_e32 v62, v74
	v_exp_f32_e32 v63, v75
	ds_read2_b64 v[104:107], v99 offset0:192 offset1:194
	v_exp_f32_e32 v68, v76
	v_exp_f32_e32 v69, v77
	v_pk_add_f32 v[64:65], v[62:63], v[66:67]
	v_cvt_pk_bf16_f32 v62, v62, v63
	v_pk_add_f32 v[66:67], v[68:69], v[64:65]
	v_cvt_pk_bf16_f32 v63, v68, v69
	s_waitcnt lgkmcnt(1)
	v_mfma_f32_32x32x16_bf16 v[18:33], v[100:103], v[114:117], v[18:33]
	v_add_u32_e32 v108, 0x7000, v147
	ds_read2_b64 v[72:75], v108 offset0:224 offset1:226
	v_exp_f32_e32 v68, v78
	v_exp_f32_e32 v69, v79
	v_exp_f32_e32 v70, v80
	v_exp_f32_e32 v71, v81
	v_cvt_pk_bf16_f32 v64, v68, v69
	v_cvt_pk_bf16_f32 v65, v70, v71
	s_waitcnt lgkmcnt(1)
	v_mfma_f32_32x32x16_bf16 v[34:49], v[104:107], v[50:53], v[34:49]
	v_sub_u32_e32 v100, v138, v1
	v_add_u32_e32 v80, 0xffffff7f, v100
	ds_read2_b64 v[76:79], v99 offset0:196 offset1:198
	v_cmp_lt_u32_e32 vcc, s95, v80
	v_add_u32_e32 v81, 0xffffff7e, v100
	s_nop 0
	v_cndmask_b32_e32 v80, v243, v82, vcc
	v_cmp_lt_u32_e32 vcc, s95, v81
	v_add_u32_e32 v82, 0xffffff7d, v100
	s_nop 0
	v_cndmask_b32_e32 v81, v243, v83, vcc
	v_cmp_lt_u32_e32 vcc, s95, v82
	v_add_u32_e32 v83, 0xffffff7c, v100
	v_max3_f32 v80, v231, v80, v81
	s_nop 0
	v_cndmask_b32_e32 v82, v243, v84, vcc
	v_cmp_lt_u32_e32 vcc, s95, v83
	s_nop 1
	v_cndmask_b32_e32 v83, v243, v85, vcc
	v_max3_f32 v84, v80, v82, v83
	s_waitcnt lgkmcnt(1)
	v_mfma_f32_32x32x16_bf16 v[2:17], v[72:75], v[50:53], v[2:17]
	v_add_u32_e32 v50, 0xffffff77, v100
	ds_read2_b64 v[80:83], v108 offset0:228 offset1:230
	v_cmp_lt_u32_e32 vcc, s95, v50
	v_add_u32_e32 v51, 0xffffff76, v100
	v_add_u32_e32 v52, 0xffffff75, v100
	v_cndmask_b32_e32 v50, v243, v86, vcc
	v_cmp_lt_u32_e32 vcc, s95, v51
	v_add_u32_e32 v53, 0xffffff74, v100
	s_nop 0
	v_cndmask_b32_e32 v51, v243, v87, vcc
	v_cmp_lt_u32_e32 vcc, s95, v52
	v_max3_f32 v50, v84, v50, v51
	s_nop 1
	v_cndmask_b32_e32 v52, v243, v88, vcc
	v_cmp_lt_u32_e32 vcc, s95, v53
	s_nop 1
	v_cndmask_b32_e32 v53, v243, v89, vcc
	v_max3_f32 v72, v50, v52, v53
	s_waitcnt lgkmcnt(1)
	v_mfma_f32_32x32x16_bf16 v[34:49], v[76:79], v[54:57], v[34:49]
	v_add_u32_e32 v73, 0xffffff6f, v100
	v_cmp_lt_u32_e32 vcc, s95, v73
	v_add_u32_e32 v74, 0xffffff6e, v100
	ds_read2_b64 v[50:53], v99 offset0:200 offset1:202
	v_cndmask_b32_e32 v73, v243, v90, vcc
	v_cmp_lt_u32_e32 vcc, s95, v74
	v_add_u32_e32 v75, 0xffffff6d, v100
	v_add_u32_e32 v76, 0xffffff6c, v100
	v_cndmask_b32_e32 v74, v243, v91, vcc
	v_cmp_lt_u32_e32 vcc, s95, v75
	v_max3_f32 v72, v72, v73, v74
	s_nop 1
	v_cndmask_b32_e32 v75, v243, v92, vcc
	v_cmp_lt_u32_e32 vcc, s95, v76
	s_nop 1
	v_cndmask_b32_e32 v76, v243, v93, vcc
	v_max3_f32 v76, v72, v75, v76
	s_waitcnt lgkmcnt(1)
	v_mfma_f32_32x32x16_bf16 v[2:17], v[80:83], v[54:57], v[2:17]
	v_add_u32_e32 v54, 0xffffff67, v100
	ds_read2_b64 v[72:75], v108 offset0:232 offset1:234
	v_cmp_lt_u32_e32 vcc, s95, v54
	v_add_u32_e32 v55, 0xffffff66, v100
	v_add_u32_e32 v56, 0xffffff65, v100
	v_cndmask_b32_e32 v54, v243, v94, vcc
	v_cmp_lt_u32_e32 vcc, s95, v55
	v_add_u32_e32 v57, 0xffffff64, v100
	s_nop 0
	v_cndmask_b32_e32 v55, v243, v95, vcc
	v_cmp_lt_u32_e32 vcc, s95, v56
	v_max3_f32 v54, v76, v54, v55
	s_nop 1
	v_cndmask_b32_e32 v56, v243, v96, vcc
	v_cmp_lt_u32_e32 vcc, s95, v57
	s_nop 1
	v_cndmask_b32_e32 v57, v243, v97, vcc
	v_max3_f32 v76, v54, v56, v57
	s_waitcnt lgkmcnt(1)
	v_mfma_f32_32x32x16_bf16 v[34:49], v[50:53], v[58:61], v[34:49]
	v_add_u32_e32 v77, 0xffffff5f, v100
	ds_read2_b64 v[54:57], v99 offset0:204 offset1:206
	v_cmp_lt_u32_e32 vcc, s95, v77
	v_add_u32_e32 v77, 0xffffff5e, v100
	v_add_u32_e32 v50, 0xffffff5d, v100
	v_cndmask_b32_e32 v18, v243, v18, vcc
	v_cmp_lt_u32_e32 vcc, s95, v77
	s_nop 1
	v_cndmask_b32_e32 v19, v243, v19, vcc
	v_cmp_lt_u32_e32 vcc, s95, v50
	v_add_u32_e32 v50, 0xffffff5c, v100
	v_max3_f32 v18, v76, v18, v19
	s_nop 0
	v_cndmask_b32_e32 v20, v243, v20, vcc
	v_cmp_lt_u32_e32 vcc, s95, v50
	s_nop 1
	v_cndmask_b32_e32 v21, v243, v21, vcc
	v_max3_f32 v50, v18, v20, v21
	s_waitcnt lgkmcnt(1)
	v_mfma_f32_32x32x16_bf16 v[2:17], v[72:75], v[58:61], v[2:17]
	ds_read2_b64 v[18:21], v108 offset0:236 offset1:238
	v_add_u32_e32 v51, 0xffffff57, v100
	v_cmp_lt_u32_e32 vcc, s95, v51
	v_add_u32_e32 v51, 0xffffff56, v100
	s_nop 0
	v_cndmask_b32_e32 v22, v243, v22, vcc
	v_cmp_lt_u32_e32 vcc, s95, v51
	v_add_u32_e32 v51, 0xffffff55, v100
	s_nop 0
	v_cndmask_b32_e32 v23, v243, v23, vcc
	v_cmp_lt_u32_e32 vcc, s95, v51
	v_add_u32_e32 v51, 0xffffff54, v100
	v_max3_f32 v22, v50, v22, v23
	s_nop 0
	v_cndmask_b32_e32 v24, v243, v24, vcc
	v_cmp_lt_u32_e32 vcc, s95, v51
	s_nop 1
	v_cndmask_b32_e32 v25, v243, v25, vcc
	v_max3_f32 v22, v22, v24, v25
	s_waitcnt lgkmcnt(1)
	v_mfma_f32_32x32x16_bf16 v[34:49], v[54:57], v[62:65], v[34:49]
	v_add_u32_e32 v23, 0xffffff4f, v100
	v_cmp_lt_u32_e32 vcc, s95, v23
	v_add_u32_e32 v24, 0xffffff4e, v100
	v_add_u32_e32 v25, 0xffffff4d, v100
	v_cndmask_b32_e32 v23, v243, v26, vcc
	v_cmp_lt_u32_e32 vcc, s95, v24
	v_add_u32_e32 v26, 0xffffff4c, v100
	s_nop 0
	v_cndmask_b32_e32 v24, v243, v27, vcc
	v_cmp_lt_u32_e32 vcc, s95, v25
	v_max3_f32 v22, v22, v23, v24
	s_nop 1
	v_cndmask_b32_e32 v25, v243, v28, vcc
	v_cmp_lt_u32_e32 vcc, s95, v26
	s_nop 1
	v_cndmask_b32_e32 v26, v243, v29, vcc
	v_max3_f32 v22, v22, v25, v26
	s_waitcnt lgkmcnt(0)
	v_mfma_f32_32x32x16_bf16 v[2:17], v[18:21], v[62:65], v[2:17]
	v_add_u32_e32 v18, 0xffffff47, v100
	v_cmp_lt_u32_e32 vcc, s95, v18
	v_add_u32_e32 v19, 0xffffff46, v100
	v_add_u32_e32 v20, 0xffffff45, v100
	v_cndmask_b32_e32 v18, v243, v30, vcc
	v_cmp_lt_u32_e32 vcc, s95, v19
	v_add_u32_e32 v21, 0xffffff44, v100
	s_nop 0
	v_cndmask_b32_e32 v19, v243, v31, vcc
	v_cmp_lt_u32_e32 vcc, s95, v20
	v_max3_f32 v18, v22, v18, v19
	s_nop 1
	v_cndmask_b32_e32 v20, v243, v32, vcc
	v_cmp_lt_u32_e32 vcc, s95, v21
	s_nop 1
	v_cndmask_b32_e32 v21, v243, v33, vcc
	v_max3_f32 v18, v18, v20, v21
	v_pk_add_f32 v[20:21], v[68:69], v[66:67]
	s_nop 0
	v_pk_add_f32 v[20:21], v[70:71], v[20:21]
	v_add_f32_e32 v19, v20, v21
	v_add_f32_e32 v68, v98, v19
	v_add_f32_e32 v19, v140, v18
	v_cmp_gt_f32_e32 vcc, v19, v143
	s_cbranch_vccz .LBB0_816
	v_mbcnt_hi_u32_b32 v66, -1, v232
	v_and_b32_e32 v19, 64, v66
	v_xor_b32_e32 v67, 32, v66
	v_add_u32_e32 v69, 64, v19
	v_cmp_lt_i32_e32 vcc, v67, v69
	v_max_f32_e32 v20, v141, v141
	s_nop 0
	v_cndmask_b32_e32 v19, v66, v67, vcc
	v_lshlrev_b32_e32 v19, 2, v19
	ds_bpermute_b32 v19, v19, v18
	v_max_f32_e32 v18, v18, v18
	s_waitcnt lgkmcnt(0)
	v_max_f32_e32 v19, v19, v19
	v_max_f32_e32 v18, v18, v19
	v_add_f32_e32 v18, v140, v18
	v_max_f32_e32 v18, v20, v18
	v_sub_f32_e32 v18, v141, v18
	v_exp_f32_e32 v70, v18
	s_nop 0
	v_pk_mul_f32 v[64:65], v[48:49], v[70:71] op_sel_hi:[1,0]
	v_pk_mul_f32 v[62:63], v[46:47], v[70:71] op_sel_hi:[1,0]
	v_pk_mul_f32 v[60:61], v[44:45], v[70:71] op_sel_hi:[1,0]
	v_pk_mul_f32 v[58:59], v[42:43], v[70:71] op_sel_hi:[1,0]
	v_pk_mul_f32 v[56:57], v[40:41], v[70:71] op_sel_hi:[1,0]
	v_pk_mul_f32 v[54:55], v[38:39], v[70:71] op_sel_hi:[1,0]
	v_pk_mul_f32 v[52:53], v[36:37], v[70:71] op_sel_hi:[1,0]
	v_pk_mul_f32 v[50:51], v[34:35], v[70:71] op_sel_hi:[1,0]
	v_pk_mul_f32 v[32:33], v[16:17], v[70:71] op_sel_hi:[1,0]
	v_pk_mul_f32 v[30:31], v[14:15], v[70:71] op_sel_hi:[1,0]
	v_pk_mul_f32 v[28:29], v[12:13], v[70:71] op_sel_hi:[1,0]
	v_pk_mul_f32 v[26:27], v[10:11], v[70:71] op_sel_hi:[1,0]
	v_pk_mul_f32 v[24:25], v[8:9], v[70:71] op_sel_hi:[1,0]
	v_pk_mul_f32 v[22:23], v[6:7], v[70:71] op_sel_hi:[1,0]
	v_pk_mul_f32 v[20:21], v[4:5], v[70:71] op_sel_hi:[1,0]
	v_pk_mul_f32 v[18:19], v[2:3], v[70:71] op_sel_hi:[1,0]
	v_mul_f32_e32 v70, v68, v70
	s_cbranch_execnz .LBB0_787

.LBB0_818:
	s_barrier
	s_waitcnt vmcnt(1)
	ds_write_b128 v165, v[136:139] offset:39936
	s_and_saveexec_b64 s[2:3], s[0:1]
	ds_write_b128 v1, v[36:39] offset:39936
	s_or_b64 exec, exec, s[2:3]
	v_mul_u32_u24_e32 v53, 0x68, v51
	v_add_u32_e32 v90, 0xd000, v161
	v_lshl_add_u32 v53, v53, 1, 0
	s_waitcnt vmcnt(0)
	v_lshrrev_b32_e32 v168, 16, v140
	v_lshrrev_b32_e32 v169, 16, v141
	v_lshrrev_b32_e32 v170, 16, v142
	v_lshrrev_b32_e32 v171, 16, v143
	v_lshl_add_u32 v166, v52, 1, v53
	v_mul_i32_i24_e32 v51, 0xffffffb8, v51
	ds_write_b16 v90, v140 offset:26112
	ds_write_b16 v90, v168 offset:26248
	ds_write_b16 v90, v141 offset:26384
	ds_write_b16 v90, v169 offset:26520
	ds_write_b16 v90, v142 offset:26656
	ds_write_b16 v90, v170 offset:26792
	ds_write_b16 v90, v143 offset:26928
	ds_write_b16 v90, v171 offset:27064
	v_add3_u32 v172, v53, v51, v52
	ds_read_b128 v[52:55], v166 offset:13312
	ds_read_b128 v[56:59], v166 offset:13344
	v_mov_b32_e32 v35, v34
	v_mov_b32_e32 v36, v34
	v_mov_b32_e32 v37, v34
	v_mov_b32_e32 v38, v34
	v_mov_b32_e32 v39, v34
	v_mov_b32_e32 v40, v34
	v_mov_b32_e32 v41, v34
	v_mov_b32_e32 v42, v34
	v_mov_b32_e32 v43, v34
	v_mov_b32_e32 v44, v34
	v_mov_b32_e32 v45, v34
	v_mov_b32_e32 v46, v34
	v_mov_b32_e32 v47, v34
	v_mov_b32_e32 v48, v34
	v_mov_b32_e32 v49, v34
	s_waitcnt lgkmcnt(1)
	s_nop 0
	v_mfma_f32_32x32x16_bf16 v[66:81], v[52:55], v[128:131], v[34:49]
	v_exp_f32_e32 v18, v18
	v_exp_f32_e32 v19, v19
	ds_read_b128 v[60:63], v166 offset:13376
	v_exp_f32_e32 v20, v20
	v_exp_f32_e32 v21, v21
	v_cvt_pk_bf16_f32 v86, v18, v19
	v_pk_add_f32 v[18:19], v[18:19], 0 op_sel_hi:[1,0]
	v_cvt_pk_bf16_f32 v87, v20, v21
	v_pk_add_f32 v[52:53], v[20:21], v[18:19]
	s_waitcnt lgkmcnt(1)
	v_mfma_f32_32x32x16_bf16 v[66:81], v[56:59], v[124:127], v[66:81]
	ds_read_b128 v[18:21], v166 offset:13408
	v_exp_f32_e32 v22, v22
	v_exp_f32_e32 v23, v23
	v_exp_f32_e32 v24, v24
	v_exp_f32_e32 v25, v25
	v_cvt_pk_bf16_f32 v88, v22, v23
	v_pk_add_f32 v[22:23], v[22:23], v[52:53]
	v_cvt_pk_bf16_f32 v89, v24, v25
	v_pk_add_f32 v[52:53], v[24:25], v[22:23]
	s_waitcnt lgkmcnt(1)
	v_mfma_f32_32x32x16_bf16 v[66:81], v[60:63], v[120:123], v[66:81]
	ds_read_b128 v[22:25], v166 offset:13440
	v_exp_f32_e32 v26, v26
	v_exp_f32_e32 v27, v27
	v_exp_f32_e32 v28, v28
	v_exp_f32_e32 v29, v29
	v_cvt_pk_bf16_f32 v148, v26, v27
	v_pk_add_f32 v[26:27], v[26:27], v[52:53]
	v_cvt_pk_bf16_f32 v149, v28, v29
	v_pk_add_f32 v[52:53], v[28:29], v[26:27]
	s_waitcnt lgkmcnt(1)
	v_mfma_f32_32x32x16_bf16 v[66:81], v[18:21], v[116:119], v[66:81]
	v_exp_f32_e32 v18, v30
	v_exp_f32_e32 v19, v31
	ds_read_b128 v[26:29], v166 offset:13472
	v_exp_f32_e32 v20, v32
	v_exp_f32_e32 v21, v33
	v_cvt_pk_bf16_f32 v150, v18, v19
	v_pk_add_f32 v[18:19], v[18:19], v[52:53]
	v_cvt_pk_bf16_f32 v151, v20, v21
	v_pk_add_f32 v[30:31], v[20:21], v[18:19]
	s_waitcnt lgkmcnt(1)
	v_mfma_f32_32x32x16_bf16 v[66:81], v[22:25], v[112:115], v[66:81]
	ds_read_b128 v[18:21], v166 offset:19968
	v_exp_f32_e32 v2, v2
	v_exp_f32_e32 v3, v3
	s_nop 0
	v_pk_add_f32 v[30:31], v[2:3], v[30:31]
	v_cvt_pk_bf16_f32 v152, v2, v3
	s_waitcnt lgkmcnt(1)
	v_mfma_f32_32x32x16_bf16 v[66:81], v[26:29], v[108:111], v[66:81]
	ds_read_b128 v[22:25], v166 offset:20000
	v_exp_f32_e32 v2, v4
	v_exp_f32_e32 v3, v5
	s_nop 0
	v_pk_add_f32 v[26:27], v[2:3], v[30:31]
	v_cvt_pk_bf16_f32 v153, v2, v3
	s_waitcnt lgkmcnt(1)
	v_mfma_f32_32x32x16_bf16 v[92:107], v[18:21], v[128:131], v[34:49]
	v_exp_f32_e32 v6, v6
	v_exp_f32_e32 v7, v7
	ds_read_b128 v[2:5], v166 offset:20032
	v_pk_add_f32 v[26:27], v[6:7], v[26:27]
	v_cvt_pk_bf16_f32 v154, v6, v7
	s_waitcnt lgkmcnt(1)
	v_mfma_f32_32x32x16_bf16 v[92:107], v[22:25], v[124:127], v[92:107]
	ds_read_b128 v[18:21], v166 offset:20064
	v_exp_f32_e32 v6, v8
	v_exp_f32_e32 v7, v9
	s_nop 0
	v_pk_add_f32 v[22:23], v[6:7], v[26:27]
	v_cvt_pk_bf16_f32 v155, v6, v7
	s_waitcnt lgkmcnt(1)
	v_mfma_f32_32x32x16_bf16 v[92:107], v[2:5], v[120:123], v[92:107]
	ds_read_b128 v[6:9], v166 offset:20096
	v_exp_f32_e32 v2, v10
	v_exp_f32_e32 v3, v11
	s_nop 0
	v_pk_add_f32 v[10:11], v[2:3], v[22:23]
	v_cvt_pk_bf16_f32 v156, v2, v3
	s_waitcnt lgkmcnt(1)
	v_mfma_f32_32x32x16_bf16 v[92:107], v[18:21], v[116:119], v[92:107]
	ds_read_b128 v[2:5], v166 offset:20128
	v_exp_f32_e32 v12, v12
	v_exp_f32_e32 v13, v13
	s_nop 0
	v_pk_add_f32 v[18:19], v[12:13], v[10:11]
	v_cvt_pk_bf16_f32 v157, v12, v13
	s_waitcnt lgkmcnt(1)
	v_mfma_f32_32x32x16_bf16 v[92:107], v[6:9], v[112:115], v[92:107]
	v_add_u32_e32 v167, 0xd000, v172
	ds_read2_b64 v[10:13], v167 offset1:2
	v_exp_f32_e32 v6, v14
	v_exp_f32_e32 v7, v15
	s_nop 0
	v_pk_add_f32 v[8:9], v[6:7], v[18:19]
	v_cvt_pk_bf16_f32 v158, v6, v7
	s_waitcnt lgkmcnt(1)
	v_mfma_f32_32x32x16_bf16 v[92:107], v[2:5], v[108:111], v[92:107]
	v_add_u32_e32 v91, 0xe000, v172
	v_exp_f32_e32 v6, v16
	v_exp_f32_e32 v7, v17
	ds_read2_b64 v[174:177], v91 offset0:32 offset1:34
	v_pk_add_f32 v[188:189], v[6:7], v[8:9]
	v_cvt_pk_bf16_f32 v159, v6, v7
	v_mov_b32_e32 v51, v50
	v_mov_b32_e32 v52, v50
	v_mov_b32_e32 v53, v50
	v_mov_b32_e32 v54, v50
	v_mov_b32_e32 v55, v50
	v_mov_b32_e32 v56, v50
	v_mov_b32_e32 v57, v50
	v_mov_b32_e32 v58, v50
	v_mov_b32_e32 v59, v50
	v_mov_b32_e32 v60, v50
	v_mov_b32_e32 v61, v50
	v_mov_b32_e32 v62, v50
	v_mov_b32_e32 v63, v50
	v_mov_b32_e32 v64, v50
	v_mov_b32_e32 v65, v50
	ds_read2_b64 v[178:181], v167 offset0:4 offset1:6
	v_max3_f32 v2, v231, v66, v67
	s_waitcnt lgkmcnt(2)
	v_mfma_f32_32x32x16_bf16 v[18:33], v[10:13], v[86:89], v[50:65]
	v_max3_f32 v173, v2, v68, v69
	v_mov_b64_e32 v[2:3], v[50:51]
	v_mov_b64_e32 v[4:5], v[52:53]
	v_mov_b64_e32 v[6:7], v[54:55]
	v_mov_b64_e32 v[8:9], v[56:57]
	v_mov_b64_e32 v[10:11], v[58:59]
	v_mov_b64_e32 v[12:13], v[60:61]
	v_mov_b64_e32 v[14:15], v[62:63]
	v_mov_b64_e32 v[16:17], v[64:65]
	ds_read2_b64 v[184:187], v91 offset0:36 offset1:38
	v_max3_f32 v51, v173, v70, v71
	s_waitcnt lgkmcnt(2)
	v_mfma_f32_32x32x16_bf16 v[2:17], v[174:177], v[86:89], v[2:17]
	v_max3_f32 v51, v51, v72, v73
	s_waitcnt lgkmcnt(1)
	v_mfma_f32_32x32x16_bf16 v[18:33], v[178:181], v[148:151], v[18:33]
	ds_read2_b64 v[52:55], v167 offset0:8 offset1:10
	v_max3_f32 v51, v51, v74, v75
	s_nop 0
	v_max3_f32 v51, v51, v76, v77
	s_waitcnt lgkmcnt(1)
	v_mfma_f32_32x32x16_bf16 v[2:17], v[184:187], v[148:151], v[2:17]
	ds_read2_b64 v[56:59], v91 offset0:40 offset1:42
	v_max3_f32 v51, v51, v78, v79
	s_nop 0
	v_max3_f32 v51, v51, v80, v81
	s_waitcnt lgkmcnt(1)
	v_mfma_f32_32x32x16_bf16 v[18:33], v[52:55], v[152:155], v[18:33]
	ds_read2_b64 v[60:63], v167 offset0:12 offset1:14
	v_max3_f32 v51, v51, v92, v93
	s_nop 0
	v_max3_f32 v51, v51, v94, v95
	s_waitcnt lgkmcnt(1)
	v_mfma_f32_32x32x16_bf16 v[2:17], v[56:59], v[152:155], v[2:17]
	ds_read2_b64 v[52:55], v91 offset0:44 offset1:46
	v_max3_f32 v51, v51, v96, v97
	s_nop 0
	v_max3_f32 v51, v51, v98, v99
	s_waitcnt lgkmcnt(1)
	v_mfma_f32_32x32x16_bf16 v[18:33], v[60:63], v[156:159], v[18:33]
	v_max3_f32 v51, v51, v100, v101
	s_nop 0
	v_max3_f32 v51, v51, v102, v103
	s_waitcnt lgkmcnt(0)
	v_mfma_f32_32x32x16_bf16 v[2:17], v[52:55], v[156:159], v[2:17]
	v_max3_f32 v51, v51, v104, v105
	s_nop 0
	v_max3_f32 v208, v51, v106, v107
	v_add_f32_e32 v51, v188, v189
	v_add_f32_e32 v150, v50, v51
	v_add_f32_e64 v50, v162, v208
	v_add_f32_e64 v51, v163, v209
	v_cmp_gt_f32_e32 vcc, v50, v51
	s_cbranch_vccz .LBB0_928
	v_mbcnt_hi_u32_b32 v34, -1, v232
	v_and_b32_e32 v36, 64, v34
	v_xor_b32_e32 v35, 32, v34
	v_add_u32_e32 v36, 64, v36
	v_cmp_lt_i32_e32 vcc, v35, v36
	v_max_f32_e32 v36, v163, v163
	s_nop 0
	v_cndmask_b32_e32 v34, v34, v35, vcc
	v_lshlrev_b32_e32 v34, 2, v34
	ds_bpermute_b32 v34, v34, v208
	v_max_f32_e32 v35, v208, v208
	s_waitcnt lgkmcnt(0)
	v_max_f32_e32 v34, v34, v34
	v_max_f32_e32 v34, v35, v34
	v_add_f32_e32 v34, v162, v34
	v_max_f32_e32 v148, v36, v34
	v_sub_f32_e32 v34, v163, v148
	v_exp_f32_e32 v36, v34
	v_sub_f32_e32 v34, v162, v148
	v_pk_add_f32 v[80:81], v[80:81], v[34:35] op_sel_hi:[1,0]
	v_pk_add_f32 v[78:79], v[78:79], v[34:35] op_sel_hi:[1,0]
	v_pk_add_f32 v[76:77], v[76:77], v[34:35] op_sel_hi:[1,0]
	v_pk_add_f32 v[74:75], v[74:75], v[34:35] op_sel_hi:[1,0]
	v_pk_add_f32 v[72:73], v[72:73], v[34:35] op_sel_hi:[1,0]
	v_pk_add_f32 v[70:71], v[70:71], v[34:35] op_sel_hi:[1,0]
	v_pk_add_f32 v[68:69], v[68:69], v[34:35] op_sel_hi:[1,0]
	v_pk_add_f32 v[66:67], v[66:67], v[34:35] op_sel_hi:[1,0]
	v_pk_add_f32 v[106:107], v[106:107], v[34:35] op_sel_hi:[1,0]
	v_pk_add_f32 v[104:105], v[104:105], v[34:35] op_sel_hi:[1,0]
	v_pk_add_f32 v[102:103], v[102:103], v[34:35] op_sel_hi:[1,0]
	v_pk_add_f32 v[100:101], v[100:101], v[34:35] op_sel_hi:[1,0]
	v_pk_add_f32 v[98:99], v[98:99], v[34:35] op_sel_hi:[1,0]
	v_pk_add_f32 v[96:97], v[96:97], v[34:35] op_sel_hi:[1,0]
	v_pk_add_f32 v[94:95], v[94:95], v[34:35] op_sel_hi:[1,0]
	v_pk_add_f32 v[92:93], v[92:93], v[34:35] op_sel_hi:[1,0]
	v_xor_b32_e32 v34, 0x80000000, v148
	v_pk_mul_f32 v[16:17], v[16:17], v[36:37] op_sel_hi:[1,0]
	v_pk_mul_f32 v[14:15], v[14:15], v[36:37] op_sel_hi:[1,0]
	v_pk_mul_f32 v[12:13], v[12:13], v[36:37] op_sel_hi:[1,0]
	v_pk_mul_f32 v[10:11], v[10:11], v[36:37] op_sel_hi:[1,0]
	v_pk_mul_f32 v[8:9], v[8:9], v[36:37] op_sel_hi:[1,0]
	v_pk_mul_f32 v[6:7], v[6:7], v[36:37] op_sel_hi:[1,0]
	v_pk_mul_f32 v[4:5], v[4:5], v[36:37] op_sel_hi:[1,0]
	v_pk_mul_f32 v[2:3], v[2:3], v[36:37] op_sel_hi:[1,0]
	v_pk_mul_f32 v[32:33], v[32:33], v[36:37] op_sel_hi:[1,0]
	v_pk_mul_f32 v[30:31], v[30:31], v[36:37] op_sel_hi:[1,0]
	v_pk_mul_f32 v[28:29], v[28:29], v[36:37] op_sel_hi:[1,0]
	v_pk_mul_f32 v[26:27], v[26:27], v[36:37] op_sel_hi:[1,0]
	v_pk_mul_f32 v[24:25], v[24:25], v[36:37] op_sel_hi:[1,0]
	v_pk_mul_f32 v[22:23], v[22:23], v[36:37] op_sel_hi:[1,0]
	v_pk_mul_f32 v[20:21], v[20:21], v[36:37] op_sel_hi:[1,0]
	v_pk_mul_f32 v[18:19], v[18:19], v[36:37] op_sel_hi:[1,0]
	v_mul_f32_e32 v150, v150, v36
	v_mov_b32_e32 v149, v148
	v_mov_b32_e32 v35, v34
	v_mov_b32_e32 v36, v34
	v_mov_b32_e32 v37, v34
	v_mov_b32_e32 v38, v34
	v_mov_b32_e32 v39, v34
	v_mov_b32_e32 v40, v34
	v_mov_b32_e32 v41, v34
	v_mov_b32_e32 v42, v34
	v_mov_b32_e32 v43, v34
	v_mov_b32_e32 v44, v34
	v_mov_b32_e32 v45, v34
	v_mov_b32_e32 v46, v34
	v_mov_b32_e32 v47, v34
	v_mov_b32_e32 v48, v34
	v_mov_b32_e32 v49, v34
	v_mov_b32_e32 v162, v148
	v_mov_b32_e32 v163, v148
	ds_write_b128 v165, v[136:139]
	s_and_saveexec_b64 s[2:3], s[0:1]

.LBB0_823:
	s_or_b64 exec, exec, s[2:3]
	ds_write_b16 v90, v140 offset:34816
	ds_write_b16 v90, v168 offset:34952
	ds_write_b16 v90, v141 offset:35088
	ds_write_b16 v90, v169 offset:35224
	ds_write_b16 v90, v142 offset:35360
	ds_write_b16 v90, v170 offset:35496
	ds_write_b16 v90, v143 offset:35632
	ds_write_b16 v90, v171 offset:35768
	ds_read_b128 v[82:85], v166 offset:26624
	ds_read_b128 v[86:89], v166 offset:26656
	s_waitcnt lgkmcnt(1)
	v_mfma_f32_32x32x16_bf16 v[50:65], v[82:85], v[128:131], v[34:49]
	v_exp_f32_e32 v82, v66
	v_exp_f32_e32 v83, v67
	v_exp_f32_e32 v68, v68
	v_exp_f32_e32 v69, v69
	ds_read_b128 v[152:155], v166 offset:26688
	v_cvt_pk_bf16_f32 v66, v82, v83
	v_pk_add_f32 v[82:83], v[82:83], 0 op_sel_hi:[1,0]
	v_cvt_pk_bf16_f32 v67, v68, v69
	v_pk_add_f32 v[90:91], v[68:69], v[82:83]
	s_waitcnt lgkmcnt(1)
	v_mfma_f32_32x32x16_bf16 v[50:65], v[86:89], v[124:127], v[50:65]
	v_exp_f32_e32 v70, v70
	v_exp_f32_e32 v71, v71
	ds_read_b128 v[82:85], v166 offset:26720
	v_exp_f32_e32 v72, v72
	v_exp_f32_e32 v73, v73
	v_cvt_pk_bf16_f32 v68, v70, v71
	v_pk_add_f32 v[70:71], v[70:71], v[90:91]
	v_cvt_pk_bf16_f32 v69, v72, v73
	v_pk_add_f32 v[90:91], v[72:73], v[70:71]
	s_waitcnt lgkmcnt(1)
	v_mfma_f32_32x32x16_bf16 v[50:65], v[152:155], v[120:123], v[50:65]
	ds_read_b128 v[86:89], v166 offset:26752
	v_exp_f32_e32 v72, v74
	v_exp_f32_e32 v73, v75
	v_exp_f32_e32 v74, v76
	v_exp_f32_e32 v75, v77
	v_cvt_pk_bf16_f32 v70, v72, v73
	v_pk_add_f32 v[72:73], v[72:73], v[90:91]
	v_cvt_pk_bf16_f32 v71, v74, v75
	v_pk_add_f32 v[76:77], v[74:75], v[72:73]
	s_waitcnt lgkmcnt(1)
	v_mfma_f32_32x32x16_bf16 v[50:65], v[82:85], v[116:119], v[50:65]
	v_exp_f32_e32 v74, v78
	v_exp_f32_e32 v75, v79
	ds_read_b128 v[152:155], v166 offset:26784
	v_cvt_pk_bf16_f32 v72, v74, v75
	v_pk_add_f32 v[74:75], v[74:75], v[76:77]
	v_exp_f32_e32 v76, v80
	v_exp_f32_e32 v77, v81
	s_nop 0
	v_pk_add_f32 v[74:75], v[76:77], v[74:75]
	v_cvt_pk_bf16_f32 v73, v76, v77
	s_waitcnt lgkmcnt(1)
	v_mfma_f32_32x32x16_bf16 v[50:65], v[86:89], v[112:115], v[50:65]
	v_exp_f32_e32 v76, v92
	v_exp_f32_e32 v77, v93
	ds_read_b128 v[78:81], v166 offset:33280
	v_pk_add_f32 v[82:83], v[76:77], v[74:75]
	v_cvt_pk_bf16_f32 v74, v76, v77
	s_waitcnt lgkmcnt(1)
	v_mfma_f32_32x32x16_bf16 v[50:65], v[152:155], v[108:111], v[50:65]
	v_exp_f32_e32 v76, v94
	v_exp_f32_e32 v77, v95
	ds_read_b128 v[156:159], v166 offset:33312
	v_pk_add_f32 v[82:83], v[76:77], v[82:83]
	v_cvt_pk_bf16_f32 v75, v76, v77
	v_exp_f32_e32 v76, v96
	v_exp_f32_e32 v77, v97
	ds_read_b128 v[152:155], v166 offset:33344
	v_pk_add_f32 v[178:179], v[76:77], v[82:83]
	s_waitcnt lgkmcnt(2)
	v_mfma_f32_32x32x16_bf16 v[82:97], v[78:81], v[128:131], v[34:49]
	v_cvt_pk_bf16_f32 v76, v76, v77
	s_waitcnt lgkmcnt(1)
	v_mfma_f32_32x32x16_bf16 v[82:97], v[156:159], v[124:127], v[82:97]
	ds_read_b128 v[174:177], v166 offset:33376
	v_exp_f32_e32 v78, v98
	v_exp_f32_e32 v79, v99
	s_nop 0
	v_pk_add_f32 v[80:81], v[78:79], v[178:179]
	v_cvt_pk_bf16_f32 v77, v78, v79
	s_waitcnt lgkmcnt(1)
	v_mfma_f32_32x32x16_bf16 v[82:97], v[152:155], v[120:123], v[82:97]
	ds_read_b128 v[156:159], v166 offset:33408
	v_exp_f32_e32 v78, v100
	v_exp_f32_e32 v79, v101
	s_nop 0
	v_pk_add_f32 v[80:81], v[78:79], v[80:81]
	v_cvt_pk_bf16_f32 v78, v78, v79
	s_waitcnt lgkmcnt(1)
	v_mfma_f32_32x32x16_bf16 v[82:97], v[174:177], v[116:119], v[82:97]
	ds_read_b128 v[152:155], v166 offset:33440
	v_exp_f32_e32 v98, v102
	v_exp_f32_e32 v99, v103
	s_nop 0
	v_pk_add_f32 v[80:81], v[98:99], v[80:81]
	v_cvt_pk_bf16_f32 v79, v98, v99
	s_waitcnt lgkmcnt(1)
	v_mfma_f32_32x32x16_bf16 v[82:97], v[156:159], v[112:115], v[82:97]
	v_add_u32_e32 v151, 0xf000, v172
	ds_read2_b64 v[100:103], v151 offset0:64 offset1:66
	v_exp_f32_e32 v98, v104
	v_exp_f32_e32 v99, v105
	s_nop 0
	v_pk_add_f32 v[156:157], v[98:99], v[80:81]
	v_cvt_pk_bf16_f32 v80, v98, v99
	s_waitcnt lgkmcnt(1)
	v_mfma_f32_32x32x16_bf16 v[82:97], v[152:155], v[108:111], v[82:97]
	v_add_u32_e32 v172, 0x3000, v167
	v_exp_f32_e32 v158, v106
	v_exp_f32_e32 v159, v107
	ds_read2_b64 v[104:107], v172 offset0:96 offset1:98
	v_pk_add_f32 v[98:99], v[158:159], v[156:157]
	v_cvt_pk_bf16_f32 v81, v158, v159
	s_waitcnt lgkmcnt(1)
	v_mfma_f32_32x32x16_bf16 v[18:33], v[100:103], v[66:69], v[18:33]
	ds_read2_b64 v[152:155], v151 offset0:68 offset1:70
	v_max3_f32 v100, v231, v50, v51
	s_nop 0
	v_max3_f32 v156, v100, v52, v53
	s_waitcnt lgkmcnt(1)
	v_mfma_f32_32x32x16_bf16 v[2:17], v[104:107], v[66:69], v[2:17]
	ds_read2_b64 v[100:103], v172 offset0:100 offset1:102
	v_max3_f32 v66, v156, v54, v55
	s_nop 0
	v_max3_f32 v104, v66, v56, v57
	s_waitcnt lgkmcnt(1)
	v_mfma_f32_32x32x16_bf16 v[18:33], v[152:155], v[70:73], v[18:33]
	ds_read2_b64 v[66:69], v151 offset0:72 offset1:74
	v_max3_f32 v104, v104, v58, v59
	s_nop 0
	v_max3_f32 v152, v104, v60, v61
	s_waitcnt lgkmcnt(1)
	v_mfma_f32_32x32x16_bf16 v[2:17], v[100:103], v[70:73], v[2:17]
	ds_read2_b64 v[104:107], v172 offset0:104 offset1:106
	v_max3_f32 v70, v152, v62, v63
	s_nop 0
	v_max3_f32 v100, v70, v64, v65
	s_waitcnt lgkmcnt(1)
	v_mfma_f32_32x32x16_bf16 v[18:33], v[66:69], v[74:77], v[18:33]
	ds_read2_b64 v[70:73], v151 offset0:76 offset1:78
	v_max3_f32 v100, v100, v82, v83
	s_nop 0
	v_max3_f32 v100, v100, v84, v85
	s_waitcnt lgkmcnt(1)
	v_mfma_f32_32x32x16_bf16 v[2:17], v[104:107], v[74:77], v[2:17]
	ds_read2_b64 v[66:69], v172 offset0:108 offset1:110
	v_max3_f32 v100, v100, v86, v87
	s_nop 0
	v_max3_f32 v100, v100, v88, v89
	s_waitcnt lgkmcnt(1)
	v_mfma_f32_32x32x16_bf16 v[18:33], v[70:73], v[78:81], v[18:33]
	v_max3_f32 v70, v100, v90, v91
	s_nop 0
	v_max3_f32 v70, v70, v92, v93
	s_waitcnt lgkmcnt(0)
	v_mfma_f32_32x32x16_bf16 v[2:17], v[66:69], v[78:81], v[2:17]
	v_max3_f32 v66, v70, v94, v95
	s_nop 0
	v_max3_f32 v208, v66, v96, v97
	v_add_f32_e32 v66, v98, v99
	v_add_f32_e32 v106, v150, v66
	v_add_f32_e64 v66, v148, v208
	v_add_f32_e64 v67, v149, v209
	v_cmp_gt_f32_e32 vcc, v66, v67
	s_cbranch_vccz .LBB0_825
	v_mbcnt_hi_u32_b32 v34, -1, v232
	v_and_b32_e32 v36, 64, v34
	v_xor_b32_e32 v35, 32, v34
	v_add_u32_e32 v36, 64, v36
	v_cmp_lt_i32_e32 vcc, v35, v36
	v_max_f32_e32 v36, v163, v163
	s_nop 0
	v_cndmask_b32_e32 v34, v34, v35, vcc
	v_lshlrev_b32_e32 v34, 2, v34
	ds_bpermute_b32 v34, v34, v208
	v_max_f32_e32 v35, v208, v208
	s_waitcnt lgkmcnt(0)
	v_max_f32_e32 v34, v34, v34
	v_max_f32_e32 v34, v35, v34
	v_add_f32_e32 v34, v162, v34
	v_max_f32_e32 v148, v36, v34
	v_sub_f32_e32 v34, v163, v148
	v_exp_f32_e32 v36, v34
	v_sub_f32_e32 v34, v162, v148
	v_pk_add_f32 v[64:65], v[64:65], v[34:35] op_sel_hi:[1,0]
	v_pk_add_f32 v[62:63], v[62:63], v[34:35] op_sel_hi:[1,0]
	v_pk_add_f32 v[60:61], v[60:61], v[34:35] op_sel_hi:[1,0]
	v_pk_add_f32 v[58:59], v[58:59], v[34:35] op_sel_hi:[1,0]
	v_pk_add_f32 v[56:57], v[56:57], v[34:35] op_sel_hi:[1,0]
	v_pk_add_f32 v[54:55], v[54:55], v[34:35] op_sel_hi:[1,0]
	v_pk_add_f32 v[52:53], v[52:53], v[34:35] op_sel_hi:[1,0]
	v_pk_add_f32 v[50:51], v[50:51], v[34:35] op_sel_hi:[1,0]
	v_pk_add_f32 v[96:97], v[96:97], v[34:35] op_sel_hi:[1,0]
	v_pk_add_f32 v[94:95], v[94:95], v[34:35] op_sel_hi:[1,0]
	v_pk_add_f32 v[92:93], v[92:93], v[34:35] op_sel_hi:[1,0]
	v_pk_add_f32 v[90:91], v[90:91], v[34:35] op_sel_hi:[1,0]
	v_pk_add_f32 v[88:89], v[88:89], v[34:35] op_sel_hi:[1,0]
	v_pk_add_f32 v[86:87], v[86:87], v[34:35] op_sel_hi:[1,0]
	v_pk_add_f32 v[84:85], v[84:85], v[34:35] op_sel_hi:[1,0]
	v_pk_add_f32 v[82:83], v[82:83], v[34:35] op_sel_hi:[1,0]
	v_xor_b32_e32 v34, 0x80000000, v148
	v_pk_mul_f32 v[16:17], v[16:17], v[36:37] op_sel_hi:[1,0]
	v_pk_mul_f32 v[14:15], v[14:15], v[36:37] op_sel_hi:[1,0]
	v_pk_mul_f32 v[12:13], v[12:13], v[36:37] op_sel_hi:[1,0]
	v_pk_mul_f32 v[10:11], v[10:11], v[36:37] op_sel_hi:[1,0]
	v_pk_mul_f32 v[8:9], v[8:9], v[36:37] op_sel_hi:[1,0]
	v_pk_mul_f32 v[6:7], v[6:7], v[36:37] op_sel_hi:[1,0]
	v_pk_mul_f32 v[4:5], v[4:5], v[36:37] op_sel_hi:[1,0]
	v_pk_mul_f32 v[2:3], v[2:3], v[36:37] op_sel_hi:[1,0]
	v_pk_mul_f32 v[32:33], v[32:33], v[36:37] op_sel_hi:[1,0]
	v_pk_mul_f32 v[30:31], v[30:31], v[36:37] op_sel_hi:[1,0]
	v_pk_mul_f32 v[28:29], v[28:29], v[36:37] op_sel_hi:[1,0]
	v_pk_mul_f32 v[26:27], v[26:27], v[36:37] op_sel_hi:[1,0]
	v_pk_mul_f32 v[24:25], v[24:25], v[36:37] op_sel_hi:[1,0]
	v_pk_mul_f32 v[22:23], v[22:23], v[36:37] op_sel_hi:[1,0]
	v_pk_mul_f32 v[20:21], v[20:21], v[36:37] op_sel_hi:[1,0]
	v_pk_mul_f32 v[18:19], v[18:19], v[36:37] op_sel_hi:[1,0]
	v_mul_f32_e32 v106, v106, v36
	v_mov_b32_e32 v149, v148
	v_mov_b32_e32 v35, v34
	v_mov_b32_e32 v36, v34
	v_mov_b32_e32 v37, v34
	v_mov_b32_e32 v38, v34
	v_mov_b32_e32 v39, v34
	v_mov_b32_e32 v40, v34
	v_mov_b32_e32 v41, v34
	v_mov_b32_e32 v42, v34
	v_mov_b32_e32 v43, v34
	v_mov_b32_e32 v44, v34
	v_mov_b32_e32 v45, v34
	v_mov_b32_e32 v46, v34
	v_mov_b32_e32 v47, v34
	v_mov_b32_e32 v48, v34
	v_mov_b32_e32 v49, v34
	v_mov_b32_e32 v162, v148
	v_mov_b32_e32 v163, v148
.LBB0_825:
	s_barrier
	ds_write_b128 v165, v[136:139] offset:13312
	s_and_saveexec_b64 s[2:3], s[0:1]
	ds_write_b128 v1, v[144:147] offset:13312
	s_or_b64 exec, exec, s[2:3]
	ds_write_b16 v161, v140 offset:53248
	ds_write_b16 v161, v168 offset:53384
	ds_write_b16 v161, v141 offset:53520
	ds_write_b16 v161, v169 offset:53656
	ds_write_b16 v161, v142 offset:53792
	ds_write_b16 v161, v170 offset:53928
	ds_write_b16 v161, v143 offset:54064
	ds_write_b16 v161, v171 offset:54200
	ds_read_b128 v[98:101], v166 offset:39936
	ds_read_b128 v[102:105], v166 offset:39968
	s_waitcnt lgkmcnt(1)
	v_mfma_f32_32x32x16_bf16 v[66:81], v[98:101], v[128:131], v[34:49]
	v_exp_f32_e32 v50, v50
	v_exp_f32_e32 v51, v51
	ds_read_b128 v[144:147], v166 offset:40000
	v_exp_f32_e32 v52, v52
	v_exp_f32_e32 v53, v53
	v_cvt_pk_bf16_f32 v98, v50, v51
	v_pk_add_f32 v[50:51], v[50:51], 0 op_sel_hi:[1,0]
	v_cvt_pk_bf16_f32 v99, v52, v53
	v_pk_add_f32 v[150:151], v[52:53], v[50:51]
	s_waitcnt lgkmcnt(1)
	v_mfma_f32_32x32x16_bf16 v[66:81], v[102:105], v[124:127], v[66:81]
	ds_read_b128 v[50:53], v166 offset:40032
	v_exp_f32_e32 v54, v54
	v_exp_f32_e32 v55, v55
	v_exp_f32_e32 v56, v56
	v_exp_f32_e32 v57, v57
	v_cvt_pk_bf16_f32 v100, v54, v55
	v_pk_add_f32 v[54:55], v[54:55], v[150:151]
	v_cvt_pk_bf16_f32 v101, v56, v57
	v_pk_add_f32 v[104:105], v[56:57], v[54:55]
	s_waitcnt lgkmcnt(1)
	v_mfma_f32_32x32x16_bf16 v[66:81], v[144:147], v[120:123], v[66:81]
	ds_read_b128 v[54:57], v166 offset:40064
	v_exp_f32_e32 v58, v58
	v_exp_f32_e32 v59, v59
	v_exp_f32_e32 v60, v60
	v_exp_f32_e32 v61, v61
	v_cvt_pk_bf16_f32 v102, v58, v59
	v_pk_add_f32 v[58:59], v[58:59], v[104:105]
	v_cvt_pk_bf16_f32 v103, v60, v61
	v_pk_add_f32 v[144:145], v[60:61], v[58:59]
	s_waitcnt lgkmcnt(1)
	v_mfma_f32_32x32x16_bf16 v[66:81], v[50:53], v[116:119], v[66:81]
	v_exp_f32_e32 v50, v62
	v_exp_f32_e32 v51, v63
	ds_read_b128 v[58:61], v166 offset:40096
	v_exp_f32_e32 v52, v64
	v_exp_f32_e32 v53, v65
	v_cvt_pk_bf16_f32 v104, v50, v51
	v_pk_add_f32 v[50:51], v[50:51], v[144:145]
	v_cvt_pk_bf16_f32 v105, v52, v53
	v_pk_add_f32 v[50:51], v[52:53], v[50:51]
	s_waitcnt lgkmcnt(1)
	v_mfma_f32_32x32x16_bf16 v[66:81], v[54:57], v[112:115], v[66:81]
	v_exp_f32_e32 v52, v82
	v_exp_f32_e32 v53, v83
	ds_read_b128 v[144:147], v166 offset:46592
	v_pk_add_f32 v[50:51], v[52:53], v[50:51]
	v_cvt_pk_bf16_f32 v82, v52, v53
	s_waitcnt lgkmcnt(1)
	v_mfma_f32_32x32x16_bf16 v[66:81], v[58:61], v[108:111], v[66:81]
	v_exp_f32_e32 v52, v84
	v_exp_f32_e32 v53, v85
	ds_read_b128 v[150:153], v166 offset:46624
	v_pk_add_f32 v[50:51], v[52:53], v[50:51]
	v_cvt_pk_bf16_f32 v83, v52, v53
	v_exp_f32_e32 v52, v86
	v_exp_f32_e32 v53, v87
	ds_read_b128 v[154:157], v166 offset:46656
	v_pk_add_f32 v[86:87], v[52:53], v[50:51]
	v_cvt_pk_bf16_f32 v84, v52, v53
	s_waitcnt lgkmcnt(2)
	v_mfma_f32_32x32x16_bf16 v[50:65], v[144:147], v[128:131], v[34:49]
	s_waitcnt lgkmcnt(1)
	v_mfma_f32_32x32x16_bf16 v[50:65], v[150:153], v[124:127], v[50:65]
	ds_read_b128 v[144:147], v166 offset:46688
	v_exp_f32_e32 v88, v88
	v_exp_f32_e32 v89, v89
	s_nop 0
	v_pk_add_f32 v[86:87], v[88:89], v[86:87]
	v_cvt_pk_bf16_f32 v85, v88, v89
	s_waitcnt lgkmcnt(1)
	v_mfma_f32_32x32x16_bf16 v[50:65], v[154:157], v[120:123], v[50:65]
	ds_read_b128 v[150:153], v166 offset:46720
	v_exp_f32_e32 v88, v90
	v_exp_f32_e32 v89, v91
	s_nop 0
	v_pk_add_f32 v[90:91], v[88:89], v[86:87]
	v_cvt_pk_bf16_f32 v86, v88, v89
	s_waitcnt lgkmcnt(1)
	v_mfma_f32_32x32x16_bf16 v[50:65], v[144:147], v[116:119], v[50:65]
	ds_read_b128 v[154:157], v166 offset:46752
	v_exp_f32_e32 v88, v92
	v_exp_f32_e32 v89, v93
	s_nop 0
	v_pk_add_f32 v[90:91], v[88:89], v[90:91]
	v_cvt_pk_bf16_f32 v87, v88, v89
	s_waitcnt lgkmcnt(1)
	v_mfma_f32_32x32x16_bf16 v[50:65], v[150:153], v[112:115], v[50:65]
	v_add_u32_e32 v107, 0x4000, v167
	ds_read2_b64 v[144:147], v107 offset0:128 offset1:130
	v_exp_f32_e32 v88, v94
	v_exp_f32_e32 v89, v95
	s_nop 0
	v_pk_add_f32 v[90:91], v[88:89], v[90:91]
	v_cvt_pk_bf16_f32 v88, v88, v89
	s_waitcnt lgkmcnt(1)
	v_mfma_f32_32x32x16_bf16 v[50:65], v[154:157], v[108:111], v[50:65]
	v_add_u32_e32 v158, 0x5000, v167
	v_exp_f32_e32 v96, v96
	v_exp_f32_e32 v97, v97
	ds_read2_b64 v[92:95], v158 offset0:160 offset1:162
	v_pk_add_f32 v[90:91], v[96:97], v[90:91]
	v_cvt_pk_bf16_f32 v89, v96, v97
	s_waitcnt lgkmcnt(1)
	v_mfma_f32_32x32x16_bf16 v[18:33], v[144:147], v[98:101], v[18:33]
	ds_read2_b64 v[150:153], v107 offset0:132 offset1:134
	v_max3_f32 v96, v231, v66, v67
	s_nop 0
	v_max3_f32 v96, v96, v68, v69
	s_waitcnt lgkmcnt(1)
	v_mfma_f32_32x32x16_bf16 v[2:17], v[92:95], v[98:101], v[2:17]
	ds_read2_b64 v[144:147], v158 offset0:164 offset1:166
	v_max3_f32 v92, v96, v70, v71
	s_nop 0
	v_max3_f32 v96, v92, v72, v73
	s_waitcnt lgkmcnt(1)
	v_mfma_f32_32x32x16_bf16 v[18:33], v[150:153], v[102:105], v[18:33]
	ds_read2_b64 v[92:95], v107 offset0:136 offset1:138
	v_max3_f32 v96, v96, v74, v75
	s_nop 0
	v_max3_f32 v100, v96, v76, v77
	s_waitcnt lgkmcnt(1)
	v_mfma_f32_32x32x16_bf16 v[2:17], v[144:147], v[102:105], v[2:17]
	ds_read2_b64 v[96:99], v158 offset0:168 offset1:170
	v_max3_f32 v100, v100, v78, v79
	s_nop 0
	v_max3_f32 v104, v100, v80, v81
	s_waitcnt lgkmcnt(1)
	v_mfma_f32_32x32x16_bf16 v[18:33], v[92:95], v[82:85], v[18:33]
	ds_read2_b64 v[100:103], v107 offset0:140 offset1:142
	v_max3_f32 v104, v104, v50, v51
	s_nop 0
	v_max3_f32 v104, v104, v52, v53
	s_waitcnt lgkmcnt(1)
	v_mfma_f32_32x32x16_bf16 v[2:17], v[96:99], v[82:85], v[2:17]
	ds_read2_b64 v[92:95], v158 offset0:172 offset1:174
	v_max3_f32 v104, v104, v54, v55
	s_nop 0
	v_max3_f32 v104, v104, v56, v57
	s_waitcnt lgkmcnt(1)
	v_mfma_f32_32x32x16_bf16 v[18:33], v[100:103], v[86:89], v[18:33]
	v_max3_f32 v82, v104, v58, v59
	s_nop 0
	v_max3_f32 v82, v82, v60, v61
	s_waitcnt lgkmcnt(0)
	v_mfma_f32_32x32x16_bf16 v[2:17], v[92:95], v[86:89], v[2:17]
	v_max3_f32 v82, v82, v62, v63
	s_nop 0
	v_max3_f32 v208, v82, v64, v65
	v_add_f32_e32 v82, v90, v91
	v_add_f32_e32 v98, v106, v82
	v_add_f32_e64 v82, v148, v208
	v_add_f32_e64 v83, v149, v209
	v_cmp_gt_f32_e32 vcc, v82, v83
	s_cbranch_vccz .LBB0_829
	v_mbcnt_hi_u32_b32 v34, -1, v232
	v_and_b32_e32 v36, 64, v34
	v_xor_b32_e32 v35, 32, v34
	v_add_u32_e32 v36, 64, v36
	v_cmp_lt_i32_e32 vcc, v35, v36
	v_max_f32_e32 v36, v163, v163
	s_nop 0
	v_cndmask_b32_e32 v34, v34, v35, vcc
	v_lshlrev_b32_e32 v34, 2, v34
	ds_bpermute_b32 v34, v34, v208
	v_max_f32_e32 v35, v208, v208
	s_waitcnt lgkmcnt(0)
	v_max_f32_e32 v34, v34, v34
	v_max_f32_e32 v34, v35, v34
	v_add_f32_e32 v34, v162, v34
	v_max_f32_e32 v148, v36, v34
	v_sub_f32_e32 v34, v163, v148
	v_exp_f32_e32 v36, v34
	v_sub_f32_e32 v34, v162, v148
	v_pk_add_f32 v[80:81], v[80:81], v[34:35] op_sel_hi:[1,0]
	v_pk_add_f32 v[78:79], v[78:79], v[34:35] op_sel_hi:[1,0]
	v_pk_add_f32 v[76:77], v[76:77], v[34:35] op_sel_hi:[1,0]
	v_pk_add_f32 v[74:75], v[74:75], v[34:35] op_sel_hi:[1,0]
	v_pk_add_f32 v[72:73], v[72:73], v[34:35] op_sel_hi:[1,0]
	v_pk_add_f32 v[70:71], v[70:71], v[34:35] op_sel_hi:[1,0]
	v_pk_add_f32 v[68:69], v[68:69], v[34:35] op_sel_hi:[1,0]
	v_pk_add_f32 v[66:67], v[66:67], v[34:35] op_sel_hi:[1,0]
	v_pk_add_f32 v[64:65], v[64:65], v[34:35] op_sel_hi:[1,0]
	v_pk_add_f32 v[62:63], v[62:63], v[34:35] op_sel_hi:[1,0]
	v_pk_add_f32 v[60:61], v[60:61], v[34:35] op_sel_hi:[1,0]
	v_pk_add_f32 v[58:59], v[58:59], v[34:35] op_sel_hi:[1,0]
	v_pk_add_f32 v[56:57], v[56:57], v[34:35] op_sel_hi:[1,0]
	v_pk_add_f32 v[54:55], v[54:55], v[34:35] op_sel_hi:[1,0]
	v_pk_add_f32 v[52:53], v[52:53], v[34:35] op_sel_hi:[1,0]
	v_pk_add_f32 v[50:51], v[50:51], v[34:35] op_sel_hi:[1,0]
	v_xor_b32_e32 v34, 0x80000000, v148
	v_pk_mul_f32 v[16:17], v[16:17], v[36:37] op_sel_hi:[1,0]
	v_pk_mul_f32 v[14:15], v[14:15], v[36:37] op_sel_hi:[1,0]
	v_pk_mul_f32 v[12:13], v[12:13], v[36:37] op_sel_hi:[1,0]
	v_pk_mul_f32 v[10:11], v[10:11], v[36:37] op_sel_hi:[1,0]
	v_pk_mul_f32 v[8:9], v[8:9], v[36:37] op_sel_hi:[1,0]
	v_pk_mul_f32 v[6:7], v[6:7], v[36:37] op_sel_hi:[1,0]
	v_pk_mul_f32 v[4:5], v[4:5], v[36:37] op_sel_hi:[1,0]
	v_pk_mul_f32 v[2:3], v[2:3], v[36:37] op_sel_hi:[1,0]
	v_pk_mul_f32 v[32:33], v[32:33], v[36:37] op_sel_hi:[1,0]
	v_pk_mul_f32 v[30:31], v[30:31], v[36:37] op_sel_hi:[1,0]
	v_pk_mul_f32 v[28:29], v[28:29], v[36:37] op_sel_hi:[1,0]
	v_pk_mul_f32 v[26:27], v[26:27], v[36:37] op_sel_hi:[1,0]
	v_pk_mul_f32 v[24:25], v[24:25], v[36:37] op_sel_hi:[1,0]
	v_pk_mul_f32 v[22:23], v[22:23], v[36:37] op_sel_hi:[1,0]
	v_pk_mul_f32 v[20:21], v[20:21], v[36:37] op_sel_hi:[1,0]
	v_pk_mul_f32 v[18:19], v[18:19], v[36:37] op_sel_hi:[1,0]
	v_mul_f32_e32 v98, v98, v36
	v_mov_b32_e32 v149, v148
	v_mov_b32_e32 v35, v34
	v_mov_b32_e32 v36, v34
	v_mov_b32_e32 v37, v34
	v_mov_b32_e32 v38, v34
	v_mov_b32_e32 v39, v34
	v_mov_b32_e32 v40, v34
	v_mov_b32_e32 v41, v34
	v_mov_b32_e32 v42, v34
	v_mov_b32_e32 v43, v34
	v_mov_b32_e32 v44, v34
	v_mov_b32_e32 v45, v34
	v_mov_b32_e32 v46, v34
	v_mov_b32_e32 v47, v34
	v_mov_b32_e32 v48, v34
	v_mov_b32_e32 v49, v34
	v_mov_b32_e32 v162, v148
	v_mov_b32_e32 v163, v148
.LBB0_829:
	ds_write_b128 v165, v[136:139] offset:26624
	s_and_saveexec_b64 s[2:3], s[0:1]
	ds_write_b128 v1, v[132:135] offset:26624
	s_or_b64 exec, exec, s[2:3]
	ds_write_b16 v161, v140 offset:61952
	ds_write_b16 v161, v168 offset:62088
	ds_write_b16 v161, v141 offset:62224
	ds_write_b16 v161, v169 offset:62360
	ds_write_b16 v161, v142 offset:62496
	ds_write_b16 v161, v170 offset:62632
	ds_write_b16 v161, v143 offset:62768
	ds_write_b16 v161, v171 offset:62904
	ds_read_b128 v[100:103], v166
	ds_read_b128 v[104:107], v166 offset:32
	s_waitcnt lgkmcnt(1)
	v_mfma_f32_32x32x16_bf16 v[82:97], v[100:103], v[128:131], v[34:49]
	v_exp_f32_e32 v100, v66
	v_exp_f32_e32 v101, v67
	ds_read_b128 v[132:135], v166 offset:64
	v_exp_f32_e32 v68, v68
	v_exp_f32_e32 v69, v69
	v_cvt_pk_bf16_f32 v66, v100, v101
	v_pk_add_f32 v[100:101], v[100:101], 0 op_sel_hi:[1,0]
	v_cvt_pk_bf16_f32 v67, v68, v69
	v_pk_add_f32 v[136:137], v[68:69], v[100:101]
	v_exp_f32_e32 v70, v70
	v_exp_f32_e32 v71, v71
	ds_read_b128 v[100:103], v166 offset:96
	v_exp_f32_e32 v72, v72
	v_exp_f32_e32 v73, v73
	v_cvt_pk_bf16_f32 v68, v70, v71
	v_pk_add_f32 v[70:71], v[70:71], v[136:137]
	s_waitcnt lgkmcnt(2)
	v_mfma_f32_32x32x16_bf16 v[82:97], v[104:107], v[124:127], v[82:97]
	v_add_f32_e64 v136, v72, v70
	v_add_f32_e64 v137, v73, v71
	v_cvt_pk_bf16_f32 v69, v72, v73
	v_exp_f32_e32 v72, v74
	v_exp_f32_e32 v73, v75
	ds_read_b128 v[104:107], v166 offset:128
	v_exp_f32_e32 v74, v76
	v_exp_f32_e32 v75, v77
	v_cvt_pk_bf16_f32 v70, v72, v73
	v_pk_add_f32 v[72:73], v[72:73], v[136:137]
	s_waitcnt lgkmcnt(2)
	v_mfma_f32_32x32x16_bf16 v[82:97], v[132:135], v[120:123], v[82:97]
	v_add_f32_e64 v132, v74, v72
	v_add_f32_e64 v133, v75, v73
	v_cvt_pk_bf16_f32 v71, v74, v75
	v_exp_f32_e32 v78, v78
	v_exp_f32_e32 v79, v79
	ds_read_b128 v[74:77], v166 offset:160
	v_exp_f32_e32 v80, v80
	v_exp_f32_e32 v81, v81
	v_cvt_pk_bf16_f32 v72, v78, v79
	v_pk_add_f32 v[78:79], v[78:79], v[132:133]
	s_waitcnt lgkmcnt(2)
	v_mfma_f32_32x32x16_bf16 v[82:97], v[100:103], v[116:119], v[82:97]
	v_add_f32_e64 v100, v80, v78
	v_add_f32_e64 v101, v81, v79
	v_cvt_pk_bf16_f32 v73, v80, v81
	ds_read_b128 v[78:81], v166 offset:6656
	v_exp_f32_e32 v50, v50
	v_exp_f32_e32 v51, v51
	s_waitcnt lgkmcnt(2)
	v_mfma_f32_32x32x16_bf16 v[82:97], v[104:107], v[112:115], v[82:97]
	v_add_f32_e64 v104, v50, v100
	v_add_f32_e64 v105, v51, v101
	v_cvt_pk_bf16_f32 v50, v50, v51
	ds_read_b128 v[100:103], v166 offset:6688
	v_exp_f32_e32 v52, v52
	v_exp_f32_e32 v53, v53
	s_waitcnt lgkmcnt(2)
	v_mfma_f32_32x32x16_bf16 v[82:97], v[74:77], v[108:111], v[82:97]
	v_add_f32_e64 v104, v52, v104
	v_add_f32_e64 v105, v53, v105
	v_cvt_pk_bf16_f32 v51, v52, v53
	ds_read_b128 v[74:77], v166 offset:6720
	v_exp_f32_e32 v52, v54
	v_exp_f32_e32 v53, v55
	s_waitcnt lgkmcnt(2)
	v_mfma_f32_32x32x16_bf16 v[34:49], v[78:81], v[128:131], v[34:49]
	v_add_f32_e64 v54, v52, v104
	v_add_f32_e64 v55, v53, v105
	v_cvt_pk_bf16_f32 v52, v52, v53
	ds_read_b128 v[78:81], v166 offset:6752
	v_exp_f32_e32 v56, v56
	v_exp_f32_e32 v57, v57
	s_waitcnt lgkmcnt(2)
	v_mfma_f32_32x32x16_bf16 v[34:49], v[100:103], v[124:127], v[34:49]
	v_add_f32_e64 v54, v56, v54
	v_add_f32_e64 v55, v57, v55
	v_cvt_pk_bf16_f32 v53, v56, v57
	ds_read_b128 v[100:103], v166 offset:6784
	v_exp_f32_e32 v56, v58
	v_exp_f32_e32 v57, v59
	s_waitcnt lgkmcnt(2)
	v_mfma_f32_32x32x16_bf16 v[34:49], v[74:77], v[120:123], v[34:49]
	v_add_f32_e64 v58, v56, v54
	v_add_f32_e64 v59, v57, v55
	v_cvt_pk_bf16_f32 v54, v56, v57
	ds_read_b128 v[74:77], v166 offset:6816
	v_exp_f32_e32 v56, v60
	v_exp_f32_e32 v57, v61
	s_waitcnt lgkmcnt(2)
	v_mfma_f32_32x32x16_bf16 v[34:49], v[78:81], v[116:119], v[34:49]
	v_add_f32_e64 v78, v56, v58
	v_add_f32_e64 v79, v57, v59
	v_cvt_pk_bf16_f32 v55, v56, v57
	v_add_u32_e32 v1, 0x6000, v167
	ds_read2_b64 v[58:61], v1 offset0:192 offset1:194
	v_exp_f32_e32 v56, v62
	v_exp_f32_e32 v57, v63
	s_waitcnt lgkmcnt(2)
	v_mfma_f32_32x32x16_bf16 v[34:49], v[100:103], v[112:115], v[34:49]
	v_add_f32_e64 v78, v56, v78
	v_add_f32_e64 v79, v57, v79
	v_cvt_pk_bf16_f32 v56, v56, v57
	v_add_u32_e32 v99, 0x7000, v167
	v_exp_f32_e32 v80, v64
	v_exp_f32_e32 v81, v65
	ds_read2_b64 v[62:65], v99 offset0:224 offset1:226
	s_waitcnt lgkmcnt(2)
	v_mfma_f32_32x32x16_bf16 v[34:49], v[74:77], v[108:111], v[34:49]
	v_add_f32_e64 v78, v80, v78
	v_add_f32_e64 v79, v81, v79
	v_cvt_pk_bf16_f32 v57, v80, v81
	s_waitcnt lgkmcnt(1)
	v_mfma_f32_32x32x16_bf16 v[18:33], v[58:61], v[66:69], v[18:33]
	ds_read2_b64 v[74:77], v1 offset0:196 offset1:198
	v_max3_f32 v58, v231, v82, v83
	s_nop 0
	v_max3_f32 v80, v58, v84, v85
	s_waitcnt lgkmcnt(1)
	v_mfma_f32_32x32x16_bf16 v[2:17], v[62:65], v[66:69], v[2:17]
	ds_read2_b64 v[58:61], v99 offset0:228 offset1:230
	v_max3_f32 v62, v80, v86, v87
	s_nop 0
	v_max3_f32 v66, v62, v88, v89
	s_waitcnt lgkmcnt(1)
	v_mfma_f32_32x32x16_bf16 v[18:33], v[74:77], v[70:73], v[18:33]
	ds_read2_b64 v[62:65], v1 offset0:200 offset1:202
	v_max3_f32 v66, v66, v90, v91
	s_nop 0
	v_max3_f32 v74, v66, v92, v93
	s_waitcnt lgkmcnt(1)
	v_mfma_f32_32x32x16_bf16 v[2:17], v[58:61], v[70:73], v[2:17]
	ds_read2_b64 v[66:69], v99 offset0:232 offset1:234
	v_max3_f32 v58, v74, v94, v95
	s_nop 0
	v_max3_f32 v70, v58, v96, v97
	s_waitcnt lgkmcnt(1)
	v_mfma_f32_32x32x16_bf16 v[18:33], v[62:65], v[50:53], v[18:33]
	ds_read2_b64 v[58:61], v1 offset0:204 offset1:206
	v_max3_f32 v1, v70, v34, v35
	s_nop 0
	v_max3_f32 v1, v1, v36, v37
	s_waitcnt lgkmcnt(1)
	v_mfma_f32_32x32x16_bf16 v[2:17], v[66:69], v[50:53], v[2:17]
	ds_read2_b64 v[34:37], v99 offset0:236 offset1:238
	v_max3_f32 v1, v1, v38, v39
	s_nop 0
	v_max3_f32 v1, v1, v40, v41
	s_waitcnt lgkmcnt(1)
	v_mfma_f32_32x32x16_bf16 v[18:33], v[58:61], v[54:57], v[18:33]
	v_max3_f32 v1, v1, v42, v43
	s_nop 0
	v_max3_f32 v1, v1, v44, v45
	s_waitcnt lgkmcnt(0)
	v_mfma_f32_32x32x16_bf16 v[2:17], v[34:37], v[54:57], v[2:17]
	v_max3_f32 v1, v1, v46, v47
	s_nop 0
	v_max3_f32 v208, v1, v48, v49
	v_add_f32_e32 v1, v78, v79
	v_add_f32_e64 v34, v148, v208
	v_add_f32_e64 v35, v149, v209
	v_add_f32_e32 v1, v98, v1
	v_cmp_gt_f32_e32 vcc, v34, v35
	s_cbranch_vccz .LBB0_929
	v_mbcnt_hi_u32_b32 v34, -1, v232
	v_and_b32_e32 v36, 64, v34
	v_xor_b32_e32 v35, 32, v34
	v_add_u32_e32 v36, 64, v36
	v_cmp_lt_i32_e32 vcc, v35, v36
	v_max_f32_e32 v38, v208, v208
	s_nop 0
	v_cndmask_b32_e32 v37, v34, v35, vcc
	v_lshlrev_b32_e32 v37, 2, v37
	ds_bpermute_b32 v37, v37, v208
	s_waitcnt lgkmcnt(0)
	v_max_f32_e32 v37, v37, v37
	v_max_f32_e32 v37, v38, v37
	v_add_f32_e32 v37, v162, v37
	v_max_f32_e32 v38, v163, v163
	v_max_f32_e32 v37, v38, v37
	v_sub_f32_e32 v37, v163, v37
	v_exp_f32_e32 v38, v37
	s_nop 0
	v_pk_mul_f32 v[16:17], v[16:17], v[38:39] op_sel_hi:[1,0]
	v_pk_mul_f32 v[14:15], v[14:15], v[38:39] op_sel_hi:[1,0]
	v_pk_mul_f32 v[12:13], v[12:13], v[38:39] op_sel_hi:[1,0]
	v_pk_mul_f32 v[10:11], v[10:11], v[38:39] op_sel_hi:[1,0]
	v_pk_mul_f32 v[8:9], v[8:9], v[38:39] op_sel_hi:[1,0]
	v_pk_mul_f32 v[6:7], v[6:7], v[38:39] op_sel_hi:[1,0]
	v_pk_mul_f32 v[4:5], v[4:5], v[38:39] op_sel_hi:[1,0]
	v_pk_mul_f32 v[2:3], v[2:3], v[38:39] op_sel_hi:[1,0]
	v_pk_mul_f32 v[32:33], v[32:33], v[38:39] op_sel_hi:[1,0]
	v_pk_mul_f32 v[30:31], v[30:31], v[38:39] op_sel_hi:[1,0]
	v_pk_mul_f32 v[28:29], v[28:29], v[38:39] op_sel_hi:[1,0]
	v_pk_mul_f32 v[26:27], v[26:27], v[38:39] op_sel_hi:[1,0]
	v_pk_mul_f32 v[24:25], v[24:25], v[38:39] op_sel_hi:[1,0]
	v_pk_mul_f32 v[22:23], v[22:23], v[38:39] op_sel_hi:[1,0]
	v_pk_mul_f32 v[20:21], v[20:21], v[38:39] op_sel_hi:[1,0]
	v_pk_mul_f32 v[18:19], v[18:19], v[38:39] op_sel_hi:[1,0]
	v_mul_f32_e32 v37, v1, v38
	s_cbranch_execnz .LBB0_834

.LBB0_842:
	s_mul_i32 s0, s5, 0x2200
	v_add_u32_e32 v82, s0, v191
	s_add_i32 s0, s15, -3
	s_min_i32 s0, s0, s14
	s_cmp_gt_i32 s0, 3
	s_cselect_b32 s1, s7, 0
	s_add_i32 s1, s1, s0
	s_lshl_b32 s0, s1, 6
	s_ashr_i32 s1, s0, 31
	s_lshl_b64 s[0:1], s[0:1], 7
	s_waitcnt vmcnt(1)
	ds_write_b128 v185, v[134:137] offset:27648
	s_waitcnt vmcnt(0)
	ds_write_b16 v82, v130 offset:36864
	ds_write_b16_d16_hi v82, v130 offset:37000
	ds_write_b16 v82, v131 offset:37136
	ds_write_b16_d16_hi v82, v131 offset:37272
	ds_write_b16 v82, v132 offset:37408
	ds_write_b16_d16_hi v82, v132 offset:37544
	ds_write_b16 v82, v133 offset:37680
	ds_write_b16_d16_hi v82, v133 offset:37816
	v_lshl_add_u64 v[82:83], v[192:193], 0, s[0:1]
	v_lshl_add_u64 v[84:85], v[194:195], 0, s[0:1]
	global_load_dwordx4 v[134:137], v[82:83], off
	global_load_dwordx4 v[130:133], v[84:85], off
	ds_read_b128 v[98:101], v245 offset:9216
	ds_read_b128 v[102:105], v245 offset:9248
	s_mul_i32 s0, s18, 0x2200
	v_add_u32_e32 v178, s0, v1
	s_waitcnt lgkmcnt(1)
	v_mfma_f32_32x32x16_bf16 v[82:97], v[98:101], v[114:117], v[50:65]
	ds_read_b128 v[106:109], v245 offset:9280
	v_exp_f32_e32 v196, v34
	v_exp_f32_e32 v197, v35
	v_exp_f32_e32 v198, v36
	v_exp_f32_e32 v199, v37
	v_cvt_pk_bf16_f32 v166, v196, v197
	v_cvt_pk_bf16_f32 v167, v198, v199
	s_waitcnt lgkmcnt(1)
	v_mfma_f32_32x32x16_bf16 v[82:97], v[102:105], v[118:121], v[82:97]
	ds_read_b128 v[98:101], v245 offset:9312
	v_exp_f32_e32 v200, v38
	v_exp_f32_e32 v201, v39
	v_exp_f32_e32 v202, v40
	v_exp_f32_e32 v203, v41
	v_cvt_pk_bf16_f32 v168, v200, v201
	v_cvt_pk_bf16_f32 v169, v202, v203
	s_waitcnt lgkmcnt(1)
	v_mfma_f32_32x32x16_bf16 v[82:97], v[106:109], v[122:125], v[82:97]
	ds_read_b128 v[162:165], v245 offset:13824
	s_waitcnt lgkmcnt(1)
	v_mfma_f32_32x32x16_bf16 v[82:97], v[98:101], v[126:129], v[82:97]
	ds_read_b128 v[170:173], v245 offset:13856
	s_waitcnt lgkmcnt(1)
	v_mfma_f32_32x32x16_bf16 v[98:113], v[162:165], v[114:117], v[50:65]
	ds_read_b128 v[174:177], v245 offset:13888
	s_waitcnt lgkmcnt(1)
	v_mfma_f32_32x32x16_bf16 v[98:113], v[170:173], v[118:121], v[98:113]
	ds_read_b128 v[162:165], v245 offset:13920
	s_waitcnt lgkmcnt(1)
	v_mfma_f32_32x32x16_bf16 v[98:113], v[174:177], v[122:125], v[98:113]
	v_add_u32_e32 v224, 0x9000, v178
	ds_read2_b64 v[170:173], v224 offset1:2
	s_waitcnt lgkmcnt(1)
	v_mfma_f32_32x32x16_bf16 v[98:113], v[162:165], v[126:129], v[98:113]
	v_add_u32_e32 v208, 0xa000, v178
	ds_read2_b64 v[174:177], v208 offset0:32 offset1:34
	s_waitcnt lgkmcnt(1)
	v_mfma_f32_32x32x16_bf16 v[2:17], v[170:173], v[166:169], v[2:17]
	ds_read2_b64 v[162:165], v224 offset0:4 offset1:6
	s_cmp_lg_u32 s16, 0
	s_cselect_b64 s[2:3], -1, 0
	s_cmp_eq_u32 s16, 0
	v_add_u32_e32 v240, s16, v234
	s_cbranch_scc1 .LBB0_844
	v_add_u32_e32 v170, 63, v240
	v_cmp_lt_u32_e32 vcc, s95, v170
	v_add_u32_e32 v170, 62, v240
	s_nop 0
	v_cndmask_b32_e32 v82, v243, v82, vcc
	v_cmp_lt_u32_e32 vcc, s95, v170
	v_add_u32_e32 v170, 61, v240
	s_nop 0
	v_cndmask_b32_e32 v83, v243, v83, vcc
	v_cmp_lt_u32_e32 vcc, s95, v170
	v_add_u32_e32 v170, 60, v240
	s_nop 0
	v_cndmask_b32_e32 v84, v243, v84, vcc
	v_cmp_lt_u32_e32 vcc, s95, v170
	s_nop 1
	v_cndmask_b32_e32 v85, v243, v85, vcc

.LBB0_858:
	v_pk_add_f32 v[164:165], v[196:197], 0 op_sel_hi:[1,0]
	v_max3_f32 v162, v162, v110, v111
	s_nop 0
	v_pk_add_f32 v[164:165], v[198:199], v[164:165]
	v_max3_f32 v208, v162, v112, v113
	s_nop 0
	v_pk_add_f32 v[164:165], v[200:201], v[164:165]
	s_nop 0
	v_pk_add_f32 v[164:165], v[202:203], v[164:165]
	s_nop 0
	v_pk_add_f32 v[164:165], v[204:205], v[164:165]
	s_nop 0
	v_pk_add_f32 v[164:165], v[214:215], v[164:165]
	s_nop 0
	v_pk_add_f32 v[164:165], v[216:217], v[164:165]
	s_nop 0
	v_pk_add_f32 v[164:165], v[218:219], v[164:165]
	s_nop 0
	v_pk_add_f32 v[164:165], v[178:179], v[164:165]
	s_nop 0
	v_pk_add_f32 v[164:165], v[180:181], v[164:165]
	s_nop 0
	v_pk_add_f32 v[164:165], v[220:221], v[164:165]
	s_nop 0
	v_pk_add_f32 v[164:165], v[222:223], v[164:165]
	s_nop 0
	v_pk_add_f32 v[164:165], v[176:177], v[164:165]
	s_nop 0
	v_pk_add_f32 v[164:165], v[226:227], v[164:165]
	s_nop 0
	v_pk_add_f32 v[162:163], v[174:175], v[164:165]
	s_nop 0
	v_pk_add_f32 v[162:163], v[224:225], v[162:163]
	v_add_f32_e32 v162, v162, v163
	v_add_f32_e32 v251, v251, v162
	v_pk_add_f32 v[162:163], v[188:189], v[208:209]
	s_nop 0
	v_cmp_gt_f32_e32 vcc, v162, v163
	s_cbranch_vccz .LBB0_860
	v_cmp_lt_i32_e32 vcc, v241, v235
	v_max_f32_e32 v51, v208, v208
	v_max_f32_e32 v52, v189, v189
	v_cndmask_b32_e32 v50, v233, v241, vcc
	v_lshlrev_b32_e32 v50, 2, v50
	ds_bpermute_b32 v50, v50, v208
	s_waitcnt lgkmcnt(0)
	v_max_f32_e32 v50, v50, v50
	v_max_f32_e32 v50, v51, v50
	v_add_f32_e32 v50, v188, v50
	v_max_f32_e32 v162, v52, v50
	v_sub_f32_e32 v50, v189, v162
	v_exp_f32_e32 v164, v50
	v_sub_f32_e32 v50, v188, v162
	v_pk_add_f32 v[96:97], v[96:97], v[50:51] op_sel_hi:[1,0]
	v_pk_add_f32 v[94:95], v[94:95], v[50:51] op_sel_hi:[1,0]
	v_pk_add_f32 v[92:93], v[92:93], v[50:51] op_sel_hi:[1,0]
	v_pk_add_f32 v[90:91], v[90:91], v[50:51] op_sel_hi:[1,0]
	v_pk_add_f32 v[88:89], v[88:89], v[50:51] op_sel_hi:[1,0]
	v_pk_add_f32 v[86:87], v[86:87], v[50:51] op_sel_hi:[1,0]
	v_pk_add_f32 v[84:85], v[84:85], v[50:51] op_sel_hi:[1,0]
	v_pk_add_f32 v[82:83], v[82:83], v[50:51] op_sel_hi:[1,0]
	v_pk_add_f32 v[112:113], v[112:113], v[50:51] op_sel_hi:[1,0]
	v_pk_add_f32 v[110:111], v[110:111], v[50:51] op_sel_hi:[1,0]
	v_pk_add_f32 v[108:109], v[108:109], v[50:51] op_sel_hi:[1,0]
	v_pk_add_f32 v[106:107], v[106:107], v[50:51] op_sel_hi:[1,0]
	v_pk_add_f32 v[104:105], v[104:105], v[50:51] op_sel_hi:[1,0]
	v_pk_add_f32 v[102:103], v[102:103], v[50:51] op_sel_hi:[1,0]
	v_pk_add_f32 v[100:101], v[100:101], v[50:51] op_sel_hi:[1,0]
	v_pk_add_f32 v[98:99], v[98:99], v[50:51] op_sel_hi:[1,0]
	v_xor_b32_e32 v50, 0x80000000, v162
	v_mov_b32_e32 v163, v162
	v_pk_mul_f32 v[16:17], v[16:17], v[164:165] op_sel_hi:[1,0]
	v_pk_mul_f32 v[14:15], v[14:15], v[164:165] op_sel_hi:[1,0]
	v_pk_mul_f32 v[12:13], v[12:13], v[164:165] op_sel_hi:[1,0]
	v_pk_mul_f32 v[10:11], v[10:11], v[164:165] op_sel_hi:[1,0]
	v_pk_mul_f32 v[8:9], v[8:9], v[164:165] op_sel_hi:[1,0]
	v_pk_mul_f32 v[6:7], v[6:7], v[164:165] op_sel_hi:[1,0]
	v_pk_mul_f32 v[4:5], v[4:5], v[164:165] op_sel_hi:[1,0]
	v_pk_mul_f32 v[2:3], v[2:3], v[164:165] op_sel_hi:[1,0]
	v_pk_mul_f32 v[32:33], v[32:33], v[164:165] op_sel_hi:[1,0]
	v_pk_mul_f32 v[30:31], v[30:31], v[164:165] op_sel_hi:[1,0]
	v_pk_mul_f32 v[28:29], v[28:29], v[164:165] op_sel_hi:[1,0]
	v_pk_mul_f32 v[26:27], v[26:27], v[164:165] op_sel_hi:[1,0]
	v_pk_mul_f32 v[24:25], v[24:25], v[164:165] op_sel_hi:[1,0]
	v_pk_mul_f32 v[22:23], v[22:23], v[164:165] op_sel_hi:[1,0]
	v_pk_mul_f32 v[20:21], v[20:21], v[164:165] op_sel_hi:[1,0]
	v_pk_mul_f32 v[18:19], v[18:19], v[164:165] op_sel_hi:[1,0]
	v_mov_b32_e32 v51, v50
	v_mov_b32_e32 v52, v50
	v_mov_b32_e32 v53, v50
	v_mov_b32_e32 v54, v50
	v_mov_b32_e32 v55, v50
	v_mov_b32_e32 v56, v50
	v_mov_b32_e32 v57, v50
	v_mov_b32_e32 v58, v50
	v_mov_b32_e32 v59, v50
	v_mov_b32_e32 v60, v50
	v_mov_b32_e32 v61, v50
	v_mov_b32_e32 v62, v50
	v_mov_b32_e32 v63, v50
	v_mov_b32_e32 v64, v50
	v_mov_b32_e32 v65, v50
	v_mul_f32_e32 v251, v251, v164
	v_mov_b64_e32 v[188:189], v[162:163]
.LBB0_860:
	s_or_b32 s2, s17, 1
	s_add_i32 s3, s18, 1
	s_cmp_lg_u32 s18, 4
	s_cselect_b32 s18, s3, 0
	s_add_i32 s3, s5, 1
	s_cmp_lg_u32 s5, 4
	s_cselect_b32 s5, s3, 0
	s_cmp_ge_i32 s2, s4
	s_cbranch_scc1 .LBB0_881
	s_mul_i32 s2, s5, 0x2200
	v_add_u32_e32 v34, s2, v191
	s_add_i32 s2, s15, -2
	s_min_i32 s2, s2, s14
	s_cmp_gt_i32 s2, 3
	s_cselect_b32 s3, s7, 0
	s_add_i32 s3, s3, s2
	s_lshl_b32 s2, s3, 6
	s_ashr_i32 s3, s2, 31
	s_lshl_b64 s[2:3], s[2:3], 7
	s_waitcnt vmcnt(7)
	ds_write_b128 v185, v[138:141]
	s_waitcnt vmcnt(6)
	ds_write_b16 v34, v142 offset:36864
	ds_write_b16_d16_hi v34, v142 offset:37000
	ds_write_b16 v34, v143 offset:37136
	ds_write_b16_d16_hi v34, v143 offset:37272
	ds_write_b16 v34, v144 offset:37408
	ds_write_b16_d16_hi v34, v144 offset:37544
	ds_write_b16 v34, v145 offset:37680
	ds_write_b16_d16_hi v34, v145 offset:37816
	v_lshl_add_u64 v[34:35], v[192:193], 0, s[2:3]
	v_lshl_add_u64 v[36:37], v[194:195], 0, s[2:3]
	global_load_dwordx4 v[138:141], v[34:35], off
	global_load_dwordx4 v[142:145], v[36:37], off
	ds_read_b128 v[66:69], v245 offset:18432
	ds_read_b128 v[70:73], v245 offset:18464
	s_mul_i32 s2, s18, 0x2200
	v_add_u32_e32 v204, s2, v1
	s_waitcnt lgkmcnt(1)
	v_mfma_f32_32x32x16_bf16 v[34:49], v[66:69], v[114:117], v[50:65]
	ds_read_b128 v[74:77], v245 offset:18496
	v_exp_f32_e32 v196, v82
	v_exp_f32_e32 v197, v83
	v_exp_f32_e32 v198, v84
	v_exp_f32_e32 v199, v85
	v_cvt_pk_bf16_f32 v162, v196, v197
	v_cvt_pk_bf16_f32 v163, v198, v199
	s_waitcnt lgkmcnt(1)
	v_mfma_f32_32x32x16_bf16 v[34:49], v[70:73], v[118:121], v[34:49]
	ds_read_b128 v[66:69], v245 offset:18528
	v_exp_f32_e32 v200, v86
	v_exp_f32_e32 v201, v87
	v_exp_f32_e32 v202, v88
	v_exp_f32_e32 v203, v89
	v_cvt_pk_bf16_f32 v164, v200, v201
	v_cvt_pk_bf16_f32 v165, v202, v203
	s_waitcnt lgkmcnt(1)
	v_mfma_f32_32x32x16_bf16 v[34:49], v[74:77], v[122:125], v[34:49]
	ds_read_b128 v[166:169], v245 offset:23040
	s_waitcnt lgkmcnt(1)
	v_mfma_f32_32x32x16_bf16 v[34:49], v[66:69], v[126:129], v[34:49]
	ds_read_b128 v[170:173], v245 offset:23072
	s_waitcnt lgkmcnt(1)
	v_mfma_f32_32x32x16_bf16 v[66:81], v[166:169], v[114:117], v[50:65]
	ds_read_b128 v[174:177], v245 offset:23104
	s_waitcnt lgkmcnt(1)
	v_mfma_f32_32x32x16_bf16 v[66:81], v[170:173], v[118:121], v[66:81]
	ds_read_b128 v[166:169], v245 offset:23136
	s_waitcnt lgkmcnt(1)
	v_mfma_f32_32x32x16_bf16 v[66:81], v[174:177], v[122:125], v[66:81]
	v_add_u32_e32 v224, 0x9000, v204
	ds_read2_b64 v[178:181], v224 offset1:2
	s_waitcnt lgkmcnt(1)
	v_mfma_f32_32x32x16_bf16 v[66:81], v[166:169], v[126:129], v[66:81]
	v_add_u32_e32 v208, 0xa000, v204
	ds_read2_b64 v[170:173], v208 offset0:32 offset1:34
	s_waitcnt lgkmcnt(1)
	v_mfma_f32_32x32x16_bf16 v[2:17], v[178:181], v[162:165], v[2:17]
	ds_read2_b64 v[166:169], v224 offset0:4 offset1:6
	s_and_b64 vcc, exec, s[0:1]
	s_cbranch_vccnz .LBB0_863
	v_add_u32_e32 v174, -1, v240
	s_movk_i32 s2, 0xfeff
	v_cmp_gt_u32_e32 vcc, s2, v174
	v_add_u32_e32 v174, -2, v240
	s_nop 0
	v_cndmask_b32_e32 v34, v34, v243, vcc
	v_cmp_lt_u32_e32 vcc, s95, v174
	v_add_u32_e32 v174, -3, v240
	s_nop 0
	v_cndmask_b32_e32 v35, v243, v35, vcc
	v_cmp_lt_u32_e32 vcc, s95, v174
	v_add_u32_e32 v174, -4, v240
	s_nop 0
	v_cndmask_b32_e32 v36, v243, v36, vcc
	v_cmp_lt_u32_e32 vcc, s95, v174
	s_nop 1
	v_cndmask_b32_e32 v37, v243, v37, vcc

.LBB0_877:
	v_pk_add_f32 v[162:163], v[196:197], 0 op_sel_hi:[1,0]
	v_max3_f32 v164, v166, v78, v79
	s_nop 0
	v_pk_add_f32 v[162:163], v[198:199], v[162:163]
	v_max3_f32 v208, v164, v80, v81
	s_nop 0
	v_pk_add_f32 v[162:163], v[200:201], v[162:163]
	s_nop 0
	v_pk_add_f32 v[162:163], v[202:203], v[162:163]
	s_nop 0
	v_pk_add_f32 v[162:163], v[204:205], v[162:163]
	s_nop 0
	v_pk_add_f32 v[162:163], v[214:215], v[162:163]
	s_nop 0
	v_pk_add_f32 v[162:163], v[216:217], v[162:163]
	s_nop 0
	v_pk_add_f32 v[162:163], v[218:219], v[162:163]
	s_nop 0
	v_pk_add_f32 v[162:163], v[178:179], v[162:163]
	s_nop 0
	v_pk_add_f32 v[162:163], v[180:181], v[162:163]
	s_nop 0
	v_pk_add_f32 v[162:163], v[220:221], v[162:163]
	s_nop 0
	v_pk_add_f32 v[162:163], v[222:223], v[162:163]
	s_nop 0
	v_pk_add_f32 v[162:163], v[176:177], v[162:163]
	s_nop 0
	v_pk_add_f32 v[162:163], v[226:227], v[162:163]
	s_nop 0
	v_pk_add_f32 v[162:163], v[174:175], v[162:163]
	s_nop 0
	v_pk_add_f32 v[162:163], v[224:225], v[162:163]
	v_add_f32_e32 v162, v162, v163
	v_add_f32_e32 v251, v251, v162
	v_pk_add_f32 v[162:163], v[188:189], v[208:209]
	s_nop 0
	v_cmp_gt_f32_e32 vcc, v162, v163
	s_cbranch_vccz .LBB0_879
	v_cmp_lt_i32_e32 vcc, v241, v235
	v_max_f32_e32 v51, v208, v208
	v_max_f32_e32 v52, v189, v189
	v_cndmask_b32_e32 v50, v233, v241, vcc
	v_lshlrev_b32_e32 v50, 2, v50
	ds_bpermute_b32 v50, v50, v208
	s_waitcnt lgkmcnt(0)
	v_max_f32_e32 v50, v50, v50
	v_max_f32_e32 v50, v51, v50
	v_add_f32_e32 v50, v188, v50
	v_max_f32_e32 v162, v52, v50
	v_sub_f32_e32 v50, v189, v162
	v_exp_f32_e32 v164, v50
	v_sub_f32_e32 v50, v188, v162
	v_pk_add_f32 v[80:81], v[80:81], v[50:51] op_sel_hi:[1,0]
	v_pk_add_f32 v[78:79], v[78:79], v[50:51] op_sel_hi:[1,0]
	v_pk_add_f32 v[76:77], v[76:77], v[50:51] op_sel_hi:[1,0]
	v_pk_add_f32 v[74:75], v[74:75], v[50:51] op_sel_hi:[1,0]
	v_pk_add_f32 v[72:73], v[72:73], v[50:51] op_sel_hi:[1,0]
	v_pk_add_f32 v[70:71], v[70:71], v[50:51] op_sel_hi:[1,0]
	v_pk_add_f32 v[68:69], v[68:69], v[50:51] op_sel_hi:[1,0]
	v_pk_add_f32 v[66:67], v[66:67], v[50:51] op_sel_hi:[1,0]
	v_pk_add_f32 v[48:49], v[48:49], v[50:51] op_sel_hi:[1,0]
	v_pk_add_f32 v[46:47], v[46:47], v[50:51] op_sel_hi:[1,0]
	v_pk_add_f32 v[44:45], v[44:45], v[50:51] op_sel_hi:[1,0]
	v_pk_add_f32 v[42:43], v[42:43], v[50:51] op_sel_hi:[1,0]
	v_pk_add_f32 v[40:41], v[40:41], v[50:51] op_sel_hi:[1,0]
	v_pk_add_f32 v[38:39], v[38:39], v[50:51] op_sel_hi:[1,0]
	v_pk_add_f32 v[36:37], v[36:37], v[50:51] op_sel_hi:[1,0]
	v_pk_add_f32 v[34:35], v[34:35], v[50:51] op_sel_hi:[1,0]
	v_xor_b32_e32 v50, 0x80000000, v162
	v_mov_b32_e32 v163, v162
	v_pk_mul_f32 v[16:17], v[16:17], v[164:165] op_sel_hi:[1,0]
	v_pk_mul_f32 v[14:15], v[14:15], v[164:165] op_sel_hi:[1,0]
	v_pk_mul_f32 v[12:13], v[12:13], v[164:165] op_sel_hi:[1,0]
	v_pk_mul_f32 v[10:11], v[10:11], v[164:165] op_sel_hi:[1,0]
	v_pk_mul_f32 v[8:9], v[8:9], v[164:165] op_sel_hi:[1,0]
	v_pk_mul_f32 v[6:7], v[6:7], v[164:165] op_sel_hi:[1,0]
	v_pk_mul_f32 v[4:5], v[4:5], v[164:165] op_sel_hi:[1,0]
	v_pk_mul_f32 v[2:3], v[2:3], v[164:165] op_sel_hi:[1,0]
	v_pk_mul_f32 v[32:33], v[32:33], v[164:165] op_sel_hi:[1,0]
	v_pk_mul_f32 v[30:31], v[30:31], v[164:165] op_sel_hi:[1,0]
	v_pk_mul_f32 v[28:29], v[28:29], v[164:165] op_sel_hi:[1,0]
	v_pk_mul_f32 v[26:27], v[26:27], v[164:165] op_sel_hi:[1,0]
	v_pk_mul_f32 v[24:25], v[24:25], v[164:165] op_sel_hi:[1,0]
	v_pk_mul_f32 v[22:23], v[22:23], v[164:165] op_sel_hi:[1,0]
	v_pk_mul_f32 v[20:21], v[20:21], v[164:165] op_sel_hi:[1,0]
	v_pk_mul_f32 v[18:19], v[18:19], v[164:165] op_sel_hi:[1,0]
	v_mov_b32_e32 v51, v50
	v_mov_b32_e32 v52, v50
	v_mov_b32_e32 v53, v50
	v_mov_b32_e32 v54, v50
	v_mov_b32_e32 v55, v50
	v_mov_b32_e32 v56, v50
	v_mov_b32_e32 v57, v50
	v_mov_b32_e32 v58, v50
	v_mov_b32_e32 v59, v50
	v_mov_b32_e32 v60, v50
	v_mov_b32_e32 v61, v50
	v_mov_b32_e32 v62, v50
	v_mov_b32_e32 v63, v50
	v_mov_b32_e32 v64, v50
	v_mov_b32_e32 v65, v50
	v_mul_f32_e32 v251, v251, v164
	v_mov_b64_e32 v[188:189], v[162:163]

.LBB0_882:
	s_mul_i32 s2, s5, 0x2200
	v_add_u32_e32 v82, s2, v191
	s_add_i32 s2, s15, -1
	s_min_i32 s2, s2, s14
	s_cmp_gt_i32 s2, 3
	s_cselect_b32 s3, s7, 0
	s_add_i32 s3, s3, s2
	s_lshl_b32 s2, s3, 6
	s_ashr_i32 s3, s2, 31
	s_lshl_b64 s[2:3], s[2:3], 7
	s_waitcnt vmcnt(5)
	ds_write_b128 v185, v[146:149] offset:9216
	s_waitcnt vmcnt(4)
	ds_write_b16 v82, v150 offset:36864
	ds_write_b16_d16_hi v82, v150 offset:37000
	ds_write_b16 v82, v151 offset:37136
	ds_write_b16_d16_hi v82, v151 offset:37272
	ds_write_b16 v82, v152 offset:37408
	ds_write_b16_d16_hi v82, v152 offset:37544
	ds_write_b16 v82, v153 offset:37680
	ds_write_b16_d16_hi v82, v153 offset:37816
	v_lshl_add_u64 v[82:83], v[192:193], 0, s[2:3]
	v_lshl_add_u64 v[84:85], v[194:195], 0, s[2:3]
	global_load_dwordx4 v[146:149], v[82:83], off
	global_load_dwordx4 v[150:153], v[84:85], off
	ds_read_b128 v[98:101], v245 offset:27648
	ds_read_b128 v[102:105], v245 offset:27680
	s_mul_i32 s2, s18, 0x2200
	v_add_u32_e32 v204, s2, v1
	s_waitcnt lgkmcnt(1)
	v_mfma_f32_32x32x16_bf16 v[82:97], v[98:101], v[114:117], v[50:65]
	ds_read_b128 v[106:109], v245 offset:27712
	v_exp_f32_e32 v196, v34
	v_exp_f32_e32 v197, v35
	v_exp_f32_e32 v198, v36
	v_exp_f32_e32 v199, v37
	v_cvt_pk_bf16_f32 v162, v196, v197
	v_cvt_pk_bf16_f32 v163, v198, v199
	s_waitcnt lgkmcnt(1)
	v_mfma_f32_32x32x16_bf16 v[82:97], v[102:105], v[118:121], v[82:97]
	ds_read_b128 v[98:101], v245 offset:27744
	v_exp_f32_e32 v200, v38
	v_exp_f32_e32 v201, v39
	v_exp_f32_e32 v202, v40
	v_exp_f32_e32 v203, v41
	v_cvt_pk_bf16_f32 v164, v200, v201
	v_cvt_pk_bf16_f32 v165, v202, v203
	s_waitcnt lgkmcnt(1)
	v_mfma_f32_32x32x16_bf16 v[82:97], v[106:109], v[122:125], v[82:97]
	ds_read_b128 v[166:169], v245 offset:32256
	s_waitcnt lgkmcnt(1)
	v_mfma_f32_32x32x16_bf16 v[82:97], v[98:101], v[126:129], v[82:97]
	ds_read_b128 v[170:173], v245 offset:32288
	s_waitcnt lgkmcnt(1)
	v_mfma_f32_32x32x16_bf16 v[98:113], v[166:169], v[114:117], v[50:65]
	ds_read_b128 v[174:177], v245 offset:32320
	s_waitcnt lgkmcnt(1)
	v_mfma_f32_32x32x16_bf16 v[98:113], v[170:173], v[118:121], v[98:113]
	ds_read_b128 v[166:169], v245 offset:32352
	s_waitcnt lgkmcnt(1)
	v_mfma_f32_32x32x16_bf16 v[98:113], v[174:177], v[122:125], v[98:113]
	v_add_u32_e32 v224, 0x9000, v204
	ds_read2_b64 v[178:181], v224 offset1:2
	s_waitcnt lgkmcnt(1)
	v_mfma_f32_32x32x16_bf16 v[98:113], v[166:169], v[126:129], v[98:113]
	v_add_u32_e32 v208, 0xa000, v204
	ds_read2_b64 v[170:173], v208 offset0:32 offset1:34
	s_waitcnt lgkmcnt(1)
	v_mfma_f32_32x32x16_bf16 v[2:17], v[178:181], v[162:165], v[2:17]
	ds_read2_b64 v[166:169], v224 offset0:4 offset1:6
	s_and_b64 vcc, exec, s[0:1]
	s_cbranch_vccnz .LBB0_884
	v_add_u32_e32 v174, 0xffffffbf, v240
	v_cmp_lt_u32_e32 vcc, s95, v174
	v_add_u32_e32 v174, 0xffffffbe, v240
	s_nop 0
	v_cndmask_b32_e32 v82, v243, v82, vcc
	v_cmp_lt_u32_e32 vcc, s95, v174
	v_add_u32_e32 v174, 0xffffffbd, v240
	s_nop 0
	v_cndmask_b32_e32 v83, v243, v83, vcc
	v_cmp_lt_u32_e32 vcc, s95, v174
	v_add_u32_e32 v174, 0xffffffbc, v240
	s_nop 0
	v_cndmask_b32_e32 v84, v243, v84, vcc
	v_cmp_lt_u32_e32 vcc, s95, v174
	s_nop 1
	v_cndmask_b32_e32 v85, v243, v85, vcc

.LBB0_898:
	v_pk_add_f32 v[162:163], v[196:197], 0 op_sel_hi:[1,0]
	v_max3_f32 v164, v166, v110, v111
	s_nop 0
	v_pk_add_f32 v[162:163], v[198:199], v[162:163]
	v_max3_f32 v208, v164, v112, v113
	s_nop 0
	v_pk_add_f32 v[162:163], v[200:201], v[162:163]
	s_nop 0
	v_pk_add_f32 v[162:163], v[202:203], v[162:163]
	s_nop 0
	v_pk_add_f32 v[162:163], v[204:205], v[162:163]
	s_nop 0
	v_pk_add_f32 v[162:163], v[214:215], v[162:163]
	s_nop 0
	v_pk_add_f32 v[162:163], v[216:217], v[162:163]
	s_nop 0
	v_pk_add_f32 v[162:163], v[218:219], v[162:163]
	s_nop 0
	v_pk_add_f32 v[162:163], v[178:179], v[162:163]
	s_nop 0
	v_pk_add_f32 v[162:163], v[180:181], v[162:163]
	s_nop 0
	v_pk_add_f32 v[162:163], v[220:221], v[162:163]
	s_nop 0
	v_pk_add_f32 v[162:163], v[222:223], v[162:163]
	s_nop 0
	v_pk_add_f32 v[162:163], v[176:177], v[162:163]
	s_nop 0
	v_pk_add_f32 v[162:163], v[226:227], v[162:163]
	s_nop 0
	v_pk_add_f32 v[162:163], v[174:175], v[162:163]
	s_nop 0
	v_pk_add_f32 v[162:163], v[224:225], v[162:163]
	v_add_f32_e32 v162, v162, v163
	v_add_f32_e32 v251, v251, v162
	v_pk_add_f32 v[162:163], v[188:189], v[208:209]
	s_nop 0
	v_cmp_gt_f32_e32 vcc, v162, v163
	s_cbranch_vccz .LBB0_900
	v_cmp_lt_i32_e32 vcc, v241, v235
	v_max_f32_e32 v51, v208, v208
	v_max_f32_e32 v52, v189, v189
	v_cndmask_b32_e32 v50, v233, v241, vcc
	v_lshlrev_b32_e32 v50, 2, v50
	ds_bpermute_b32 v50, v50, v208
	s_waitcnt lgkmcnt(0)
	v_max_f32_e32 v50, v50, v50
	v_max_f32_e32 v50, v51, v50
	v_add_f32_e32 v50, v188, v50
	v_max_f32_e32 v162, v52, v50
	v_sub_f32_e32 v50, v189, v162
	v_exp_f32_e32 v164, v50
	v_sub_f32_e32 v50, v188, v162
	v_pk_add_f32 v[96:97], v[96:97], v[50:51] op_sel_hi:[1,0]
	v_pk_add_f32 v[94:95], v[94:95], v[50:51] op_sel_hi:[1,0]
	v_pk_add_f32 v[92:93], v[92:93], v[50:51] op_sel_hi:[1,0]
	v_pk_add_f32 v[90:91], v[90:91], v[50:51] op_sel_hi:[1,0]
	v_pk_add_f32 v[88:89], v[88:89], v[50:51] op_sel_hi:[1,0]
	v_pk_add_f32 v[86:87], v[86:87], v[50:51] op_sel_hi:[1,0]
	v_pk_add_f32 v[84:85], v[84:85], v[50:51] op_sel_hi:[1,0]
	v_pk_add_f32 v[82:83], v[82:83], v[50:51] op_sel_hi:[1,0]
	v_pk_add_f32 v[112:113], v[112:113], v[50:51] op_sel_hi:[1,0]
	v_pk_add_f32 v[110:111], v[110:111], v[50:51] op_sel_hi:[1,0]
	v_pk_add_f32 v[108:109], v[108:109], v[50:51] op_sel_hi:[1,0]
	v_pk_add_f32 v[106:107], v[106:107], v[50:51] op_sel_hi:[1,0]
	v_pk_add_f32 v[104:105], v[104:105], v[50:51] op_sel_hi:[1,0]
	v_pk_add_f32 v[102:103], v[102:103], v[50:51] op_sel_hi:[1,0]
	v_pk_add_f32 v[100:101], v[100:101], v[50:51] op_sel_hi:[1,0]
	v_pk_add_f32 v[98:99], v[98:99], v[50:51] op_sel_hi:[1,0]
	v_xor_b32_e32 v50, 0x80000000, v162
	v_mov_b32_e32 v163, v162
	v_pk_mul_f32 v[16:17], v[16:17], v[164:165] op_sel_hi:[1,0]
	v_pk_mul_f32 v[14:15], v[14:15], v[164:165] op_sel_hi:[1,0]
	v_pk_mul_f32 v[12:13], v[12:13], v[164:165] op_sel_hi:[1,0]
	v_pk_mul_f32 v[10:11], v[10:11], v[164:165] op_sel_hi:[1,0]
	v_pk_mul_f32 v[8:9], v[8:9], v[164:165] op_sel_hi:[1,0]
	v_pk_mul_f32 v[6:7], v[6:7], v[164:165] op_sel_hi:[1,0]
	v_pk_mul_f32 v[4:5], v[4:5], v[164:165] op_sel_hi:[1,0]
	v_pk_mul_f32 v[2:3], v[2:3], v[164:165] op_sel_hi:[1,0]
	v_pk_mul_f32 v[32:33], v[32:33], v[164:165] op_sel_hi:[1,0]
	v_pk_mul_f32 v[30:31], v[30:31], v[164:165] op_sel_hi:[1,0]
	v_pk_mul_f32 v[28:29], v[28:29], v[164:165] op_sel_hi:[1,0]
	v_pk_mul_f32 v[26:27], v[26:27], v[164:165] op_sel_hi:[1,0]
	v_pk_mul_f32 v[24:25], v[24:25], v[164:165] op_sel_hi:[1,0]
	v_pk_mul_f32 v[22:23], v[22:23], v[164:165] op_sel_hi:[1,0]
	v_pk_mul_f32 v[20:21], v[20:21], v[164:165] op_sel_hi:[1,0]
	v_pk_mul_f32 v[18:19], v[18:19], v[164:165] op_sel_hi:[1,0]
	v_mov_b32_e32 v51, v50
	v_mov_b32_e32 v52, v50
	v_mov_b32_e32 v53, v50
	v_mov_b32_e32 v54, v50
	v_mov_b32_e32 v55, v50
	v_mov_b32_e32 v56, v50
	v_mov_b32_e32 v57, v50
	v_mov_b32_e32 v58, v50
	v_mov_b32_e32 v59, v50
	v_mov_b32_e32 v60, v50
	v_mov_b32_e32 v61, v50
	v_mov_b32_e32 v62, v50
	v_mov_b32_e32 v63, v50
	v_mov_b32_e32 v64, v50
	v_mov_b32_e32 v65, v50
	v_mul_f32_e32 v251, v251, v164
	v_mov_b64_e32 v[188:189], v[162:163]

.LBB0_901:
	s_mul_i32 s0, s5, 0x2200
	v_add_u32_e32 v34, s0, v191
	s_min_i32 s0, s15, s14
	s_cmp_gt_i32 s0, 3
	s_cselect_b32 s1, s7, 0
	s_add_i32 s1, s1, s0
	s_lshl_b32 s0, s1, 6
	s_ashr_i32 s1, s0, 31
	s_lshl_b64 s[0:1], s[0:1], 7
	s_waitcnt vmcnt(3)
	ds_write_b128 v185, v[154:157] offset:18432
	s_waitcnt vmcnt(2)
	ds_write_b16 v34, v158 offset:36864
	ds_write_b16_d16_hi v34, v158 offset:37000
	ds_write_b16 v34, v159 offset:37136
	ds_write_b16_d16_hi v34, v159 offset:37272
	ds_write_b16 v34, v160 offset:37408
	ds_write_b16_d16_hi v34, v160 offset:37544
	ds_write_b16 v34, v161 offset:37680
	ds_write_b16_d16_hi v34, v161 offset:37816
	v_lshl_add_u64 v[34:35], v[192:193], 0, s[0:1]
	v_lshl_add_u64 v[36:37], v[194:195], 0, s[0:1]
	global_load_dwordx4 v[154:157], v[34:35], off
	global_load_dwordx4 v[158:161], v[36:37], off
	ds_read_b128 v[66:69], v245
	ds_read_b128 v[70:73], v245 offset:32
	s_mul_i32 s0, s18, 0x2200
	v_add_u32_e32 v170, s0, v1
	s_waitcnt lgkmcnt(1)
	v_mfma_f32_32x32x16_bf16 v[34:49], v[66:69], v[114:117], v[50:65]
	v_exp_f32_e32 v66, v82
	v_exp_f32_e32 v67, v83
	ds_read_b128 v[74:77], v245 offset:64
	v_pk_add_f32 v[68:69], v[66:67], 0 op_sel_hi:[1,0]
	v_cvt_pk_bf16_f32 v82, v66, v67
	v_exp_f32_e32 v66, v84
	v_exp_f32_e32 v67, v85
	s_nop 0
	v_pk_add_f32 v[78:79], v[66:67], v[68:69]
	v_cvt_pk_bf16_f32 v83, v66, v67
	s_waitcnt lgkmcnt(1)
	v_mfma_f32_32x32x16_bf16 v[34:49], v[70:73], v[118:121], v[34:49]
	v_exp_f32_e32 v70, v86
	v_exp_f32_e32 v71, v87
	ds_read_b128 v[66:69], v245 offset:96
	v_pk_add_f32 v[72:73], v[70:71], v[78:79]
	v_cvt_pk_bf16_f32 v84, v70, v71
	v_exp_f32_e32 v70, v88
	v_exp_f32_e32 v71, v89
	s_nop 0
	v_pk_add_f32 v[72:73], v[70:71], v[72:73]
	v_cvt_pk_bf16_f32 v85, v70, v71
	v_exp_f32_e32 v70, v90
	v_exp_f32_e32 v71, v91
	s_waitcnt lgkmcnt(1)
	v_mfma_f32_32x32x16_bf16 v[34:49], v[74:77], v[122:125], v[34:49]
	ds_read_b128 v[162:165], v245 offset:4608
	v_add_f32_e64 v72, v70, v72
	v_add_f32_e64 v73, v71, v73
	v_cvt_pk_bf16_f32 v86, v70, v71
	v_exp_f32_e32 v70, v92
	v_exp_f32_e32 v71, v93
	s_nop 0
	v_pk_add_f32 v[72:73], v[70:71], v[72:73]
	v_cvt_pk_bf16_f32 v87, v70, v71
	s_waitcnt lgkmcnt(1)
	v_mfma_f32_32x32x16_bf16 v[34:49], v[66:69], v[126:129], v[34:49]
	v_exp_f32_e32 v66, v94
	v_exp_f32_e32 v67, v95
	ds_read_b128 v[166:169], v245 offset:4640
	v_pk_add_f32 v[68:69], v[66:67], v[72:73]
	v_cvt_pk_bf16_f32 v88, v66, v67
	v_exp_f32_e32 v66, v96
	v_exp_f32_e32 v67, v97
	s_nop 0
	v_pk_add_f32 v[68:69], v[66:67], v[68:69]
	v_cvt_pk_bf16_f32 v89, v66, v67
	v_exp_f32_e32 v90, v98
	v_exp_f32_e32 v91, v99
	ds_read_b128 v[94:97], v245 offset:4672
	v_exp_f32_e32 v92, v100
	v_exp_f32_e32 v93, v101
	v_pk_add_f32 v[98:99], v[90:91], v[68:69]
	s_waitcnt lgkmcnt(2)
	v_mfma_f32_32x32x16_bf16 v[66:81], v[162:165], v[114:117], v[50:65]
	v_cvt_pk_bf16_f32 v90, v90, v91
	v_add_f32_e64 v98, v92, v98
	v_add_f32_e64 v99, v93, v99
	v_cvt_pk_bf16_f32 v91, v92, v93
	s_waitcnt lgkmcnt(1)
	v_mfma_f32_32x32x16_bf16 v[66:81], v[166:169], v[118:121], v[66:81]
	v_exp_f32_e32 v92, v102
	v_exp_f32_e32 v93, v103
	ds_read_b128 v[162:165], v245 offset:4704
	v_exp_f32_e32 v100, v104
	v_exp_f32_e32 v101, v105
	v_pk_add_f32 v[98:99], v[92:93], v[98:99]
	v_cvt_pk_bf16_f32 v92, v92, v93
	v_pk_add_f32 v[98:99], v[100:101], v[98:99]
	v_cvt_pk_bf16_f32 v93, v100, v101
	s_waitcnt lgkmcnt(1)
	v_mfma_f32_32x32x16_bf16 v[66:81], v[94:97], v[122:125], v[66:81]
	v_add_u32_e32 v171, 0x9000, v170
	v_exp_f32_e32 v94, v106
	v_exp_f32_e32 v95, v107
	ds_read2_b64 v[166:169], v171 offset1:2
	v_exp_f32_e32 v100, v108
	v_exp_f32_e32 v101, v109
	v_pk_add_f32 v[96:97], v[94:95], v[98:99]
	v_cvt_pk_bf16_f32 v94, v94, v95
	v_pk_add_f32 v[98:99], v[100:101], v[96:97]
	v_cvt_pk_bf16_f32 v95, v100, v101
	s_waitcnt lgkmcnt(1)
	v_mfma_f32_32x32x16_bf16 v[66:81], v[162:165], v[126:129], v[66:81]
	v_add_u32_e32 v170, 0xa000, v170
	ds_read2_b64 v[104:107], v170 offset0:32 offset1:34
	v_exp_f32_e32 v100, v110
	v_exp_f32_e32 v101, v111
	v_exp_f32_e32 v102, v112
	v_exp_f32_e32 v103, v113
	v_cvt_pk_bf16_f32 v96, v100, v101
	v_cvt_pk_bf16_f32 v97, v102, v103
	s_waitcnt lgkmcnt(1)
	v_mfma_f32_32x32x16_bf16 v[2:17], v[166:169], v[82:85], v[2:17]
	v_add_u32_e32 v112, 0xffffff7f, v240
	v_cmp_lt_u32_e32 vcc, s95, v112
	v_add_u32_e32 v112, 0xffffff7e, v240
	ds_read2_b64 v[108:111], v171 offset0:4 offset1:6
	v_cndmask_b32_e32 v34, v243, v34, vcc
	v_cmp_lt_u32_e32 vcc, s95, v112
	v_add_u32_e32 v112, 0xffffff7d, v240
	s_nop 0
	v_cndmask_b32_e32 v35, v243, v35, vcc
	v_cmp_lt_u32_e32 vcc, s95, v112
	v_add_u32_e32 v112, 0xffffff7c, v240
	s_nop 0
	v_cndmask_b32_e32 v36, v243, v36, vcc
	v_cmp_lt_u32_e32 vcc, s95, v112
	v_max3_f32 v112, v231, v34, v35
	s_nop 1
	v_cndmask_b32_e32 v37, v243, v37, vcc
	v_max3_f32 v112, v112, v36, v37
	s_waitcnt lgkmcnt(1)
	v_mfma_f32_32x32x16_bf16 v[18:33], v[104:107], v[82:85], v[18:33]
	v_add_u32_e32 v82, 0xffffff77, v240
	v_cmp_lt_u32_e32 vcc, s95, v82
	v_add_u32_e32 v82, 0xffffff76, v240
	ds_read2_b64 v[162:165], v170 offset0:36 offset1:38
	v_cndmask_b32_e32 v38, v243, v38, vcc
	v_cmp_lt_u32_e32 vcc, s95, v82
	v_add_u32_e32 v82, 0xffffff75, v240
	s_nop 0
	v_cndmask_b32_e32 v39, v243, v39, vcc
	v_cmp_lt_u32_e32 vcc, s95, v82
	v_add_u32_e32 v82, 0xffffff74, v240
	s_nop 0
	v_cndmask_b32_e32 v40, v243, v40, vcc
	v_cmp_lt_u32_e32 vcc, s95, v82
	v_max3_f32 v82, v112, v38, v39
	s_nop 1
	v_cndmask_b32_e32 v41, v243, v41, vcc
	v_max3_f32 v104, v82, v40, v41
	s_waitcnt lgkmcnt(1)
	v_mfma_f32_32x32x16_bf16 v[2:17], v[108:111], v[86:89], v[2:17]
	v_add_u32_e32 v105, 0xffffff6f, v240
	v_cmp_lt_u32_e32 vcc, s95, v105
	v_add_u32_e32 v105, 0xffffff6e, v240
	ds_read2_b64 v[82:85], v171 offset0:8 offset1:10
	v_cndmask_b32_e32 v42, v243, v42, vcc
	v_cmp_lt_u32_e32 vcc, s95, v105
	v_add_u32_e32 v105, 0xffffff6d, v240
	s_nop 0
	v_cndmask_b32_e32 v43, v243, v43, vcc
	v_cmp_lt_u32_e32 vcc, s95, v105
	v_add_u32_e32 v105, 0xffffff6c, v240
	v_max3_f32 v104, v104, v42, v43
	s_nop 0
	v_cndmask_b32_e32 v44, v243, v44, vcc
	v_cmp_lt_u32_e32 vcc, s95, v105
	s_nop 1
	v_cndmask_b32_e32 v45, v243, v45, vcc
	v_max3_f32 v108, v104, v44, v45
	s_waitcnt lgkmcnt(1)
	v_mfma_f32_32x32x16_bf16 v[18:33], v[162:165], v[86:89], v[18:33]
	v_add_u32_e32 v86, 0xffffff67, v240
	v_cmp_lt_u32_e32 vcc, s95, v86
	v_add_u32_e32 v86, 0xffffff66, v240
	ds_read2_b64 v[104:107], v170 offset0:40 offset1:42
	v_cndmask_b32_e32 v46, v243, v46, vcc
	v_cmp_lt_u32_e32 vcc, s95, v86
	v_add_u32_e32 v86, 0xffffff65, v240
	s_nop 0
	v_cndmask_b32_e32 v47, v243, v47, vcc
	v_cmp_lt_u32_e32 vcc, s95, v86
	v_add_u32_e32 v86, 0xffffff64, v240
	s_nop 0
	v_cndmask_b32_e32 v48, v243, v48, vcc
	v_cmp_lt_u32_e32 vcc, s95, v86
	v_max3_f32 v86, v108, v46, v47
	s_nop 1
	v_cndmask_b32_e32 v49, v243, v49, vcc
	v_max3_f32 v108, v86, v48, v49
	s_waitcnt lgkmcnt(1)
	v_mfma_f32_32x32x16_bf16 v[2:17], v[82:85], v[90:93], v[2:17]
	v_add_u32_e32 v82, 0xffffff5f, v240
	v_cmp_lt_u32_e32 vcc, s95, v82
	v_add_u32_e32 v82, 0xffffff5e, v240
	ds_read2_b64 v[86:89], v171 offset0:12 offset1:14
	v_cndmask_b32_e32 v66, v243, v66, vcc
	v_cmp_lt_u32_e32 vcc, s95, v82
	v_add_u32_e32 v82, 0xffffff5d, v240
	s_nop 0
	v_cndmask_b32_e32 v67, v243, v67, vcc
	v_cmp_lt_u32_e32 vcc, s95, v82
	v_add_u32_e32 v82, 0xffffff5c, v240
	s_nop 0
	v_cndmask_b32_e32 v68, v243, v68, vcc
	v_cmp_lt_u32_e32 vcc, s95, v82
	v_max3_f32 v82, v108, v66, v67
	s_nop 1
	v_cndmask_b32_e32 v69, v243, v69, vcc
	v_max3_f32 v108, v82, v68, v69
	s_waitcnt lgkmcnt(1)
	v_mfma_f32_32x32x16_bf16 v[18:33], v[104:107], v[90:93], v[18:33]
	v_add_u32_e32 v109, 0xffffff57, v240
	v_cmp_lt_u32_e32 vcc, s95, v109
	v_add_u32_e32 v109, 0xffffff56, v240
	ds_read2_b64 v[82:85], v170 offset0:44 offset1:46
	v_cndmask_b32_e32 v70, v243, v70, vcc
	v_cmp_lt_u32_e32 vcc, s95, v109
	v_add_u32_e32 v90, 0xffffff55, v240
	s_nop 0
	v_cndmask_b32_e32 v71, v243, v71, vcc
	v_cmp_lt_u32_e32 vcc, s95, v90
	v_add_u32_e32 v90, 0xffffff54, v240
	s_nop 0
	v_cndmask_b32_e32 v72, v243, v72, vcc
	v_cmp_lt_u32_e32 vcc, s95, v90
	v_max3_f32 v90, v108, v70, v71
	s_nop 1
	v_cndmask_b32_e32 v73, v243, v73, vcc
	v_max3_f32 v90, v90, v72, v73
	s_waitcnt lgkmcnt(1)
	v_mfma_f32_32x32x16_bf16 v[2:17], v[86:89], v[94:97], v[2:17]
	v_add_u32_e32 v86, 0xffffff4f, v240
	v_cmp_lt_u32_e32 vcc, s95, v86
	v_add_u32_e32 v86, 0xffffff4e, v240
	s_nop 0
	v_cndmask_b32_e32 v74, v243, v74, vcc
	v_cmp_lt_u32_e32 vcc, s95, v86
	v_add_u32_e32 v86, 0xffffff4d, v240
	s_nop 0
	v_cndmask_b32_e32 v75, v243, v75, vcc
	v_cmp_lt_u32_e32 vcc, s95, v86
	v_add_u32_e32 v86, 0xffffff4c, v240
	s_nop 0
	v_cndmask_b32_e32 v76, v243, v76, vcc
	v_cmp_lt_u32_e32 vcc, s95, v86
	v_max3_f32 v86, v90, v74, v75
	s_nop 1
	v_cndmask_b32_e32 v77, v243, v77, vcc
	v_max3_f32 v86, v86, v76, v77
	s_waitcnt lgkmcnt(0)
	v_mfma_f32_32x32x16_bf16 v[18:33], v[82:85], v[94:97], v[18:33]
	v_add_u32_e32 v82, 0xffffff47, v240
	v_cmp_lt_u32_e32 vcc, s95, v82
	v_add_u32_e32 v82, 0xffffff46, v240
	s_nop 0
	v_cndmask_b32_e32 v78, v243, v78, vcc
	v_cmp_lt_u32_e32 vcc, s95, v82
	v_add_u32_e32 v82, 0xffffff45, v240
	s_nop 0
	v_cndmask_b32_e32 v79, v243, v79, vcc
	v_cmp_lt_u32_e32 vcc, s95, v82
	v_add_u32_e32 v82, 0xffffff44, v240
	s_nop 0
	v_cndmask_b32_e32 v80, v243, v80, vcc
	v_cmp_lt_u32_e32 vcc, s95, v82
	v_max3_f32 v82, v86, v78, v79
	s_nop 1
	v_cndmask_b32_e32 v81, v243, v81, vcc
	v_max3_f32 v208, v82, v80, v81
	v_pk_add_f32 v[82:83], v[100:101], v[98:99]
	s_nop 0
	v_pk_add_f32 v[82:83], v[102:103], v[82:83]
	v_add_f32_e32 v82, v82, v83
	v_add_f32_e32 v251, v251, v82
	v_pk_add_f32 v[82:83], v[188:189], v[208:209]
	s_nop 0
	v_cmp_gt_f32_e32 vcc, v82, v83
	s_cbranch_vccz .LBB0_840
	v_cmp_lt_i32_e32 vcc, v241, v235
	v_max_f32_e32 v51, v208, v208
	v_max_f32_e32 v52, v189, v189
	v_cndmask_b32_e32 v50, v233, v241, vcc
	v_lshlrev_b32_e32 v50, 2, v50
	ds_bpermute_b32 v50, v50, v208
	s_waitcnt lgkmcnt(0)
	v_max_f32_e32 v50, v50, v50
	v_max_f32_e32 v50, v51, v50
	v_add_f32_e32 v50, v188, v50
	v_max_f32_e32 v82, v52, v50
	v_sub_f32_e32 v50, v189, v82
	v_exp_f32_e32 v84, v50
	v_sub_f32_e32 v50, v188, v82
	v_pk_add_f32 v[80:81], v[80:81], v[50:51] op_sel_hi:[1,0]
	v_pk_add_f32 v[78:79], v[78:79], v[50:51] op_sel_hi:[1,0]
	v_pk_add_f32 v[76:77], v[76:77], v[50:51] op_sel_hi:[1,0]
	v_pk_add_f32 v[74:75], v[74:75], v[50:51] op_sel_hi:[1,0]
	v_pk_add_f32 v[72:73], v[72:73], v[50:51] op_sel_hi:[1,0]
	v_pk_add_f32 v[70:71], v[70:71], v[50:51] op_sel_hi:[1,0]
	v_pk_add_f32 v[68:69], v[68:69], v[50:51] op_sel_hi:[1,0]
	v_pk_add_f32 v[66:67], v[66:67], v[50:51] op_sel_hi:[1,0]
	v_pk_add_f32 v[48:49], v[48:49], v[50:51] op_sel_hi:[1,0]
	v_pk_add_f32 v[46:47], v[46:47], v[50:51] op_sel_hi:[1,0]
	v_pk_add_f32 v[44:45], v[44:45], v[50:51] op_sel_hi:[1,0]
	v_pk_add_f32 v[42:43], v[42:43], v[50:51] op_sel_hi:[1,0]
	v_pk_add_f32 v[40:41], v[40:41], v[50:51] op_sel_hi:[1,0]
	v_pk_add_f32 v[38:39], v[38:39], v[50:51] op_sel_hi:[1,0]
	v_pk_add_f32 v[36:37], v[36:37], v[50:51] op_sel_hi:[1,0]
	v_pk_add_f32 v[34:35], v[34:35], v[50:51] op_sel_hi:[1,0]
	v_xor_b32_e32 v50, 0x80000000, v82
	v_mov_b32_e32 v83, v82
	v_pk_mul_f32 v[16:17], v[16:17], v[84:85] op_sel_hi:[1,0]
	v_pk_mul_f32 v[14:15], v[14:15], v[84:85] op_sel_hi:[1,0]
	v_pk_mul_f32 v[12:13], v[12:13], v[84:85] op_sel_hi:[1,0]
	v_pk_mul_f32 v[10:11], v[10:11], v[84:85] op_sel_hi:[1,0]
	v_pk_mul_f32 v[8:9], v[8:9], v[84:85] op_sel_hi:[1,0]
	v_pk_mul_f32 v[6:7], v[6:7], v[84:85] op_sel_hi:[1,0]
	v_pk_mul_f32 v[4:5], v[4:5], v[84:85] op_sel_hi:[1,0]
	v_pk_mul_f32 v[2:3], v[2:3], v[84:85] op_sel_hi:[1,0]
	v_pk_mul_f32 v[32:33], v[32:33], v[84:85] op_sel_hi:[1,0]
	v_pk_mul_f32 v[30:31], v[30:31], v[84:85] op_sel_hi:[1,0]
	v_pk_mul_f32 v[28:29], v[28:29], v[84:85] op_sel_hi:[1,0]
	v_pk_mul_f32 v[26:27], v[26:27], v[84:85] op_sel_hi:[1,0]
	v_pk_mul_f32 v[24:25], v[24:25], v[84:85] op_sel_hi:[1,0]
	v_pk_mul_f32 v[22:23], v[22:23], v[84:85] op_sel_hi:[1,0]
	v_pk_mul_f32 v[20:21], v[20:21], v[84:85] op_sel_hi:[1,0]
	v_pk_mul_f32 v[18:19], v[18:19], v[84:85] op_sel_hi:[1,0]
	v_mov_b32_e32 v51, v50
	v_mov_b32_e32 v52, v50
	v_mov_b32_e32 v53, v50
	v_mov_b32_e32 v54, v50
	v_mov_b32_e32 v55, v50
	v_mov_b32_e32 v56, v50
	v_mov_b32_e32 v57, v50
	v_mov_b32_e32 v58, v50
	v_mov_b32_e32 v59, v50
	v_mov_b32_e32 v60, v50
	v_mov_b32_e32 v61, v50
	v_mov_b32_e32 v62, v50
	v_mov_b32_e32 v63, v50
	v_mov_b32_e32 v64, v50
	v_mov_b32_e32 v65, v50
	v_mul_f32_e32 v251, v251, v84
	v_mov_b64_e32 v[188:189], v[82:83]
	s_branch .LBB0_840

.LBB0_937:
	s_or_b64 exec, exec, s[6:7]
	s_lshl_b32 s84, s14, 7
	v_lshl_add_u64 v[82:83], v[220:221], 0, s[84:85]
	global_load_dwordx4 v[178:181], v[82:83], off
	ds_read_b128 v[100:103], v249 offset:13312
	ds_read_b128 v[104:107], v249 offset:13344
	s_mul_i32 s4, s10, 0x2200
	v_add_u32_e32 v99, s4, v248
	s_waitcnt lgkmcnt(1)
	v_mfma_f32_32x32x16_bf16 v[82:97], v[100:103], v[134:137], v[50:65]
	v_exp_f32_e32 v100, v66
	v_exp_f32_e32 v101, v67
	ds_read_b128 v[108:111], v249 offset:13376
	v_exp_f32_e32 v68, v68
	v_exp_f32_e32 v69, v69
	v_cvt_pk_bf16_f32 v66, v100, v101
	v_cvt_pk_bf16_f32 v67, v68, v69
	v_pk_add_f32 v[112:113], v[68:69], v[100:101]
	s_waitcnt lgkmcnt(1)
	v_mfma_f32_32x32x16_bf16 v[82:97], v[104:107], v[138:141], v[82:97]
	ds_read_b128 v[100:103], v249 offset:13408
	v_exp_f32_e32 v70, v70
	v_exp_f32_e32 v71, v71
	v_exp_f32_e32 v72, v72
	v_exp_f32_e32 v73, v73
	v_cvt_pk_bf16_f32 v68, v70, v71
	v_pk_add_f32 v[70:71], v[70:71], v[112:113]
	v_cvt_pk_bf16_f32 v69, v72, v73
	v_pk_add_f32 v[112:113], v[72:73], v[70:71]
	s_waitcnt lgkmcnt(1)
	v_mfma_f32_32x32x16_bf16 v[82:97], v[108:111], v[142:145], v[82:97]
	v_exp_f32_e32 v72, v74
	v_exp_f32_e32 v73, v75
	ds_read_b128 v[104:107], v249 offset:13440
	v_exp_f32_e32 v74, v76
	v_exp_f32_e32 v75, v77
	v_cvt_pk_bf16_f32 v70, v72, v73
	v_pk_add_f32 v[72:73], v[72:73], v[112:113]
	v_cvt_pk_bf16_f32 v71, v74, v75
	v_pk_add_f32 v[108:109], v[74:75], v[72:73]
	s_waitcnt lgkmcnt(1)
	v_mfma_f32_32x32x16_bf16 v[82:97], v[100:103], v[146:149], v[82:97]
	v_exp_f32_e32 v78, v78
	v_exp_f32_e32 v79, v79
	v_exp_f32_e32 v80, v80
	v_exp_f32_e32 v81, v81
	ds_read_b128 v[74:77], v249 offset:13472
	v_cvt_pk_bf16_f32 v72, v78, v79
	v_pk_add_f32 v[78:79], v[78:79], v[108:109]
	v_cvt_pk_bf16_f32 v73, v80, v81
	v_pk_add_f32 v[100:101], v[80:81], v[78:79]
	s_waitcnt lgkmcnt(1)
	v_mfma_f32_32x32x16_bf16 v[82:97], v[104:107], v[150:153], v[82:97]
	v_exp_f32_e32 v34, v34
	v_exp_f32_e32 v35, v35
	ds_read_b128 v[78:81], v249 offset:19968
	v_pk_add_f32 v[104:105], v[34:35], v[100:101]
	v_cvt_pk_bf16_f32 v34, v34, v35
	s_waitcnt lgkmcnt(1)
	v_mfma_f32_32x32x16_bf16 v[82:97], v[74:77], v[154:157], v[82:97]
	v_exp_f32_e32 v36, v36
	v_exp_f32_e32 v37, v37
	ds_read_b128 v[100:103], v249 offset:20000
	v_pk_add_f32 v[104:105], v[36:37], v[104:105]
	v_cvt_pk_bf16_f32 v35, v36, v37
	s_waitcnt lgkmcnt(1)
	v_mfma_f32_32x32x16_bf16 v[118:133], v[78:81], v[134:137], v[50:65]
	v_exp_f32_e32 v36, v38
	v_exp_f32_e32 v37, v39
	ds_read_b128 v[74:77], v249 offset:20032
	v_pk_add_f32 v[38:39], v[36:37], v[104:105]
	v_cvt_pk_bf16_f32 v36, v36, v37
	s_waitcnt lgkmcnt(1)
	v_mfma_f32_32x32x16_bf16 v[118:133], v[100:103], v[138:141], v[118:133]
	v_exp_f32_e32 v40, v40
	v_exp_f32_e32 v41, v41
	ds_read_b128 v[78:81], v249 offset:20064
	v_pk_add_f32 v[38:39], v[40:41], v[38:39]
	v_cvt_pk_bf16_f32 v37, v40, v41
	s_waitcnt lgkmcnt(1)
	v_mfma_f32_32x32x16_bf16 v[118:133], v[74:77], v[142:145], v[118:133]
	v_exp_f32_e32 v40, v42
	v_exp_f32_e32 v41, v43
	ds_read_b128 v[100:103], v249 offset:20096
	v_pk_add_f32 v[42:43], v[40:41], v[38:39]
	v_cvt_pk_bf16_f32 v38, v40, v41
	s_waitcnt lgkmcnt(1)
	v_mfma_f32_32x32x16_bf16 v[118:133], v[78:81], v[146:149], v[118:133]
	v_exp_f32_e32 v40, v44
	v_exp_f32_e32 v41, v45
	ds_read_b128 v[74:77], v249 offset:20128
	v_pk_add_f32 v[42:43], v[40:41], v[42:43]
	v_cvt_pk_bf16_f32 v39, v40, v41
	s_waitcnt lgkmcnt(1)
	v_mfma_f32_32x32x16_bf16 v[118:133], v[100:103], v[150:153], v[118:133]
	v_add_u32_e32 v104, 0xd000, v99
	v_exp_f32_e32 v40, v46
	v_exp_f32_e32 v41, v47
	ds_read2_b64 v[78:81], v104 offset1:2
	v_pk_add_f32 v[42:43], v[40:41], v[42:43]
	v_cvt_pk_bf16_f32 v40, v40, v41
	s_waitcnt lgkmcnt(1)
	v_mfma_f32_32x32x16_bf16 v[118:133], v[74:77], v[154:157], v[118:133]
	v_add_u32_e32 v99, 0xe000, v99
	v_exp_f32_e32 v48, v48
	v_exp_f32_e32 v49, v49
	ds_read2_b64 v[44:47], v99 offset0:32 offset1:34
	v_pk_add_f32 v[42:43], v[48:49], v[42:43]
	v_cvt_pk_bf16_f32 v41, v48, v49
	s_waitcnt lgkmcnt(1)
	v_mfma_f32_32x32x16_bf16 v[18:33], v[78:81], v[66:69], v[18:33]
	ds_read2_b64 v[74:77], v104 offset0:4 offset1:6
	v_max3_f32 v48, v231, v82, v83
	v_max3_f32 v48, v48, v84, v85
	s_waitcnt lgkmcnt(1)
	v_mfma_f32_32x32x16_bf16 v[2:17], v[44:47], v[66:69], v[2:17]
	ds_read2_b64 v[78:81], v99 offset0:36 offset1:38
	v_max3_f32 v44, v48, v86, v87
	v_max3_f32 v48, v44, v88, v89
	s_waitcnt lgkmcnt(1)
	v_mfma_f32_32x32x16_bf16 v[18:33], v[74:77], v[70:73], v[18:33]
	ds_read2_b64 v[44:47], v104 offset0:8 offset1:10
	v_max3_f32 v48, v48, v90, v91
	v_max3_f32 v48, v48, v92, v93
	s_waitcnt lgkmcnt(1)
	v_mfma_f32_32x32x16_bf16 v[2:17], v[78:81], v[70:73], v[2:17]
	ds_read2_b64 v[66:69], v99 offset0:40 offset1:42
	v_max3_f32 v48, v48, v94, v95
	v_max3_f32 v48, v48, v96, v97
	s_waitcnt lgkmcnt(1)
	v_mfma_f32_32x32x16_bf16 v[18:33], v[44:47], v[34:37], v[18:33]
	ds_read2_b64 v[70:73], v104 offset0:12 offset1:14
	v_max3_f32 v48, v48, v118, v119
	v_max3_f32 v48, v48, v120, v121
	s_waitcnt lgkmcnt(1)
	v_mfma_f32_32x32x16_bf16 v[2:17], v[66:69], v[34:37], v[2:17]
	ds_read2_b64 v[44:47], v99 offset0:44 offset1:46
	v_max3_f32 v48, v48, v122, v123
	v_max3_f32 v48, v48, v124, v125
	s_waitcnt lgkmcnt(1)
	v_mfma_f32_32x32x16_bf16 v[18:33], v[70:73], v[38:41], v[18:33]
	v_max3_f32 v34, v48, v126, v127
	v_max3_f32 v34, v34, v128, v129
	s_waitcnt lgkmcnt(0)
	v_mfma_f32_32x32x16_bf16 v[2:17], v[44:47], v[38:41], v[2:17]
	v_max3_f32 v34, v34, v130, v131
	v_max3_f32 v208, v34, v132, v133
	v_add_f32_e32 v34, v42, v43
	v_add_f32_e32 v100, v98, v34
	v_add_f32_e64 v34, v222, v208
	v_add_f32_e64 v35, v223, v209
	v_cmp_gt_f32_e32 vcc, v34, v35
	s_cbranch_vccz .LBB0_956
	v_cmp_lt_i32_e32 vcc, v241, v235
	v_max_f32_e32 v35, v208, v208
	v_max_f32_e32 v36, v223, v223
	v_cndmask_b32_e32 v34, v233, v241, vcc
	v_lshlrev_b32_e32 v34, 2, v34
	ds_bpermute_b32 v34, v34, v208
	s_waitcnt lgkmcnt(0)
	v_max_f32_e32 v34, v34, v34
	v_max_f32_e32 v34, v35, v34
	v_add_f32_e32 v34, v222, v34
	v_max_f32_e32 v224, v36, v34
	v_sub_f32_e32 v34, v223, v224
	v_exp_f32_e32 v36, v34
	v_sub_f32_e32 v34, v222, v224
	v_pk_add_f32 v[96:97], v[96:97], v[34:35] op_sel_hi:[1,0]
	v_pk_add_f32 v[94:95], v[94:95], v[34:35] op_sel_hi:[1,0]
	v_pk_add_f32 v[92:93], v[92:93], v[34:35] op_sel_hi:[1,0]
	v_pk_add_f32 v[90:91], v[90:91], v[34:35] op_sel_hi:[1,0]
	v_pk_add_f32 v[88:89], v[88:89], v[34:35] op_sel_hi:[1,0]
	v_pk_add_f32 v[86:87], v[86:87], v[34:35] op_sel_hi:[1,0]
	v_pk_add_f32 v[84:85], v[84:85], v[34:35] op_sel_hi:[1,0]
	v_pk_add_f32 v[82:83], v[82:83], v[34:35] op_sel_hi:[1,0]
	v_pk_add_f32 v[132:133], v[132:133], v[34:35] op_sel_hi:[1,0]
	v_pk_add_f32 v[130:131], v[130:131], v[34:35] op_sel_hi:[1,0]
	v_pk_add_f32 v[128:129], v[128:129], v[34:35] op_sel_hi:[1,0]
	v_pk_add_f32 v[126:127], v[126:127], v[34:35] op_sel_hi:[1,0]
	v_pk_add_f32 v[124:125], v[124:125], v[34:35] op_sel_hi:[1,0]
	v_pk_add_f32 v[122:123], v[122:123], v[34:35] op_sel_hi:[1,0]
	v_pk_add_f32 v[120:121], v[120:121], v[34:35] op_sel_hi:[1,0]
	v_pk_add_f32 v[118:119], v[118:119], v[34:35] op_sel_hi:[1,0]
	v_xor_b32_e32 v34, 0x80000000, v224
	v_pk_mul_f32 v[16:17], v[16:17], v[36:37] op_sel_hi:[1,0]
	v_pk_mul_f32 v[14:15], v[14:15], v[36:37] op_sel_hi:[1,0]
	v_pk_mul_f32 v[12:13], v[12:13], v[36:37] op_sel_hi:[1,0]
	v_pk_mul_f32 v[10:11], v[10:11], v[36:37] op_sel_hi:[1,0]
	v_pk_mul_f32 v[8:9], v[8:9], v[36:37] op_sel_hi:[1,0]
	v_pk_mul_f32 v[6:7], v[6:7], v[36:37] op_sel_hi:[1,0]
	v_pk_mul_f32 v[4:5], v[4:5], v[36:37] op_sel_hi:[1,0]
	v_pk_mul_f32 v[2:3], v[2:3], v[36:37] op_sel_hi:[1,0]
	v_pk_mul_f32 v[32:33], v[32:33], v[36:37] op_sel_hi:[1,0]
	v_pk_mul_f32 v[30:31], v[30:31], v[36:37] op_sel_hi:[1,0]
	v_pk_mul_f32 v[28:29], v[28:29], v[36:37] op_sel_hi:[1,0]
	v_pk_mul_f32 v[26:27], v[26:27], v[36:37] op_sel_hi:[1,0]
	v_pk_mul_f32 v[24:25], v[24:25], v[36:37] op_sel_hi:[1,0]
	v_pk_mul_f32 v[22:23], v[22:23], v[36:37] op_sel_hi:[1,0]
	v_pk_mul_f32 v[20:21], v[20:21], v[36:37] op_sel_hi:[1,0]
	v_pk_mul_f32 v[18:19], v[18:19], v[36:37] op_sel_hi:[1,0]
	v_mul_f32_e32 v100, v100, v36
	v_mov_b32_e32 v225, v224
	v_mov_b32_e32 v35, v34
	v_mov_b32_e32 v36, v34
	v_mov_b32_e32 v37, v34
	v_mov_b32_e32 v38, v34
	v_mov_b32_e32 v39, v34
	v_mov_b32_e32 v40, v34
	v_mov_b32_e32 v41, v34
	v_mov_b32_e32 v42, v34
	v_mov_b32_e32 v43, v34
	v_mov_b32_e32 v44, v34
	v_mov_b32_e32 v45, v34
	v_mov_b32_e32 v46, v34
	v_mov_b32_e32 v47, v34
	v_mov_b32_e32 v48, v34
	v_mov_b32_e32 v49, v34
	v_mov_b32_e32 v50, v34
	v_mov_b32_e32 v51, v34
	v_mov_b32_e32 v52, v34
	v_mov_b32_e32 v53, v34
	v_mov_b32_e32 v54, v34
	v_mov_b32_e32 v55, v34
	v_mov_b32_e32 v56, v34
	v_mov_b32_e32 v57, v34
	v_mov_b32_e32 v58, v34
	v_mov_b32_e32 v59, v34
	v_mov_b32_e32 v60, v34
	v_mov_b32_e32 v61, v34
	v_mov_b32_e32 v62, v34
	v_mov_b32_e32 v63, v34
	v_mov_b32_e32 v64, v34
	v_mov_b32_e32 v65, v34
	v_mov_b32_e32 v222, v224
	v_mov_b32_e32 v223, v224
	s_waitcnt vmcnt(7)
	ds_write_b128 v1, v[182:185]
	s_and_saveexec_b64 s[4:5], s[2:3]

.LBB0_942:
	s_or_b64 exec, exec, s[6:7]
	s_add_i32 s4, s10, 1
	s_cmp_lg_u32 s10, 4
	s_cselect_b32 s10, s4, 0
	s_lshl_b32 s84, s14, 7
	v_lshl_add_u64 v[66:67], v[220:221], 0, s[84:85]
	global_load_dwordx4 v[194:197], v[66:67], off
	ds_read_b128 v[102:105], v249 offset:26624
	ds_read_b128 v[106:109], v249 offset:26656
	s_mul_i32 s4, s10, 0x2200
	v_add_u32_e32 v101, s4, v248
	s_waitcnt lgkmcnt(1)
	v_mfma_f32_32x32x16_bf16 v[66:81], v[102:105], v[134:137], v[34:49]
	ds_read_b128 v[110:113], v249 offset:26688
	v_exp_f32_e32 v98, v82
	v_exp_f32_e32 v99, v83
	v_exp_f32_e32 v84, v84
	v_exp_f32_e32 v85, v85
	v_cvt_pk_bf16_f32 v82, v98, v99
	v_cvt_pk_bf16_f32 v83, v84, v85
	v_pk_add_f32 v[98:99], v[84:85], v[98:99]
	s_waitcnt lgkmcnt(1)
	v_mfma_f32_32x32x16_bf16 v[66:81], v[106:109], v[138:141], v[66:81]
	v_exp_f32_e32 v86, v86
	v_exp_f32_e32 v87, v87
	ds_read_b128 v[102:105], v249 offset:26720
	v_exp_f32_e32 v88, v88
	v_exp_f32_e32 v89, v89
	v_cvt_pk_bf16_f32 v84, v86, v87
	v_pk_add_f32 v[86:87], v[86:87], v[98:99]
	v_cvt_pk_bf16_f32 v85, v88, v89
	v_pk_add_f32 v[98:99], v[88:89], v[86:87]
	s_waitcnt lgkmcnt(1)
	v_mfma_f32_32x32x16_bf16 v[66:81], v[110:113], v[142:145], v[66:81]
	ds_read_b128 v[106:109], v249 offset:26752
	v_exp_f32_e32 v88, v90
	v_exp_f32_e32 v89, v91
	v_exp_f32_e32 v90, v92
	v_exp_f32_e32 v91, v93
	v_cvt_pk_bf16_f32 v86, v88, v89
	v_pk_add_f32 v[88:89], v[88:89], v[98:99]
	v_cvt_pk_bf16_f32 v87, v90, v91
	v_pk_add_f32 v[92:93], v[90:91], v[88:89]
	s_waitcnt lgkmcnt(1)
	v_mfma_f32_32x32x16_bf16 v[66:81], v[102:105], v[146:149], v[66:81]
	v_exp_f32_e32 v90, v94
	v_exp_f32_e32 v91, v95
	ds_read_b128 v[110:113], v249 offset:26784
	v_cvt_pk_bf16_f32 v88, v90, v91
	v_pk_add_f32 v[90:91], v[90:91], v[92:93]
	v_exp_f32_e32 v92, v96
	v_exp_f32_e32 v93, v97
	s_nop 0
	v_pk_add_f32 v[90:91], v[92:93], v[90:91]
	v_cvt_pk_bf16_f32 v89, v92, v93
	s_waitcnt lgkmcnt(1)
	v_mfma_f32_32x32x16_bf16 v[66:81], v[106:109], v[150:153], v[66:81]
	v_exp_f32_e32 v92, v118
	v_exp_f32_e32 v93, v119
	ds_read_b128 v[94:97], v249 offset:33280
	v_pk_add_f32 v[98:99], v[92:93], v[90:91]
	v_cvt_pk_bf16_f32 v90, v92, v93
	s_waitcnt lgkmcnt(1)
	v_mfma_f32_32x32x16_bf16 v[66:81], v[110:113], v[154:157], v[66:81]
	v_exp_f32_e32 v92, v120
	v_exp_f32_e32 v93, v121
	ds_read_b128 v[102:105], v249 offset:33312
	v_pk_add_f32 v[98:99], v[92:93], v[98:99]
	v_cvt_pk_bf16_f32 v91, v92, v93
	v_exp_f32_e32 v92, v122
	v_exp_f32_e32 v93, v123
	s_waitcnt lgkmcnt(1)
	v_mfma_f32_32x32x16_bf16 v[108:123], v[94:97], v[134:137], v[34:49]
	ds_read_b128 v[236:239], v249 offset:33344
	v_add_f32_e64 v106, v92, v98
	v_add_f32_e64 v107, v93, v99
	v_cvt_pk_bf16_f32 v92, v92, v93
	s_waitcnt lgkmcnt(1)
	v_mfma_f32_32x32x16_bf16 v[108:123], v[102:105], v[138:141], v[108:123]
	v_exp_f32_e32 v94, v124
	v_exp_f32_e32 v95, v125
	ds_read_b128 v[96:99], v249 offset:33376
	v_pk_add_f32 v[106:107], v[94:95], v[106:107]
	v_cvt_pk_bf16_f32 v93, v94, v95
	s_waitcnt lgkmcnt(1)
	v_mfma_f32_32x32x16_bf16 v[108:123], v[236:239], v[142:145], v[108:123]
	v_exp_f32_e32 v94, v126
	v_exp_f32_e32 v95, v127
	ds_read_b128 v[102:105], v249 offset:33408
	v_pk_add_f32 v[106:107], v[94:95], v[106:107]
	v_cvt_pk_bf16_f32 v94, v94, v95
	s_waitcnt lgkmcnt(1)
	v_mfma_f32_32x32x16_bf16 v[108:123], v[96:99], v[146:149], v[108:123]
	v_exp_f32_e32 v96, v128
	v_exp_f32_e32 v97, v129
	ds_read_b128 v[124:127], v249 offset:33440
	v_pk_add_f32 v[98:99], v[96:97], v[106:107]
	v_cvt_pk_bf16_f32 v95, v96, v97
	s_waitcnt lgkmcnt(1)
	v_mfma_f32_32x32x16_bf16 v[108:123], v[102:105], v[150:153], v[108:123]
	v_add_u32_e32 v208, 0xd000, v101
	v_exp_f32_e32 v96, v130
	v_exp_f32_e32 v97, v131
	ds_read2_b64 v[236:239], v208 offset1:2
	v_pk_add_f32 v[98:99], v[96:97], v[98:99]
	v_cvt_pk_bf16_f32 v96, v96, v97
	s_waitcnt lgkmcnt(1)
	v_mfma_f32_32x32x16_bf16 v[108:123], v[124:127], v[154:157], v[108:123]
	v_add_u32_e32 v101, 0xe000, v101
	v_exp_f32_e32 v106, v132
	v_exp_f32_e32 v107, v133
	ds_read2_b64 v[102:105], v101 offset0:32 offset1:34
	v_pk_add_f32 v[98:99], v[106:107], v[98:99]
	v_cvt_pk_bf16_f32 v97, v106, v107
	s_waitcnt lgkmcnt(1)
	v_mfma_f32_32x32x16_bf16 v[18:33], v[236:239], v[82:85], v[18:33]
	ds_read2_b64 v[124:127], v208 offset0:4 offset1:6
	v_max3_f32 v106, v231, v66, v67
	v_max3_f32 v106, v106, v68, v69
	s_waitcnt lgkmcnt(1)
	v_mfma_f32_32x32x16_bf16 v[2:17], v[102:105], v[82:85], v[2:17]
	ds_read2_b64 v[128:131], v101 offset0:36 offset1:38
	v_max3_f32 v82, v106, v70, v71
	v_max3_f32 v102, v82, v72, v73
	s_waitcnt lgkmcnt(1)
	v_mfma_f32_32x32x16_bf16 v[18:33], v[124:127], v[86:89], v[18:33]
	ds_read2_b64 v[82:85], v208 offset0:8 offset1:10
	v_max3_f32 v102, v102, v74, v75
	v_max3_f32 v106, v102, v76, v77
	s_waitcnt lgkmcnt(1)
	v_mfma_f32_32x32x16_bf16 v[2:17], v[128:131], v[86:89], v[2:17]
	ds_read2_b64 v[102:105], v101 offset0:40 offset1:42
	v_max3_f32 v86, v106, v78, v79
	v_max3_f32 v106, v86, v80, v81
	s_waitcnt lgkmcnt(1)
	v_mfma_f32_32x32x16_bf16 v[18:33], v[82:85], v[90:93], v[18:33]
	ds_read2_b64 v[86:89], v208 offset0:12 offset1:14
	v_max3_f32 v106, v106, v108, v109
	v_max3_f32 v106, v106, v110, v111
	s_waitcnt lgkmcnt(1)
	v_mfma_f32_32x32x16_bf16 v[2:17], v[102:105], v[90:93], v[2:17]
	ds_read2_b64 v[82:85], v101 offset0:44 offset1:46
	v_max3_f32 v101, v106, v112, v113
	v_max3_f32 v101, v101, v114, v115
	s_waitcnt lgkmcnt(1)
	v_mfma_f32_32x32x16_bf16 v[18:33], v[86:89], v[94:97], v[18:33]
	v_max3_f32 v86, v101, v116, v117
	v_max3_f32 v86, v86, v118, v119
	s_waitcnt lgkmcnt(0)
	v_mfma_f32_32x32x16_bf16 v[2:17], v[82:85], v[94:97], v[2:17]
	v_max3_f32 v82, v86, v120, v121
	v_max3_f32 v208, v82, v122, v123
	v_add_f32_e32 v82, v98, v99
	v_add_f32_e32 v124, v100, v82
	v_add_f32_e64 v82, v224, v208
	v_add_f32_e64 v83, v225, v209
	v_cmp_gt_f32_e32 vcc, v82, v83
	s_cbranch_vccz .LBB0_944
	v_cmp_lt_i32_e32 vcc, v241, v235
	v_max_f32_e32 v35, v208, v208
	v_max_f32_e32 v36, v223, v223
	v_cndmask_b32_e32 v34, v233, v241, vcc
	v_lshlrev_b32_e32 v34, 2, v34
	ds_bpermute_b32 v34, v34, v208
	s_waitcnt lgkmcnt(0)
	v_max_f32_e32 v34, v34, v34
	v_max_f32_e32 v34, v35, v34
	v_add_f32_e32 v34, v222, v34
	v_max_f32_e32 v224, v36, v34
	v_sub_f32_e32 v34, v223, v224
	v_exp_f32_e32 v36, v34
	v_sub_f32_e32 v34, v222, v224
	v_pk_add_f32 v[80:81], v[80:81], v[34:35] op_sel_hi:[1,0]
	v_pk_add_f32 v[78:79], v[78:79], v[34:35] op_sel_hi:[1,0]
	v_pk_add_f32 v[76:77], v[76:77], v[34:35] op_sel_hi:[1,0]
	v_pk_add_f32 v[74:75], v[74:75], v[34:35] op_sel_hi:[1,0]
	v_pk_add_f32 v[72:73], v[72:73], v[34:35] op_sel_hi:[1,0]
	v_pk_add_f32 v[70:71], v[70:71], v[34:35] op_sel_hi:[1,0]
	v_pk_add_f32 v[68:69], v[68:69], v[34:35] op_sel_hi:[1,0]
	v_pk_add_f32 v[66:67], v[66:67], v[34:35] op_sel_hi:[1,0]
	v_pk_add_f32 v[122:123], v[122:123], v[34:35] op_sel_hi:[1,0]
	v_pk_add_f32 v[120:121], v[120:121], v[34:35] op_sel_hi:[1,0]
	v_pk_add_f32 v[118:119], v[118:119], v[34:35] op_sel_hi:[1,0]
	v_pk_add_f32 v[116:117], v[116:117], v[34:35] op_sel_hi:[1,0]
	v_pk_add_f32 v[114:115], v[114:115], v[34:35] op_sel_hi:[1,0]
	v_pk_add_f32 v[112:113], v[112:113], v[34:35] op_sel_hi:[1,0]
	v_pk_add_f32 v[110:111], v[110:111], v[34:35] op_sel_hi:[1,0]
	v_pk_add_f32 v[108:109], v[108:109], v[34:35] op_sel_hi:[1,0]
	v_xor_b32_e32 v34, 0x80000000, v224
	v_pk_mul_f32 v[16:17], v[16:17], v[36:37] op_sel_hi:[1,0]
	v_pk_mul_f32 v[14:15], v[14:15], v[36:37] op_sel_hi:[1,0]
	v_pk_mul_f32 v[12:13], v[12:13], v[36:37] op_sel_hi:[1,0]
	v_pk_mul_f32 v[10:11], v[10:11], v[36:37] op_sel_hi:[1,0]
	v_pk_mul_f32 v[8:9], v[8:9], v[36:37] op_sel_hi:[1,0]
	v_pk_mul_f32 v[6:7], v[6:7], v[36:37] op_sel_hi:[1,0]
	v_pk_mul_f32 v[4:5], v[4:5], v[36:37] op_sel_hi:[1,0]
	v_pk_mul_f32 v[2:3], v[2:3], v[36:37] op_sel_hi:[1,0]
	v_pk_mul_f32 v[32:33], v[32:33], v[36:37] op_sel_hi:[1,0]
	v_pk_mul_f32 v[30:31], v[30:31], v[36:37] op_sel_hi:[1,0]
	v_pk_mul_f32 v[28:29], v[28:29], v[36:37] op_sel_hi:[1,0]
	v_pk_mul_f32 v[26:27], v[26:27], v[36:37] op_sel_hi:[1,0]
	v_pk_mul_f32 v[24:25], v[24:25], v[36:37] op_sel_hi:[1,0]
	v_pk_mul_f32 v[22:23], v[22:23], v[36:37] op_sel_hi:[1,0]
	v_pk_mul_f32 v[20:21], v[20:21], v[36:37] op_sel_hi:[1,0]
	v_pk_mul_f32 v[18:19], v[18:19], v[36:37] op_sel_hi:[1,0]
	v_mul_f32_e32 v124, v124, v36
	v_mov_b32_e32 v225, v224
	v_mov_b32_e32 v35, v34
	v_mov_b32_e32 v36, v34
	v_mov_b32_e32 v37, v34
	v_mov_b32_e32 v38, v34
	v_mov_b32_e32 v39, v34
	v_mov_b32_e32 v40, v34
	v_mov_b32_e32 v41, v34
	v_mov_b32_e32 v42, v34
	v_mov_b32_e32 v43, v34
	v_mov_b32_e32 v44, v34
	v_mov_b32_e32 v45, v34
	v_mov_b32_e32 v46, v34
	v_mov_b32_e32 v47, v34
	v_mov_b32_e32 v48, v34
	v_mov_b32_e32 v49, v34
	v_mov_b32_e32 v50, v34
	v_mov_b32_e32 v51, v34
	v_mov_b32_e32 v52, v34
	v_mov_b32_e32 v53, v34
	v_mov_b32_e32 v54, v34
	v_mov_b32_e32 v55, v34
	v_mov_b32_e32 v56, v34
	v_mov_b32_e32 v57, v34
	v_mov_b32_e32 v58, v34
	v_mov_b32_e32 v59, v34
	v_mov_b32_e32 v60, v34
	v_mov_b32_e32 v61, v34
	v_mov_b32_e32 v62, v34
	v_mov_b32_e32 v63, v34
	v_mov_b32_e32 v64, v34
	v_mov_b32_e32 v65, v34
	v_mov_b32_e32 v222, v224
	v_mov_b32_e32 v223, v224

.LBB0_948:
	s_or_b64 exec, exec, s[6:7]
	s_add_i32 s4, s10, 1
	s_cmp_lg_u32 s10, 4
	s_cselect_b32 s10, s4, 0
	s_lshl_b32 s84, s14, 7
	v_lshl_add_u64 v[82:83], v[220:221], 0, s[84:85]
	global_load_dwordx4 v[198:201], v[82:83], off
	ds_read_b128 v[98:101], v249 offset:39936
	ds_read_b128 v[102:105], v249 offset:39968
	s_mul_i32 s4, s10, 0x2200
	v_add_u32_e32 v125, s4, v248
	s_waitcnt lgkmcnt(1)
	v_mfma_f32_32x32x16_bf16 v[82:97], v[98:101], v[134:137], v[34:49]
	v_exp_f32_e32 v98, v66
	v_exp_f32_e32 v99, v67
	v_exp_f32_e32 v68, v68
	v_exp_f32_e32 v69, v69
	ds_read_b128 v[126:129], v249 offset:40000
	v_cvt_pk_bf16_f32 v66, v98, v99
	v_cvt_pk_bf16_f32 v67, v68, v69
	v_pk_add_f32 v[106:107], v[68:69], v[98:99]
	s_waitcnt lgkmcnt(1)
	v_mfma_f32_32x32x16_bf16 v[82:97], v[102:105], v[138:141], v[82:97]
	v_exp_f32_e32 v70, v70
	v_exp_f32_e32 v71, v71
	ds_read_b128 v[98:101], v249 offset:40032
	v_exp_f32_e32 v72, v72
	v_exp_f32_e32 v73, v73
	v_cvt_pk_bf16_f32 v68, v70, v71
	v_pk_add_f32 v[70:71], v[70:71], v[106:107]
	v_cvt_pk_bf16_f32 v69, v72, v73
	v_pk_add_f32 v[106:107], v[72:73], v[70:71]
	s_waitcnt lgkmcnt(1)
	v_mfma_f32_32x32x16_bf16 v[82:97], v[126:129], v[142:145], v[82:97]
	ds_read_b128 v[102:105], v249 offset:40064
	v_exp_f32_e32 v72, v74
	v_exp_f32_e32 v73, v75
	v_exp_f32_e32 v74, v76
	v_exp_f32_e32 v75, v77
	v_cvt_pk_bf16_f32 v70, v72, v73
	v_pk_add_f32 v[72:73], v[72:73], v[106:107]
	v_cvt_pk_bf16_f32 v71, v74, v75
	v_pk_add_f32 v[76:77], v[74:75], v[72:73]
	s_waitcnt lgkmcnt(1)
	v_mfma_f32_32x32x16_bf16 v[82:97], v[98:101], v[146:149], v[82:97]
	v_exp_f32_e32 v74, v78
	v_exp_f32_e32 v75, v79
	ds_read_b128 v[126:129], v249 offset:40096
	v_cvt_pk_bf16_f32 v72, v74, v75
	v_pk_add_f32 v[74:75], v[74:75], v[76:77]
	v_exp_f32_e32 v76, v80
	v_exp_f32_e32 v77, v81
	s_nop 0
	v_pk_add_f32 v[74:75], v[76:77], v[74:75]
	v_cvt_pk_bf16_f32 v73, v76, v77
	s_waitcnt lgkmcnt(1)
	v_mfma_f32_32x32x16_bf16 v[82:97], v[102:105], v[150:153], v[82:97]
	v_exp_f32_e32 v76, v108
	v_exp_f32_e32 v77, v109
	ds_read_b128 v[78:81], v249 offset:46592
	v_pk_add_f32 v[98:99], v[76:77], v[74:75]
	v_cvt_pk_bf16_f32 v74, v76, v77
	s_waitcnt lgkmcnt(1)
	v_mfma_f32_32x32x16_bf16 v[82:97], v[126:129], v[154:157], v[82:97]
	v_exp_f32_e32 v76, v110
	v_exp_f32_e32 v77, v111
	ds_read_b128 v[130:133], v249 offset:46624
	v_pk_add_f32 v[98:99], v[76:77], v[98:99]
	v_cvt_pk_bf16_f32 v75, v76, v77
	v_exp_f32_e32 v76, v112
	v_exp_f32_e32 v77, v113
	ds_read_b128 v[126:129], v249 offset:46656
	v_pk_add_f32 v[250:251], v[76:77], v[98:99]
	s_waitcnt lgkmcnt(2)
	v_mfma_f32_32x32x16_bf16 v[98:113], v[78:81], v[134:137], v[34:49]
	v_cvt_pk_bf16_f32 v76, v76, v77
	s_waitcnt lgkmcnt(1)
	v_mfma_f32_32x32x16_bf16 v[98:113], v[130:133], v[138:141], v[98:113]
	v_exp_f32_e32 v78, v114
	v_exp_f32_e32 v79, v115
	ds_read_b128 v[236:239], v249 offset:46688
	v_pk_add_f32 v[80:81], v[78:79], v[250:251]
	v_cvt_pk_bf16_f32 v77, v78, v79
	s_waitcnt lgkmcnt(1)
	v_mfma_f32_32x32x16_bf16 v[98:113], v[126:129], v[142:145], v[98:113]
	v_exp_f32_e32 v78, v116
	v_exp_f32_e32 v79, v117
	ds_read_b128 v[130:133], v249 offset:46720
	v_pk_add_f32 v[80:81], v[78:79], v[80:81]
	v_cvt_pk_bf16_f32 v78, v78, v79
	s_waitcnt lgkmcnt(1)
	v_mfma_f32_32x32x16_bf16 v[98:113], v[236:239], v[146:149], v[98:113]
	v_exp_f32_e32 v114, v118
	v_exp_f32_e32 v115, v119
	ds_read_b128 v[126:129], v249 offset:46752
	v_pk_add_f32 v[80:81], v[114:115], v[80:81]
	v_cvt_pk_bf16_f32 v79, v114, v115
	s_waitcnt lgkmcnt(1)
	v_mfma_f32_32x32x16_bf16 v[98:113], v[130:133], v[150:153], v[98:113]
	v_add_u32_e32 v208, 0xd000, v125
	v_exp_f32_e32 v114, v120
	v_exp_f32_e32 v115, v121
	ds_read2_b64 v[116:119], v208 offset1:2
	v_pk_add_f32 v[130:131], v[114:115], v[80:81]
	v_cvt_pk_bf16_f32 v80, v114, v115
	s_waitcnt lgkmcnt(1)
	v_mfma_f32_32x32x16_bf16 v[98:113], v[126:129], v[154:157], v[98:113]
	v_exp_f32_e32 v132, v122
	v_exp_f32_e32 v133, v123
	v_add_u32_e32 v125, 0xe000, v125
	ds_read2_b64 v[120:123], v125 offset0:32 offset1:34
	v_pk_add_f32 v[114:115], v[132:133], v[130:131]
	v_cvt_pk_bf16_f32 v81, v132, v133
	s_waitcnt lgkmcnt(1)
	v_mfma_f32_32x32x16_bf16 v[18:33], v[116:119], v[66:69], v[18:33]
	ds_read2_b64 v[126:129], v208 offset0:4 offset1:6
	v_max3_f32 v116, v231, v82, v83
	v_max3_f32 v130, v116, v84, v85
	s_waitcnt lgkmcnt(1)
	v_mfma_f32_32x32x16_bf16 v[2:17], v[120:123], v[66:69], v[2:17]
	ds_read2_b64 v[116:119], v125 offset0:36 offset1:38
	v_max3_f32 v66, v130, v86, v87
	v_max3_f32 v120, v66, v88, v89
	s_waitcnt lgkmcnt(1)
	v_mfma_f32_32x32x16_bf16 v[18:33], v[126:129], v[70:73], v[18:33]
	ds_read2_b64 v[66:69], v208 offset0:8 offset1:10
	v_max3_f32 v120, v120, v90, v91
	v_max3_f32 v126, v120, v92, v93
	s_waitcnt lgkmcnt(1)
	v_mfma_f32_32x32x16_bf16 v[2:17], v[116:119], v[70:73], v[2:17]
	ds_read2_b64 v[120:123], v125 offset0:40 offset1:42
	v_max3_f32 v70, v126, v94, v95
	v_max3_f32 v116, v70, v96, v97
	s_waitcnt lgkmcnt(1)
	v_mfma_f32_32x32x16_bf16 v[18:33], v[66:69], v[74:77], v[18:33]
	ds_read2_b64 v[70:73], v208 offset0:12 offset1:14
	v_max3_f32 v116, v116, v98, v99
	v_max3_f32 v116, v116, v100, v101
	s_waitcnt lgkmcnt(1)
	v_mfma_f32_32x32x16_bf16 v[2:17], v[120:123], v[74:77], v[2:17]
	ds_read2_b64 v[66:69], v125 offset0:44 offset1:46
	v_max3_f32 v116, v116, v102, v103
	v_max3_f32 v116, v116, v104, v105
	s_waitcnt lgkmcnt(1)
	v_mfma_f32_32x32x16_bf16 v[18:33], v[70:73], v[78:81], v[18:33]
	v_max3_f32 v70, v116, v106, v107
	v_max3_f32 v70, v70, v108, v109
	s_waitcnt lgkmcnt(0)
	v_mfma_f32_32x32x16_bf16 v[2:17], v[66:69], v[78:81], v[2:17]
	v_max3_f32 v66, v70, v110, v111
	v_max3_f32 v208, v66, v112, v113
	v_add_f32_e32 v66, v114, v115
	v_add_f32_e32 v114, v124, v66
	v_add_f32_e64 v66, v224, v208
	v_add_f32_e64 v67, v225, v209
	v_cmp_gt_f32_e32 vcc, v66, v67
	s_cbranch_vccz .LBB0_950
	v_cmp_lt_i32_e32 vcc, v241, v235
	v_max_f32_e32 v35, v208, v208
	v_max_f32_e32 v36, v223, v223
	v_cndmask_b32_e32 v34, v233, v241, vcc
	v_lshlrev_b32_e32 v34, 2, v34
	ds_bpermute_b32 v34, v34, v208
	s_waitcnt lgkmcnt(0)
	v_max_f32_e32 v34, v34, v34
	v_max_f32_e32 v34, v35, v34
	v_add_f32_e32 v34, v222, v34
	v_max_f32_e32 v224, v36, v34
	v_sub_f32_e32 v34, v223, v224
	v_exp_f32_e32 v36, v34
	v_sub_f32_e32 v34, v222, v224
	v_pk_add_f32 v[96:97], v[96:97], v[34:35] op_sel_hi:[1,0]
	v_pk_add_f32 v[94:95], v[94:95], v[34:35] op_sel_hi:[1,0]
	v_pk_add_f32 v[92:93], v[92:93], v[34:35] op_sel_hi:[1,0]
	v_pk_add_f32 v[90:91], v[90:91], v[34:35] op_sel_hi:[1,0]
	v_pk_add_f32 v[88:89], v[88:89], v[34:35] op_sel_hi:[1,0]
	v_pk_add_f32 v[86:87], v[86:87], v[34:35] op_sel_hi:[1,0]
	v_pk_add_f32 v[84:85], v[84:85], v[34:35] op_sel_hi:[1,0]
	v_pk_add_f32 v[82:83], v[82:83], v[34:35] op_sel_hi:[1,0]
	v_pk_add_f32 v[112:113], v[112:113], v[34:35] op_sel_hi:[1,0]
	v_pk_add_f32 v[110:111], v[110:111], v[34:35] op_sel_hi:[1,0]
	v_pk_add_f32 v[108:109], v[108:109], v[34:35] op_sel_hi:[1,0]
	v_pk_add_f32 v[106:107], v[106:107], v[34:35] op_sel_hi:[1,0]
	v_pk_add_f32 v[104:105], v[104:105], v[34:35] op_sel_hi:[1,0]
	v_pk_add_f32 v[102:103], v[102:103], v[34:35] op_sel_hi:[1,0]
	v_pk_add_f32 v[100:101], v[100:101], v[34:35] op_sel_hi:[1,0]
	v_pk_add_f32 v[98:99], v[98:99], v[34:35] op_sel_hi:[1,0]
	v_xor_b32_e32 v34, 0x80000000, v224
	v_pk_mul_f32 v[16:17], v[16:17], v[36:37] op_sel_hi:[1,0]
	v_pk_mul_f32 v[14:15], v[14:15], v[36:37] op_sel_hi:[1,0]
	v_pk_mul_f32 v[12:13], v[12:13], v[36:37] op_sel_hi:[1,0]
	v_pk_mul_f32 v[10:11], v[10:11], v[36:37] op_sel_hi:[1,0]
	v_pk_mul_f32 v[8:9], v[8:9], v[36:37] op_sel_hi:[1,0]
	v_pk_mul_f32 v[6:7], v[6:7], v[36:37] op_sel_hi:[1,0]
	v_pk_mul_f32 v[4:5], v[4:5], v[36:37] op_sel_hi:[1,0]
	v_pk_mul_f32 v[2:3], v[2:3], v[36:37] op_sel_hi:[1,0]
	v_pk_mul_f32 v[32:33], v[32:33], v[36:37] op_sel_hi:[1,0]
	v_pk_mul_f32 v[30:31], v[30:31], v[36:37] op_sel_hi:[1,0]
	v_pk_mul_f32 v[28:29], v[28:29], v[36:37] op_sel_hi:[1,0]
	v_pk_mul_f32 v[26:27], v[26:27], v[36:37] op_sel_hi:[1,0]
	v_pk_mul_f32 v[24:25], v[24:25], v[36:37] op_sel_hi:[1,0]
	v_pk_mul_f32 v[22:23], v[22:23], v[36:37] op_sel_hi:[1,0]
	v_pk_mul_f32 v[20:21], v[20:21], v[36:37] op_sel_hi:[1,0]
	v_pk_mul_f32 v[18:19], v[18:19], v[36:37] op_sel_hi:[1,0]
	v_mul_f32_e32 v114, v114, v36
	v_mov_b32_e32 v225, v224
	v_mov_b32_e32 v35, v34
	v_mov_b32_e32 v36, v34
	v_mov_b32_e32 v37, v34
	v_mov_b32_e32 v38, v34
	v_mov_b32_e32 v39, v34
	v_mov_b32_e32 v40, v34
	v_mov_b32_e32 v41, v34
	v_mov_b32_e32 v42, v34
	v_mov_b32_e32 v43, v34
	v_mov_b32_e32 v44, v34
	v_mov_b32_e32 v45, v34
	v_mov_b32_e32 v46, v34
	v_mov_b32_e32 v47, v34
	v_mov_b32_e32 v48, v34
	v_mov_b32_e32 v49, v34
	v_mov_b32_e32 v50, v34
	v_mov_b32_e32 v51, v34
	v_mov_b32_e32 v52, v34
	v_mov_b32_e32 v53, v34
	v_mov_b32_e32 v54, v34
	v_mov_b32_e32 v55, v34
	v_mov_b32_e32 v56, v34
	v_mov_b32_e32 v57, v34
	v_mov_b32_e32 v58, v34
	v_mov_b32_e32 v59, v34
	v_mov_b32_e32 v60, v34
	v_mov_b32_e32 v61, v34
	v_mov_b32_e32 v62, v34
	v_mov_b32_e32 v63, v34
	v_mov_b32_e32 v64, v34
	v_mov_b32_e32 v65, v34
	v_mov_b32_e32 v222, v224
	v_mov_b32_e32 v223, v224

.LBB0_954:
	s_or_b64 exec, exec, s[6:7]
	s_add_i32 s4, s10, 1
	s_cmp_lg_u32 s10, 4
	s_cselect_b32 s4, s4, 0
	s_lshl_b32 s84, s14, 7
	v_lshl_add_u64 v[66:67], v[220:221], 0, s[84:85]
	global_load_dwordx4 v[202:205], v[66:67], off
	ds_read_b128 v[116:119], v249
	ds_read_b128 v[120:123], v249 offset:32
	s_mul_i32 s5, s4, 0x2200
	v_add_u32_e32 v115, s5, v248
	s_waitcnt lgkmcnt(1)
	v_mfma_f32_32x32x16_bf16 v[66:81], v[116:119], v[134:137], v[34:49]
	v_exp_f32_e32 v116, v82
	v_exp_f32_e32 v117, v83
	ds_read_b128 v[124:127], v249 offset:64
	v_exp_f32_e32 v84, v84
	v_exp_f32_e32 v85, v85
	v_cvt_pk_bf16_f32 v82, v116, v117
	v_cvt_pk_bf16_f32 v83, v84, v85
	v_pk_add_f32 v[128:129], v[84:85], v[116:117]
	s_waitcnt lgkmcnt(1)
	v_mfma_f32_32x32x16_bf16 v[66:81], v[120:123], v[138:141], v[66:81]
	v_exp_f32_e32 v86, v86
	v_exp_f32_e32 v87, v87
	ds_read_b128 v[116:119], v249 offset:96
	v_exp_f32_e32 v88, v88
	v_exp_f32_e32 v89, v89
	v_cvt_pk_bf16_f32 v84, v86, v87
	v_pk_add_f32 v[86:87], v[86:87], v[128:129]
	v_cvt_pk_bf16_f32 v85, v88, v89
	v_pk_add_f32 v[128:129], v[88:89], v[86:87]
	s_waitcnt lgkmcnt(1)
	v_mfma_f32_32x32x16_bf16 v[66:81], v[124:127], v[142:145], v[66:81]
	v_exp_f32_e32 v88, v90
	v_exp_f32_e32 v89, v91
	ds_read_b128 v[120:123], v249 offset:128
	v_exp_f32_e32 v90, v92
	v_exp_f32_e32 v91, v93
	v_cvt_pk_bf16_f32 v86, v88, v89
	v_pk_add_f32 v[88:89], v[88:89], v[128:129]
	v_cvt_pk_bf16_f32 v87, v90, v91
	v_pk_add_f32 v[92:93], v[90:91], v[88:89]
	s_waitcnt lgkmcnt(1)
	v_mfma_f32_32x32x16_bf16 v[66:81], v[116:119], v[146:149], v[66:81]
	v_exp_f32_e32 v90, v94
	v_exp_f32_e32 v91, v95
	ds_read_b128 v[124:127], v249 offset:160
	v_cvt_pk_bf16_f32 v88, v90, v91
	v_pk_add_f32 v[90:91], v[90:91], v[92:93]
	v_exp_f32_e32 v92, v96
	v_exp_f32_e32 v93, v97
	s_nop 0
	v_pk_add_f32 v[90:91], v[92:93], v[90:91]
	v_cvt_pk_bf16_f32 v89, v92, v93
	s_waitcnt lgkmcnt(1)
	v_mfma_f32_32x32x16_bf16 v[66:81], v[120:123], v[150:153], v[66:81]
	v_exp_f32_e32 v96, v98
	v_exp_f32_e32 v97, v99
	ds_read_b128 v[92:95], v249 offset:6656
	v_pk_add_f32 v[116:117], v[96:97], v[90:91]
	v_cvt_pk_bf16_f32 v90, v96, v97
	s_waitcnt lgkmcnt(1)
	v_mfma_f32_32x32x16_bf16 v[66:81], v[124:127], v[154:157], v[66:81]
	v_exp_f32_e32 v100, v100
	v_exp_f32_e32 v101, v101
	ds_read_b128 v[96:99], v249 offset:6688
	v_pk_add_f32 v[120:121], v[100:101], v[116:117]
	v_cvt_pk_bf16_f32 v91, v100, v101
	s_waitcnt lgkmcnt(1)
	v_mfma_f32_32x32x16_bf16 v[34:49], v[92:95], v[134:137], v[34:49]
	v_exp_f32_e32 v92, v102
	v_exp_f32_e32 v93, v103
	ds_read_b128 v[116:119], v249 offset:6720
	v_pk_add_f32 v[94:95], v[92:93], v[120:121]
	v_cvt_pk_bf16_f32 v92, v92, v93
	s_waitcnt lgkmcnt(1)
	v_mfma_f32_32x32x16_bf16 v[34:49], v[96:99], v[138:141], v[34:49]
	v_exp_f32_e32 v96, v104
	v_exp_f32_e32 v97, v105
	ds_read_b128 v[100:103], v249 offset:6752
	v_pk_add_f32 v[94:95], v[96:97], v[94:95]
	v_cvt_pk_bf16_f32 v93, v96, v97
	s_waitcnt lgkmcnt(1)
	v_mfma_f32_32x32x16_bf16 v[34:49], v[116:119], v[142:145], v[34:49]
	v_exp_f32_e32 v104, v106
	v_exp_f32_e32 v105, v107
	ds_read_b128 v[96:99], v249 offset:6784
	v_pk_add_f32 v[116:117], v[104:105], v[94:95]
	v_cvt_pk_bf16_f32 v94, v104, v105
	s_waitcnt lgkmcnt(1)
	v_mfma_f32_32x32x16_bf16 v[34:49], v[100:103], v[146:149], v[34:49]
	v_exp_f32_e32 v100, v108
	v_exp_f32_e32 v101, v109
	ds_read_b128 v[104:107], v249 offset:6816
	v_pk_add_f32 v[108:109], v[100:101], v[116:117]
	v_cvt_pk_bf16_f32 v95, v100, v101
	s_waitcnt lgkmcnt(1)
	v_mfma_f32_32x32x16_bf16 v[34:49], v[96:99], v[150:153], v[34:49]
	v_add_u32_e32 v116, 0xd000, v115
	v_exp_f32_e32 v96, v110
	v_exp_f32_e32 v97, v111
	ds_read2_b64 v[100:103], v116 offset1:2
	v_pk_add_f32 v[98:99], v[96:97], v[108:109]
	v_cvt_pk_bf16_f32 v96, v96, v97
	s_waitcnt lgkmcnt(1)
	v_mfma_f32_32x32x16_bf16 v[34:49], v[104:107], v[154:157], v[34:49]
	v_exp_f32_e32 v112, v112
	v_exp_f32_e32 v113, v113
	v_add_u32_e32 v115, 0xe000, v115
	ds_read2_b64 v[108:111], v115 offset0:32 offset1:34
	v_pk_add_f32 v[98:99], v[112:113], v[98:99]
	v_cvt_pk_bf16_f32 v97, v112, v113
	s_waitcnt lgkmcnt(1)
	v_mfma_f32_32x32x16_bf16 v[18:33], v[100:103], v[82:85], v[18:33]
	ds_read2_b64 v[104:107], v116 offset0:4 offset1:6
	v_max3_f32 v100, v231, v66, v67
	v_max3_f32 v112, v100, v68, v69
	s_waitcnt lgkmcnt(1)
	v_mfma_f32_32x32x16_bf16 v[2:17], v[108:111], v[82:85], v[2:17]
	ds_read2_b64 v[100:103], v115 offset0:36 offset1:38
	v_max3_f32 v82, v112, v70, v71
	v_max3_f32 v108, v82, v72, v73
	s_waitcnt lgkmcnt(1)
	v_mfma_f32_32x32x16_bf16 v[18:33], v[104:107], v[86:89], v[18:33]
	ds_read2_b64 v[82:85], v116 offset0:8 offset1:10
	v_max3_f32 v104, v108, v74, v75
	v_max3_f32 v108, v104, v76, v77
	s_waitcnt lgkmcnt(1)
	v_mfma_f32_32x32x16_bf16 v[2:17], v[100:103], v[86:89], v[2:17]
	ds_read2_b64 v[104:107], v115 offset0:40 offset1:42
	v_max3_f32 v86, v108, v78, v79
	v_max3_f32 v100, v86, v80, v81
	s_waitcnt lgkmcnt(1)
	v_mfma_f32_32x32x16_bf16 v[18:33], v[82:85], v[90:93], v[18:33]
	ds_read2_b64 v[86:89], v116 offset0:12 offset1:14
	v_max3_f32 v100, v100, v34, v35
	v_max3_f32 v100, v100, v36, v37
	s_waitcnt lgkmcnt(1)
	v_mfma_f32_32x32x16_bf16 v[2:17], v[104:107], v[90:93], v[2:17]
	ds_read2_b64 v[82:85], v115 offset0:44 offset1:46
	v_max3_f32 v100, v100, v38, v39
	v_max3_f32 v100, v100, v40, v41
	s_waitcnt lgkmcnt(1)
	v_mfma_f32_32x32x16_bf16 v[18:33], v[86:89], v[94:97], v[18:33]
	v_max3_f32 v86, v100, v42, v43
	v_max3_f32 v86, v86, v44, v45
	s_waitcnt lgkmcnt(0)
	v_mfma_f32_32x32x16_bf16 v[2:17], v[82:85], v[94:97], v[2:17]
	v_max3_f32 v82, v86, v46, v47
	v_max3_f32 v208, v82, v48, v49
	v_add_f32_e32 v82, v98, v99
	v_add_f32_e32 v98, v114, v82
	v_add_f32_e64 v82, v224, v208
	v_add_f32_e64 v83, v225, v209
	v_cmp_gt_f32_e32 vcc, v82, v83
	s_cbranch_vccz .LBB0_932
	v_cmp_lt_i32_e32 vcc, v241, v235
	v_max_f32_e32 v51, v208, v208
	v_max_f32_e32 v52, v223, v223
	v_cndmask_b32_e32 v50, v233, v241, vcc
	v_lshlrev_b32_e32 v50, 2, v50
	ds_bpermute_b32 v50, v50, v208
	s_waitcnt lgkmcnt(0)
	v_max_f32_e32 v50, v50, v50
	v_max_f32_e32 v50, v51, v50
	v_add_f32_e32 v50, v222, v50
	v_max_f32_e32 v82, v52, v50
	v_sub_f32_e32 v50, v223, v82
	v_exp_f32_e32 v52, v50
	v_sub_f32_e32 v50, v222, v82
	v_pk_add_f32 v[80:81], v[80:81], v[50:51] op_sel_hi:[1,0]
	v_pk_add_f32 v[78:79], v[78:79], v[50:51] op_sel_hi:[1,0]
	v_pk_add_f32 v[76:77], v[76:77], v[50:51] op_sel_hi:[1,0]
	v_pk_add_f32 v[74:75], v[74:75], v[50:51] op_sel_hi:[1,0]
	v_pk_add_f32 v[72:73], v[72:73], v[50:51] op_sel_hi:[1,0]
	v_pk_add_f32 v[70:71], v[70:71], v[50:51] op_sel_hi:[1,0]
	v_pk_add_f32 v[68:69], v[68:69], v[50:51] op_sel_hi:[1,0]
	v_pk_add_f32 v[66:67], v[66:67], v[50:51] op_sel_hi:[1,0]
	v_pk_add_f32 v[48:49], v[48:49], v[50:51] op_sel_hi:[1,0]
	v_pk_add_f32 v[46:47], v[46:47], v[50:51] op_sel_hi:[1,0]
	v_pk_add_f32 v[44:45], v[44:45], v[50:51] op_sel_hi:[1,0]
	v_pk_add_f32 v[42:43], v[42:43], v[50:51] op_sel_hi:[1,0]
	v_pk_add_f32 v[40:41], v[40:41], v[50:51] op_sel_hi:[1,0]
	v_pk_add_f32 v[38:39], v[38:39], v[50:51] op_sel_hi:[1,0]
	v_pk_add_f32 v[36:37], v[36:37], v[50:51] op_sel_hi:[1,0]
	v_pk_add_f32 v[34:35], v[34:35], v[50:51] op_sel_hi:[1,0]
	v_xor_b32_e32 v50, 0x80000000, v82
	v_pk_mul_f32 v[16:17], v[16:17], v[52:53] op_sel_hi:[1,0]
	v_pk_mul_f32 v[14:15], v[14:15], v[52:53] op_sel_hi:[1,0]
	v_pk_mul_f32 v[12:13], v[12:13], v[52:53] op_sel_hi:[1,0]
	v_pk_mul_f32 v[10:11], v[10:11], v[52:53] op_sel_hi:[1,0]
	v_pk_mul_f32 v[8:9], v[8:9], v[52:53] op_sel_hi:[1,0]
	v_pk_mul_f32 v[6:7], v[6:7], v[52:53] op_sel_hi:[1,0]
	v_pk_mul_f32 v[4:5], v[4:5], v[52:53] op_sel_hi:[1,0]
	v_pk_mul_f32 v[2:3], v[2:3], v[52:53] op_sel_hi:[1,0]
	v_pk_mul_f32 v[32:33], v[32:33], v[52:53] op_sel_hi:[1,0]
	v_pk_mul_f32 v[30:31], v[30:31], v[52:53] op_sel_hi:[1,0]
	v_pk_mul_f32 v[28:29], v[28:29], v[52:53] op_sel_hi:[1,0]
	v_pk_mul_f32 v[26:27], v[26:27], v[52:53] op_sel_hi:[1,0]
	v_pk_mul_f32 v[24:25], v[24:25], v[52:53] op_sel_hi:[1,0]
	v_pk_mul_f32 v[22:23], v[22:23], v[52:53] op_sel_hi:[1,0]
	v_pk_mul_f32 v[20:21], v[20:21], v[52:53] op_sel_hi:[1,0]
	v_pk_mul_f32 v[18:19], v[18:19], v[52:53] op_sel_hi:[1,0]
	v_mul_f32_e32 v98, v98, v52
	v_mov_b32_e32 v51, v50
	v_mov_b32_e32 v52, v50
	v_mov_b32_e32 v53, v50
	v_mov_b32_e32 v54, v50
	v_mov_b32_e32 v55, v50
	v_mov_b32_e32 v56, v50
	v_mov_b32_e32 v57, v50
	v_mov_b32_e32 v58, v50
	v_mov_b32_e32 v59, v50
	v_mov_b32_e32 v60, v50
	v_mov_b32_e32 v61, v50
	v_mov_b32_e32 v62, v50
	v_mov_b32_e32 v63, v50
	v_mov_b32_e32 v64, v50
	v_mov_b32_e32 v65, v50
	v_mov_b32_e32 v222, v82
	v_mov_b32_e32 v223, v82
	s_branch .LBB0_932
